# k44: k36 + nt hint on GEMM epilogue result stores of P1a P1b P4 P6 P11 P13
# baseline (speedup 1.0000x reference)
.LBB0_138:
	s_lshl_b32 s0, s26, 8
	v_add_u32_e32 v144, s0, v146
	v_ashrrev_i32_e32 v145, 31, v144
	v_lshl_or_b32 v160, s52, 8, v155
	v_lshlrev_b64 v[144:145], 11, v[144:145]
	v_ashrrev_i32_e32 v161, 31, v160
	v_lshl_add_u64 v[162:163], s[82:83], 0, v[144:145]
	v_lshlrev_b64 v[144:145], 1, v[160:161]
	v_lshl_add_u64 v[160:161], v[162:163], 0, v[144:145]
	v_cvt_pk_bf16_f32 v124, v124, v125
	v_cvt_pk_bf16_f32 v125, v126, v127
	v_cvt_pk_bf16_f32 v126, v120, v121
	v_cvt_pk_bf16_f32 v127, v122, v123
	global_store_dwordx4 v[160:161], v[124:127], off nt
	v_cvt_pk_bf16_f32 v112, v112, v113
	v_cvt_pk_bf16_f32 v113, v114, v115
	v_cvt_pk_bf16_f32 v114, v104, v105
	v_add_u32_e32 v104, s0, v148
	v_ashrrev_i32_e32 v105, 31, v104
	v_lshlrev_b64 v[104:105], 11, v[104:105]
	v_lshl_add_u64 v[104:105], s[82:83], 0, v[104:105]
	v_cvt_pk_bf16_f32 v115, v106, v107
	global_store_dwordx4 v[160:161], v[112:115], off offset:256 nt
	s_andn2_b64 vcc, exec, s[4:5]
	s_nop 0
	v_lshl_add_u64 v[112:113], v[104:105], 0, v[144:145]
	v_cvt_pk_bf16_f32 v104, v116, v117
	v_cvt_pk_bf16_f32 v105, v118, v119
	v_cvt_pk_bf16_f32 v106, v108, v109
	v_cvt_pk_bf16_f32 v107, v110, v111
	global_store_dwordx4 v[112:113], v[104:107], off nt
	v_cvt_pk_bf16_f32 v96, v96, v97
	v_cvt_pk_bf16_f32 v97, v98, v99
	v_cvt_pk_bf16_f32 v98, v88, v89
	v_add_u32_e32 v88, s0, v149
	v_ashrrev_i32_e32 v89, 31, v88
	v_lshlrev_b64 v[88:89], 11, v[88:89]
	v_lshl_add_u64 v[88:89], s[82:83], 0, v[88:89]
	v_cvt_pk_bf16_f32 v99, v90, v91
	global_store_dwordx4 v[112:113], v[96:99], off offset:256 nt
	s_nop 1
	v_lshl_add_u64 v[96:97], v[88:89], 0, v[144:145]
	v_cvt_pk_bf16_f32 v88, v100, v101
	v_cvt_pk_bf16_f32 v89, v102, v103
	v_cvt_pk_bf16_f32 v90, v92, v93
	v_cvt_pk_bf16_f32 v91, v94, v95
	global_store_dwordx4 v[96:97], v[88:91], off nt
	v_cvt_pk_bf16_f32 v80, v80, v81
	v_cvt_pk_bf16_f32 v81, v82, v83
	v_cvt_pk_bf16_f32 v82, v72, v73
	v_add_u32_e32 v72, s0, v150
	v_ashrrev_i32_e32 v73, 31, v72
	v_lshlrev_b64 v[72:73], 11, v[72:73]
	v_lshl_add_u64 v[72:73], s[82:83], 0, v[72:73]
	v_cvt_pk_bf16_f32 v83, v74, v75
	global_store_dwordx4 v[96:97], v[80:83], off offset:256 nt
	s_nop 1
	v_lshl_add_u64 v[80:81], v[72:73], 0, v[144:145]
	v_cvt_pk_bf16_f32 v72, v84, v85
	v_cvt_pk_bf16_f32 v73, v86, v87
	v_cvt_pk_bf16_f32 v74, v76, v77
	v_cvt_pk_bf16_f32 v75, v78, v79
	global_store_dwordx4 v[80:81], v[72:75], off nt
	v_cvt_pk_bf16_f32 v68, v68, v69
	v_cvt_pk_bf16_f32 v69, v70, v71
	v_cvt_pk_bf16_f32 v70, v64, v65
	v_add_u32_e32 v64, s0, v151
	v_ashrrev_i32_e32 v65, 31, v64
	v_lshlrev_b64 v[64:65], 11, v[64:65]
	v_lshl_add_u64 v[64:65], s[82:83], 0, v[64:65]
	v_lshl_add_u64 v[64:65], v[64:65], 0, v[144:145]
	v_cvt_pk_bf16_f32 v71, v66, v67
	global_store_dwordx4 v[80:81], v[68:71], off offset:256 nt
	v_cvt_pk_bf16_f32 v60, v60, v61
	v_cvt_pk_bf16_f32 v61, v62, v63
	v_cvt_pk_bf16_f32 v62, v56, v57
	v_cvt_pk_bf16_f32 v63, v58, v59
	global_store_dwordx4 v[64:65], v[60:63], off nt
	v_cvt_pk_bf16_f32 v48, v48, v49
	v_cvt_pk_bf16_f32 v49, v50, v51
	v_cvt_pk_bf16_f32 v50, v40, v41
	v_add_u32_e32 v40, s0, v152
	v_ashrrev_i32_e32 v41, 31, v40
	v_lshlrev_b64 v[40:41], 11, v[40:41]
	v_lshl_add_u64 v[40:41], s[82:83], 0, v[40:41]
	v_cvt_pk_bf16_f32 v51, v42, v43
	global_store_dwordx4 v[64:65], v[48:51], off offset:256 nt
	s_nop 1
	v_lshl_add_u64 v[48:49], v[40:41], 0, v[144:145]
	v_cvt_pk_bf16_f32 v40, v52, v53
	v_cvt_pk_bf16_f32 v41, v54, v55
	v_cvt_pk_bf16_f32 v42, v44, v45
	v_cvt_pk_bf16_f32 v43, v46, v47
	global_store_dwordx4 v[48:49], v[40:43], off nt
	v_cvt_pk_bf16_f32 v32, v32, v33
	v_cvt_pk_bf16_f32 v33, v34, v35
	v_cvt_pk_bf16_f32 v34, v24, v25
	v_add_u32_e32 v24, s0, v153
	v_ashrrev_i32_e32 v25, 31, v24
	v_lshlrev_b64 v[24:25], 11, v[24:25]
	v_lshl_add_u64 v[24:25], s[82:83], 0, v[24:25]
	v_cvt_pk_bf16_f32 v35, v26, v27
	global_store_dwordx4 v[48:49], v[32:35], off offset:256 nt
	s_nop 1
	v_lshl_add_u64 v[32:33], v[24:25], 0, v[144:145]
	v_cvt_pk_bf16_f32 v24, v36, v37
	v_cvt_pk_bf16_f32 v25, v38, v39
	v_cvt_pk_bf16_f32 v26, v28, v29
	v_cvt_pk_bf16_f32 v27, v30, v31
	global_store_dwordx4 v[32:33], v[24:27], off nt
	v_cvt_pk_bf16_f32 v16, v16, v17
	v_cvt_pk_bf16_f32 v17, v18, v19
	v_cvt_pk_bf16_f32 v18, v8, v9
	v_add_u32_e32 v8, s0, v154
	v_ashrrev_i32_e32 v9, 31, v8
	v_lshlrev_b64 v[8:9], 11, v[8:9]
	v_lshl_add_u64 v[8:9], s[82:83], 0, v[8:9]
	v_cvt_pk_bf16_f32 v19, v10, v11
	global_store_dwordx4 v[32:33], v[16:19], off offset:256 nt
	s_mov_b64 s[0:1], -1
	s_nop 0
	v_lshl_add_u64 v[16:17], v[8:9], 0, v[144:145]
	v_cvt_pk_bf16_f32 v8, v20, v21
	v_cvt_pk_bf16_f32 v9, v22, v23
	v_cvt_pk_bf16_f32 v10, v12, v13
	v_cvt_pk_bf16_f32 v11, v14, v15
	global_store_dwordx4 v[16:17], v[8:11], off nt
	v_cvt_pk_bf16_f32 v4, v4, v5
	v_cvt_pk_bf16_f32 v5, v6, v7
	v_cvt_pk_bf16_f32 v6, v0, v1
	v_cvt_pk_bf16_f32 v7, v2, v3
	global_store_dwordx4 v[16:17], v[4:7], off offset:256 nt
	s_cbranch_vccnz .LBB0_127
	s_andn2_b64 vcc, exec, s[10:11]
	s_cbranch_vccnz .LBB0_126
	s_barrier
	s_branch .LBB0_126

.LBB0_158:
	s_lshl_b32 s0, s24, 8
	v_add_u32_e32 v144, s0, v146
	v_ashrrev_i32_e32 v145, 31, v144
	v_lshl_or_b32 v160, s42, 8, v155
	v_readlane_b32 s44, v254, 0
	v_lshlrev_b64 v[144:145], 11, v[144:145]
	v_readlane_b32 s50, v254, 6
	v_readlane_b32 s51, v254, 7
	v_ashrrev_i32_e32 v161, 31, v160
	v_cvt_pk_bf16_f32 v124, v124, v125
	v_cvt_pk_bf16_f32 v125, v126, v127
	v_cvt_pk_bf16_f32 v126, v120, v121
	v_cvt_pk_bf16_f32 v127, v122, v123
	s_nop 0
	v_lshl_add_u64 v[162:163], s[50:51], 0, v[144:145]
	v_lshlrev_b64 v[144:145], 1, v[160:161]
	v_lshl_add_u64 v[160:161], v[162:163], 0, v[144:145]
	global_store_dwordx4 v[160:161], v[124:127], off nt
	v_cvt_pk_bf16_f32 v112, v112, v113
	v_cvt_pk_bf16_f32 v113, v114, v115
	v_cvt_pk_bf16_f32 v114, v104, v105
	v_add_u32_e32 v104, s0, v148
	v_ashrrev_i32_e32 v105, 31, v104
	v_lshlrev_b64 v[104:105], 11, v[104:105]
	v_lshl_add_u64 v[104:105], s[50:51], 0, v[104:105]
	v_cvt_pk_bf16_f32 v115, v106, v107
	global_store_dwordx4 v[160:161], v[112:115], off offset:256 nt
	s_andn2_b64 vcc, exec, s[6:7]
	v_readlane_b32 s45, v254, 1
	v_lshl_add_u64 v[112:113], v[104:105], 0, v[144:145]
	v_cvt_pk_bf16_f32 v104, v116, v117
	v_cvt_pk_bf16_f32 v105, v118, v119
	v_cvt_pk_bf16_f32 v106, v108, v109
	v_cvt_pk_bf16_f32 v107, v110, v111
	global_store_dwordx4 v[112:113], v[104:107], off nt
	v_cvt_pk_bf16_f32 v96, v96, v97
	v_cvt_pk_bf16_f32 v97, v98, v99
	v_cvt_pk_bf16_f32 v98, v88, v89
	v_add_u32_e32 v88, s0, v149
	v_ashrrev_i32_e32 v89, 31, v88
	v_lshlrev_b64 v[88:89], 11, v[88:89]
	v_lshl_add_u64 v[88:89], s[50:51], 0, v[88:89]
	v_cvt_pk_bf16_f32 v99, v90, v91
	global_store_dwordx4 v[112:113], v[96:99], off offset:256 nt
	v_readlane_b32 s46, v254, 2
	v_readlane_b32 s47, v254, 3
	v_lshl_add_u64 v[96:97], v[88:89], 0, v[144:145]
	v_cvt_pk_bf16_f32 v88, v100, v101
	v_cvt_pk_bf16_f32 v89, v102, v103
	v_cvt_pk_bf16_f32 v90, v92, v93
	v_cvt_pk_bf16_f32 v91, v94, v95
	global_store_dwordx4 v[96:97], v[88:91], off nt
	v_cvt_pk_bf16_f32 v80, v80, v81
	v_cvt_pk_bf16_f32 v81, v82, v83
	v_cvt_pk_bf16_f32 v82, v72, v73
	v_add_u32_e32 v72, s0, v150
	v_ashrrev_i32_e32 v73, 31, v72
	v_lshlrev_b64 v[72:73], 11, v[72:73]
	v_lshl_add_u64 v[72:73], s[50:51], 0, v[72:73]
	v_cvt_pk_bf16_f32 v83, v74, v75
	global_store_dwordx4 v[96:97], v[80:83], off offset:256 nt
	v_readlane_b32 s48, v254, 4
	v_readlane_b32 s49, v254, 5
	v_lshl_add_u64 v[80:81], v[72:73], 0, v[144:145]
	v_cvt_pk_bf16_f32 v72, v84, v85
	v_cvt_pk_bf16_f32 v73, v86, v87
	v_cvt_pk_bf16_f32 v74, v76, v77
	v_cvt_pk_bf16_f32 v75, v78, v79
	global_store_dwordx4 v[80:81], v[72:75], off nt
	v_cvt_pk_bf16_f32 v68, v68, v69
	v_cvt_pk_bf16_f32 v69, v70, v71
	v_cvt_pk_bf16_f32 v70, v64, v65
	v_add_u32_e32 v64, s0, v151
	v_ashrrev_i32_e32 v65, 31, v64
	v_lshlrev_b64 v[64:65], 11, v[64:65]
	v_lshl_add_u64 v[64:65], s[50:51], 0, v[64:65]
	v_lshl_add_u64 v[64:65], v[64:65], 0, v[144:145]
	v_cvt_pk_bf16_f32 v71, v66, v67
	global_store_dwordx4 v[80:81], v[68:71], off offset:256 nt
	v_cvt_pk_bf16_f32 v60, v60, v61
	v_cvt_pk_bf16_f32 v61, v62, v63
	v_cvt_pk_bf16_f32 v62, v56, v57
	v_cvt_pk_bf16_f32 v63, v58, v59
	global_store_dwordx4 v[64:65], v[60:63], off nt
	v_cvt_pk_bf16_f32 v48, v48, v49
	v_cvt_pk_bf16_f32 v49, v50, v51
	v_cvt_pk_bf16_f32 v50, v40, v41
	v_add_u32_e32 v40, s0, v152
	v_ashrrev_i32_e32 v41, 31, v40
	v_lshlrev_b64 v[40:41], 11, v[40:41]
	v_lshl_add_u64 v[40:41], s[50:51], 0, v[40:41]
	v_cvt_pk_bf16_f32 v51, v42, v43
	global_store_dwordx4 v[64:65], v[48:51], off offset:256 nt
	s_nop 1
	v_lshl_add_u64 v[48:49], v[40:41], 0, v[144:145]
	v_cvt_pk_bf16_f32 v40, v52, v53
	v_cvt_pk_bf16_f32 v41, v54, v55
	v_cvt_pk_bf16_f32 v42, v44, v45
	v_cvt_pk_bf16_f32 v43, v46, v47
	global_store_dwordx4 v[48:49], v[40:43], off nt
	v_cvt_pk_bf16_f32 v32, v32, v33
	v_cvt_pk_bf16_f32 v33, v34, v35
	v_cvt_pk_bf16_f32 v34, v24, v25
	v_add_u32_e32 v24, s0, v153
	v_ashrrev_i32_e32 v25, 31, v24
	v_lshlrev_b64 v[24:25], 11, v[24:25]
	v_lshl_add_u64 v[24:25], s[50:51], 0, v[24:25]
	v_cvt_pk_bf16_f32 v35, v26, v27
	global_store_dwordx4 v[48:49], v[32:35], off offset:256 nt
	s_nop 1
	v_lshl_add_u64 v[32:33], v[24:25], 0, v[144:145]
	v_cvt_pk_bf16_f32 v24, v36, v37
	v_cvt_pk_bf16_f32 v25, v38, v39
	v_cvt_pk_bf16_f32 v26, v28, v29
	v_cvt_pk_bf16_f32 v27, v30, v31
	global_store_dwordx4 v[32:33], v[24:27], off nt
	v_cvt_pk_bf16_f32 v20, v20, v21
	v_cvt_pk_bf16_f32 v21, v22, v23
	v_cvt_pk_bf16_f32 v22, v12, v13
	v_add_u32_e32 v12, s0, v154
	v_ashrrev_i32_e32 v13, 31, v12
	v_lshlrev_b64 v[12:13], 11, v[12:13]
	v_lshl_add_u64 v[12:13], s[50:51], 0, v[12:13]
	v_cvt_pk_bf16_f32 v23, v14, v15
	global_store_dwordx4 v[32:33], v[20:23], off offset:256 nt
	s_mov_b64 s[0:1], -1
	s_nop 0
	v_lshl_add_u64 v[20:21], v[12:13], 0, v[144:145]
	v_cvt_pk_bf16_f32 v12, v16, v17
	v_cvt_pk_bf16_f32 v13, v18, v19
	v_cvt_pk_bf16_f32 v14, v8, v9
	v_cvt_pk_bf16_f32 v15, v10, v11
	global_store_dwordx4 v[20:21], v[12:15], off nt
	v_cvt_pk_bf16_f32 v4, v4, v5
	v_cvt_pk_bf16_f32 v5, v6, v7
	v_cvt_pk_bf16_f32 v6, v0, v1
	v_cvt_pk_bf16_f32 v7, v2, v3
	global_store_dwordx4 v[20:21], v[4:7], off offset:256 nt
	s_cbranch_vccnz .LBB0_147
	s_andn2_b64 vcc, exec, s[10:11]
	s_cbranch_vccnz .LBB0_146
	s_barrier
	s_branch .LBB0_146

.LBB0_178:
	s_lshl_b32 s0, s26, 8
	v_add_u32_e32 v144, s0, v146
	v_ashrrev_i32_e32 v145, 31, v144
	v_lshl_or_b32 v160, s58, 8, v155
	v_lshlrev_b64 v[144:145], 11, v[144:145]
	v_ashrrev_i32_e32 v161, 31, v160
	v_lshl_add_u64 v[162:163], s[14:15], 0, v[144:145]
	v_lshlrev_b64 v[144:145], 1, v[160:161]
	v_lshl_add_u64 v[160:161], v[162:163], 0, v[144:145]
	v_cvt_pk_bf16_f32 v124, v124, v125
	v_cvt_pk_bf16_f32 v125, v126, v127
	v_cvt_pk_bf16_f32 v126, v120, v121
	v_cvt_pk_bf16_f32 v127, v122, v123
	global_store_dwordx4 v[160:161], v[124:127], off nt
	v_cvt_pk_bf16_f32 v112, v112, v113
	v_cvt_pk_bf16_f32 v113, v114, v115
	v_cvt_pk_bf16_f32 v114, v104, v105
	v_add_u32_e32 v104, s0, v148
	v_ashrrev_i32_e32 v105, 31, v104
	v_lshlrev_b64 v[104:105], 11, v[104:105]
	v_lshl_add_u64 v[104:105], s[14:15], 0, v[104:105]
	v_cvt_pk_bf16_f32 v115, v106, v107
	global_store_dwordx4 v[160:161], v[112:115], off offset:256 nt
	s_andn2_b64 vcc, exec, s[6:7]
	s_nop 0
	v_lshl_add_u64 v[112:113], v[104:105], 0, v[144:145]
	v_cvt_pk_bf16_f32 v104, v116, v117
	v_cvt_pk_bf16_f32 v105, v118, v119
	v_cvt_pk_bf16_f32 v106, v108, v109
	v_cvt_pk_bf16_f32 v107, v110, v111
	global_store_dwordx4 v[112:113], v[104:107], off nt
	v_cvt_pk_bf16_f32 v96, v96, v97
	v_cvt_pk_bf16_f32 v97, v98, v99
	v_cvt_pk_bf16_f32 v98, v88, v89
	v_add_u32_e32 v88, s0, v149
	v_ashrrev_i32_e32 v89, 31, v88
	v_lshlrev_b64 v[88:89], 11, v[88:89]
	v_lshl_add_u64 v[88:89], s[14:15], 0, v[88:89]
	v_cvt_pk_bf16_f32 v99, v90, v91
	global_store_dwordx4 v[112:113], v[96:99], off offset:256 nt
	s_nop 1
	v_lshl_add_u64 v[96:97], v[88:89], 0, v[144:145]
	v_cvt_pk_bf16_f32 v88, v100, v101
	v_cvt_pk_bf16_f32 v89, v102, v103
	v_cvt_pk_bf16_f32 v90, v92, v93
	v_cvt_pk_bf16_f32 v91, v94, v95
	global_store_dwordx4 v[96:97], v[88:91], off nt
	v_cvt_pk_bf16_f32 v80, v80, v81
	v_cvt_pk_bf16_f32 v81, v82, v83
	v_cvt_pk_bf16_f32 v82, v72, v73
	v_add_u32_e32 v72, s0, v150
	v_ashrrev_i32_e32 v73, 31, v72
	v_lshlrev_b64 v[72:73], 11, v[72:73]
	v_lshl_add_u64 v[72:73], s[14:15], 0, v[72:73]
	v_cvt_pk_bf16_f32 v83, v74, v75
	global_store_dwordx4 v[96:97], v[80:83], off offset:256 nt
	s_nop 1
	v_lshl_add_u64 v[80:81], v[72:73], 0, v[144:145]
	v_cvt_pk_bf16_f32 v72, v84, v85
	v_cvt_pk_bf16_f32 v73, v86, v87
	v_cvt_pk_bf16_f32 v74, v76, v77
	v_cvt_pk_bf16_f32 v75, v78, v79
	global_store_dwordx4 v[80:81], v[72:75], off nt
	v_cvt_pk_bf16_f32 v68, v68, v69
	v_cvt_pk_bf16_f32 v69, v70, v71
	v_cvt_pk_bf16_f32 v70, v64, v65
	v_add_u32_e32 v64, s0, v151
	v_ashrrev_i32_e32 v65, 31, v64
	v_lshlrev_b64 v[64:65], 11, v[64:65]
	v_lshl_add_u64 v[64:65], s[14:15], 0, v[64:65]
	v_lshl_add_u64 v[64:65], v[64:65], 0, v[144:145]
	v_cvt_pk_bf16_f32 v71, v66, v67
	global_store_dwordx4 v[80:81], v[68:71], off offset:256 nt
	v_cvt_pk_bf16_f32 v60, v60, v61
	v_cvt_pk_bf16_f32 v61, v62, v63
	v_cvt_pk_bf16_f32 v62, v56, v57
	v_cvt_pk_bf16_f32 v63, v58, v59
	global_store_dwordx4 v[64:65], v[60:63], off nt
	v_cvt_pk_bf16_f32 v48, v48, v49
	v_cvt_pk_bf16_f32 v49, v50, v51
	v_cvt_pk_bf16_f32 v50, v40, v41
	v_add_u32_e32 v40, s0, v152
	v_ashrrev_i32_e32 v41, 31, v40
	v_lshlrev_b64 v[40:41], 11, v[40:41]
	v_lshl_add_u64 v[40:41], s[14:15], 0, v[40:41]
	v_cvt_pk_bf16_f32 v51, v42, v43
	global_store_dwordx4 v[64:65], v[48:51], off offset:256 nt
	s_nop 1
	v_lshl_add_u64 v[48:49], v[40:41], 0, v[144:145]
	v_cvt_pk_bf16_f32 v40, v52, v53
	v_cvt_pk_bf16_f32 v41, v54, v55
	v_cvt_pk_bf16_f32 v42, v44, v45
	v_cvt_pk_bf16_f32 v43, v46, v47
	global_store_dwordx4 v[48:49], v[40:43], off nt
	v_cvt_pk_bf16_f32 v32, v32, v33
	v_cvt_pk_bf16_f32 v33, v34, v35
	v_cvt_pk_bf16_f32 v34, v24, v25
	v_add_u32_e32 v24, s0, v153
	v_ashrrev_i32_e32 v25, 31, v24
	v_lshlrev_b64 v[24:25], 11, v[24:25]
	v_lshl_add_u64 v[24:25], s[14:15], 0, v[24:25]
	v_cvt_pk_bf16_f32 v35, v26, v27
	global_store_dwordx4 v[48:49], v[32:35], off offset:256 nt
	s_nop 1
	v_lshl_add_u64 v[32:33], v[24:25], 0, v[144:145]
	v_cvt_pk_bf16_f32 v24, v36, v37
	v_cvt_pk_bf16_f32 v25, v38, v39
	v_cvt_pk_bf16_f32 v26, v28, v29
	v_cvt_pk_bf16_f32 v27, v30, v31
	global_store_dwordx4 v[32:33], v[24:27], off nt
	v_cvt_pk_bf16_f32 v16, v16, v17
	v_cvt_pk_bf16_f32 v17, v18, v19
	v_cvt_pk_bf16_f32 v18, v8, v9
	v_add_u32_e32 v8, s0, v154
	v_ashrrev_i32_e32 v9, 31, v8
	v_lshlrev_b64 v[8:9], 11, v[8:9]
	v_lshl_add_u64 v[8:9], s[14:15], 0, v[8:9]
	v_cvt_pk_bf16_f32 v19, v10, v11
	global_store_dwordx4 v[32:33], v[16:19], off offset:256 nt
	s_mov_b64 s[0:1], -1
	s_nop 0
	v_lshl_add_u64 v[16:17], v[8:9], 0, v[144:145]
	v_cvt_pk_bf16_f32 v8, v20, v21
	v_cvt_pk_bf16_f32 v9, v22, v23
	v_cvt_pk_bf16_f32 v10, v12, v13
	v_cvt_pk_bf16_f32 v11, v14, v15
	global_store_dwordx4 v[16:17], v[8:11], off nt
	v_cvt_pk_bf16_f32 v4, v4, v5
	v_cvt_pk_bf16_f32 v5, v6, v7
	v_cvt_pk_bf16_f32 v6, v0, v1
	v_cvt_pk_bf16_f32 v7, v2, v3
	global_store_dwordx4 v[16:17], v[4:7], off offset:256 nt
	s_cbranch_vccnz .LBB0_167
	s_andn2_b64 vcc, exec, s[10:11]
	s_cbranch_vccnz .LBB0_166
	s_barrier
	s_branch .LBB0_166

.LBB0_198:
	s_lshl_b32 s0, s34, 8
	v_add_u32_e32 v144, s0, v146
	v_ashrrev_i32_e32 v145, 31, v144
	v_lshl_or_b32 v160, s76, 8, v155
	v_lshlrev_b64 v[144:145], 9, v[144:145]
	v_ashrrev_i32_e32 v161, 31, v160
	v_lshl_add_u64 v[162:163], s[16:17], 0, v[144:145]
	v_lshlrev_b64 v[144:145], 1, v[160:161]
	v_lshl_add_u64 v[160:161], v[162:163], 0, v[144:145]
	v_cvt_pk_bf16_f32 v124, v124, v125
	v_cvt_pk_bf16_f32 v125, v126, v127
	v_cvt_pk_bf16_f32 v126, v120, v121
	v_cvt_pk_bf16_f32 v127, v122, v123
	global_store_dwordx4 v[160:161], v[124:127], off nt
	v_cvt_pk_bf16_f32 v112, v112, v113
	v_cvt_pk_bf16_f32 v113, v114, v115
	v_cvt_pk_bf16_f32 v114, v104, v105
	v_add_u32_e32 v104, s0, v148
	v_ashrrev_i32_e32 v105, 31, v104
	v_lshlrev_b64 v[104:105], 9, v[104:105]
	v_lshl_add_u64 v[104:105], s[16:17], 0, v[104:105]
	v_cvt_pk_bf16_f32 v115, v106, v107
	global_store_dwordx4 v[160:161], v[112:115], off offset:256 nt
	s_andn2_b64 vcc, exec, s[6:7]
	s_nop 0
	v_lshl_add_u64 v[112:113], v[104:105], 0, v[144:145]
	v_cvt_pk_bf16_f32 v104, v116, v117
	v_cvt_pk_bf16_f32 v105, v118, v119
	v_cvt_pk_bf16_f32 v106, v108, v109
	v_cvt_pk_bf16_f32 v107, v110, v111
	global_store_dwordx4 v[112:113], v[104:107], off nt
	v_cvt_pk_bf16_f32 v96, v96, v97
	v_cvt_pk_bf16_f32 v97, v98, v99
	v_cvt_pk_bf16_f32 v98, v88, v89
	v_add_u32_e32 v88, s0, v149
	v_ashrrev_i32_e32 v89, 31, v88
	v_lshlrev_b64 v[88:89], 9, v[88:89]
	v_lshl_add_u64 v[88:89], s[16:17], 0, v[88:89]
	v_cvt_pk_bf16_f32 v99, v90, v91
	global_store_dwordx4 v[112:113], v[96:99], off offset:256 nt
	s_nop 1
	v_lshl_add_u64 v[96:97], v[88:89], 0, v[144:145]
	v_cvt_pk_bf16_f32 v88, v100, v101
	v_cvt_pk_bf16_f32 v89, v102, v103
	v_cvt_pk_bf16_f32 v90, v92, v93
	v_cvt_pk_bf16_f32 v91, v94, v95
	global_store_dwordx4 v[96:97], v[88:91], off nt
	v_cvt_pk_bf16_f32 v80, v80, v81
	v_cvt_pk_bf16_f32 v81, v82, v83
	v_cvt_pk_bf16_f32 v82, v72, v73
	v_add_u32_e32 v72, s0, v150
	v_ashrrev_i32_e32 v73, 31, v72
	v_lshlrev_b64 v[72:73], 9, v[72:73]
	v_lshl_add_u64 v[72:73], s[16:17], 0, v[72:73]
	v_cvt_pk_bf16_f32 v83, v74, v75
	global_store_dwordx4 v[96:97], v[80:83], off offset:256 nt
	s_nop 1
	v_lshl_add_u64 v[80:81], v[72:73], 0, v[144:145]
	v_cvt_pk_bf16_f32 v72, v84, v85
	v_cvt_pk_bf16_f32 v73, v86, v87
	v_cvt_pk_bf16_f32 v74, v76, v77
	v_cvt_pk_bf16_f32 v75, v78, v79
	global_store_dwordx4 v[80:81], v[72:75], off nt
	v_cvt_pk_bf16_f32 v68, v68, v69
	v_cvt_pk_bf16_f32 v69, v70, v71
	v_cvt_pk_bf16_f32 v70, v64, v65
	v_add_u32_e32 v64, s0, v151
	v_ashrrev_i32_e32 v65, 31, v64
	v_lshlrev_b64 v[64:65], 9, v[64:65]
	v_lshl_add_u64 v[64:65], s[16:17], 0, v[64:65]
	v_lshl_add_u64 v[64:65], v[64:65], 0, v[144:145]
	v_cvt_pk_bf16_f32 v71, v66, v67
	global_store_dwordx4 v[80:81], v[68:71], off offset:256 nt
	v_cvt_pk_bf16_f32 v60, v60, v61
	v_cvt_pk_bf16_f32 v61, v62, v63
	v_cvt_pk_bf16_f32 v62, v56, v57
	v_cvt_pk_bf16_f32 v63, v58, v59
	global_store_dwordx4 v[64:65], v[60:63], off nt
	v_cvt_pk_bf16_f32 v48, v48, v49
	v_cvt_pk_bf16_f32 v49, v50, v51
	v_cvt_pk_bf16_f32 v50, v40, v41
	v_add_u32_e32 v40, s0, v152
	v_ashrrev_i32_e32 v41, 31, v40
	v_lshlrev_b64 v[40:41], 9, v[40:41]
	v_lshl_add_u64 v[40:41], s[16:17], 0, v[40:41]
	v_cvt_pk_bf16_f32 v51, v42, v43
	global_store_dwordx4 v[64:65], v[48:51], off offset:256 nt
	s_nop 1
	v_lshl_add_u64 v[48:49], v[40:41], 0, v[144:145]
	v_cvt_pk_bf16_f32 v40, v52, v53
	v_cvt_pk_bf16_f32 v41, v54, v55
	v_cvt_pk_bf16_f32 v42, v44, v45
	v_cvt_pk_bf16_f32 v43, v46, v47
	global_store_dwordx4 v[48:49], v[40:43], off nt
	v_cvt_pk_bf16_f32 v32, v32, v33
	v_cvt_pk_bf16_f32 v33, v34, v35
	v_cvt_pk_bf16_f32 v34, v24, v25
	v_add_u32_e32 v24, s0, v153
	v_ashrrev_i32_e32 v25, 31, v24
	v_lshlrev_b64 v[24:25], 9, v[24:25]
	v_lshl_add_u64 v[24:25], s[16:17], 0, v[24:25]
	v_cvt_pk_bf16_f32 v35, v26, v27
	global_store_dwordx4 v[48:49], v[32:35], off offset:256 nt
	s_nop 1
	v_lshl_add_u64 v[32:33], v[24:25], 0, v[144:145]
	v_cvt_pk_bf16_f32 v24, v36, v37
	v_cvt_pk_bf16_f32 v25, v38, v39
	v_cvt_pk_bf16_f32 v26, v28, v29
	v_cvt_pk_bf16_f32 v27, v30, v31
	global_store_dwordx4 v[32:33], v[24:27], off nt
	v_cvt_pk_bf16_f32 v16, v16, v17
	v_cvt_pk_bf16_f32 v17, v18, v19
	v_cvt_pk_bf16_f32 v18, v8, v9
	v_add_u32_e32 v8, s0, v154
	v_ashrrev_i32_e32 v9, 31, v8
	v_lshlrev_b64 v[8:9], 9, v[8:9]
	v_lshl_add_u64 v[8:9], s[16:17], 0, v[8:9]
	v_cvt_pk_bf16_f32 v19, v10, v11
	global_store_dwordx4 v[32:33], v[16:19], off offset:256 nt
	s_mov_b64 s[0:1], -1
	s_nop 0
	v_lshl_add_u64 v[16:17], v[8:9], 0, v[144:145]
	v_cvt_pk_bf16_f32 v8, v20, v21
	v_cvt_pk_bf16_f32 v9, v22, v23
	v_cvt_pk_bf16_f32 v10, v12, v13
	v_cvt_pk_bf16_f32 v11, v14, v15
	global_store_dwordx4 v[16:17], v[8:11], off nt
	v_cvt_pk_bf16_f32 v4, v4, v5
	v_cvt_pk_bf16_f32 v5, v6, v7
	v_cvt_pk_bf16_f32 v6, v0, v1
	v_cvt_pk_bf16_f32 v7, v2, v3
	global_store_dwordx4 v[16:17], v[4:7], off offset:256 nt
	s_cbranch_vccnz .LBB0_187
	s_andn2_b64 vcc, exec, s[18:19]
	s_cbranch_vccnz .LBB0_186
	s_barrier
	s_branch .LBB0_186

.LBB0_332:
	s_waitcnt vmcnt(0)
	v_lshl_add_u32 v144, s10, 8, v150
	v_ashrrev_i32_e32 v145, 31, v144
	v_lshl_or_b32 v142, s96, 8, v152
	v_lshlrev_b64 v[146:147], 10, v[144:145]
	v_cmp_lt_i32_e64 s[8:9], s33, v142
	v_add_u32_e32 v136, 0xfffffc00, v142
	v_lshl_add_u64 v[146:147], s[80:81], 0, v[146:147]
	s_and_saveexec_b64 s[0:1], s[8:9]
	s_xor_b64 s[10:11], exec, s[0:1]
	s_cbranch_execz .LBB0_334
	v_pk_add_f32 v[120:121], v[120:121], v[170:171]
	v_pk_add_f32 v[124:125], v[124:125], v[166:167]
	v_pk_add_f32 v[148:149], v[122:123], v[172:173]
	v_mul_f32_e32 v122, 0xbfb8aa3b, v124
	v_mul_f32_e32 v120, 0xbfb8aa3b, v120
	v_exp_f32_e32 v124, v122
	v_mul_f32_e32 v122, 0xbfb8aa3b, v125
	v_exp_f32_e32 v125, v120
	v_pk_add_f32 v[126:127], v[126:127], v[168:169]
	v_mul_f32_e32 v120, 0xbfb8aa3b, v121
	v_exp_f32_e32 v156, v122
	v_mul_f32_e32 v122, 0xbfb8aa3b, v126
	v_exp_f32_e32 v157, v120
	v_mul_f32_e32 v120, 0xbfb8aa3b, v148
	v_exp_f32_e32 v126, v122
	v_mul_f32_e32 v122, 0xbfb8aa3b, v127
	v_exp_f32_e32 v127, v120
	v_mul_f32_e32 v120, 0xbfb8aa3b, v149
	v_exp_f32_e32 v123, v120
	v_pk_add_f32 v[120:121], v[124:125], 1.0 op_sel_hi:[1,0]
	v_pk_add_f32 v[126:127], v[126:127], 1.0 op_sel_hi:[1,0]
	v_exp_f32_e32 v122, v122
	v_rcp_f32_e32 v121, v121
	v_pk_add_f32 v[122:123], v[122:123], 1.0 op_sel_hi:[1,0]
	v_rcp_f32_e32 v120, v120
	v_pk_add_f32 v[124:125], v[156:157], 1.0 op_sel_hi:[1,0]
	v_pk_fma_f32 v[120:121], v[120:121], s[28:29], 0.5 op_sel_hi:[1,0,0]
	v_rcp_f32_e32 v125, v125
	v_rcp_f32_e32 v124, v124
	v_rcp_f32_e32 v127, v127
	v_rcp_f32_e32 v126, v126
	v_rcp_f32_e32 v123, v123
	v_rcp_f32_e32 v122, v122
	v_cvt_u32_f32_e32 v143, v121
	v_cvt_u32_f32_e32 v148, v120
	v_pk_fma_f32 v[120:121], v[124:125], s[28:29], 0.5 op_sel_hi:[1,0,0]
	s_nop 0
	v_cvt_u32_f32_e32 v120, v120
	v_cvt_u32_f32_e32 v121, v121
	v_lshlrev_b32_e32 v120, 8, v120
	v_lshlrev_b32_e32 v121, 8, v121
	v_or_b32_e32 v124, v121, v143
	v_or_b32_e32 v125, v120, v148
	v_pk_fma_f32 v[120:121], v[126:127], s[28:29], 0.5 op_sel_hi:[1,0,0]
	s_nop 0
	v_cvt_u32_f32_sdwa v120, v120 dst_sel:WORD_1 dst_unused:UNUSED_PAD src0_sel:DWORD
	v_cvt_u32_f32_sdwa v121, v121 dst_sel:WORD_1 dst_unused:UNUSED_PAD src0_sel:DWORD
	v_or_b32_e32 v125, v125, v120
	v_or_b32_e32 v124, v124, v121
	v_pk_fma_f32 v[120:121], v[122:123], s[28:29], 0.5 op_sel_hi:[1,0,0]
	v_lshl_add_u64 v[122:123], v[146:147], 0, v[136:137]
	v_cvt_u32_f32_sdwa v120, v120 dst_sel:BYTE_3 dst_unused:UNUSED_PAD src0_sel:DWORD
	v_cvt_u32_f32_sdwa v121, v121 dst_sel:BYTE_3 dst_unused:UNUSED_PAD src0_sel:DWORD
	v_or_b32_e32 v120, v125, v120
	v_or_b32_e32 v121, v124, v121
	global_store_dwordx2 v[122:123], v[120:121], off nt
.LBB0_334:
	s_or_saveexec_b64 s[10:11], s[10:11]
	v_lshlrev_b64 v[148:149], 11, v[144:145]
	v_ashrrev_i32_e32 v143, 31, v142
	v_lshl_add_u64 v[148:149], s[62:63], 0, v[148:149]
	s_xor_b64 exec, exec, s[10:11]
	s_cbranch_execz .LBB0_336
	v_pk_add_f32 v[120:121], v[120:121], v[170:171]
	v_pk_add_f32 v[124:125], v[124:125], v[166:167]
	v_pk_add_f32 v[122:123], v[122:123], v[172:173]
	v_mul_f32_e32 v124, 0xbfb8aa3b, v124
	v_exp_f32_e32 v124, v124
	v_mul_f32_e32 v125, 0xbfb8aa3b, v125
	v_exp_f32_e32 v125, v125
	v_pk_add_f32 v[126:127], v[126:127], v[168:169]
	v_add_f32_e32 v124, 1.0, v124
	v_add_f32_e32 v125, 1.0, v125
	v_mul_f32_e32 v126, 0xbfb8aa3b, v126
	v_exp_f32_e32 v126, v126
	v_rcp_f32_e32 v124, v124
	v_add_f32_e32 v126, 1.0, v126
	v_mul_f32_e32 v127, 0xbfb8aa3b, v127
	v_exp_f32_e32 v127, v127
	v_rcp_f32_e32 v125, v125
	v_add_f32_e32 v127, 1.0, v127
	v_mul_f32_e32 v120, 0xbfb8aa3b, v120
	v_exp_f32_e32 v120, v120
	v_rcp_f32_e32 v126, v126
	v_add_f32_e32 v120, 1.0, v120
	v_mul_f32_e32 v124, 0xbf60028a, v124
	v_mul_f32_e32 v125, 0xbf60028a, v125
	v_rcp_f32_e32 v127, v127
	v_mul_f32_e32 v126, 0xbf60028a, v126
	v_mul_f32_e32 v127, 0xbf60028a, v127
	v_rcp_f32_e32 v120, v120
	s_nop 0
	v_mul_f32_e32 v145, 0xbf60028a, v120
	v_mul_f32_e32 v120, 0xbfb8aa3b, v121
	v_exp_f32_e32 v120, v120
	s_nop 0
	v_add_f32_e32 v120, 1.0, v120
	v_rcp_f32_e32 v120, v120
	s_nop 0
	v_mul_f32_e32 v158, 0xbf60028a, v120
	v_mul_f32_e32 v120, 0xbfb8aa3b, v122
	v_exp_f32_e32 v120, v120
	s_nop 0
	v_add_f32_e32 v120, 1.0, v120
	v_rcp_f32_e32 v120, v120
	s_nop 0
	v_mul_f32_e32 v159, 0xbf60028a, v120
	v_mul_f32_e32 v120, 0xbfb8aa3b, v123
	v_exp_f32_e32 v120, v120
	s_nop 0
	v_add_f32_e32 v120, 1.0, v120
	v_rcp_f32_e32 v120, v120
	s_nop 0
	v_mul_f32_e32 v123, 0xbf60028a, v120
	v_lshl_add_u64 v[156:157], v[142:143], 1, v[148:149]
	v_cvt_pk_bf16_f32 v120, v124, v125
	v_cvt_pk_bf16_f32 v121, v126, v127
	v_cvt_pk_bf16_f32 v122, v145, v158
	v_cvt_pk_bf16_f32 v123, v159, v123
	global_store_dwordx4 v[156:157], v[120:123], off nt
.LBB0_336:
	s_or_b64 exec, exec, s[10:11]
	s_nop 0
	v_or_b32_e32 v120, 0x80, v142
	v_cmp_lt_i32_e64 s[10:11], s33, v120
	v_add_u32_e32 v120, 0xfffffc80, v142
	s_and_saveexec_b64 s[0:1], s[10:11]
	s_xor_b64 s[96:97], exec, s[0:1]
	s_cbranch_execz .LBB0_338
	v_mov_b32_e32 v121, v137
	v_pk_add_f32 v[112:113], v[112:113], v[178:179]
	v_pk_add_f32 v[116:117], v[116:117], v[174:175]
	v_pk_add_f32 v[124:125], v[114:115], v[180:181]
	v_mul_f32_e32 v114, 0xbfb8aa3b, v116
	v_mul_f32_e32 v112, 0xbfb8aa3b, v112
	v_exp_f32_e32 v116, v114
	v_mul_f32_e32 v114, 0xbfb8aa3b, v117
	v_exp_f32_e32 v117, v112
	v_pk_add_f32 v[118:119], v[118:119], v[176:177]
	v_mul_f32_e32 v112, 0xbfb8aa3b, v113
	v_exp_f32_e32 v122, v114
	v_mul_f32_e32 v114, 0xbfb8aa3b, v118
	v_exp_f32_e32 v123, v112
	v_mul_f32_e32 v112, 0xbfb8aa3b, v124
	v_exp_f32_e32 v118, v114
	v_mul_f32_e32 v114, 0xbfb8aa3b, v119
	v_exp_f32_e32 v119, v112
	v_mul_f32_e32 v112, 0xbfb8aa3b, v125
	v_exp_f32_e32 v115, v112
	v_pk_add_f32 v[112:113], v[116:117], 1.0 op_sel_hi:[1,0]
	v_pk_add_f32 v[118:119], v[118:119], 1.0 op_sel_hi:[1,0]
	v_exp_f32_e32 v114, v114
	v_rcp_f32_e32 v113, v113
	v_pk_add_f32 v[114:115], v[114:115], 1.0 op_sel_hi:[1,0]
	v_rcp_f32_e32 v112, v112
	v_pk_add_f32 v[116:117], v[122:123], 1.0 op_sel_hi:[1,0]
	v_pk_fma_f32 v[112:113], v[112:113], s[28:29], 0.5 op_sel_hi:[1,0,0]
	v_rcp_f32_e32 v117, v117
	v_rcp_f32_e32 v116, v116
	v_rcp_f32_e32 v119, v119
	v_rcp_f32_e32 v118, v118
	v_rcp_f32_e32 v115, v115
	v_rcp_f32_e32 v114, v114
	v_cvt_u32_f32_e32 v122, v113
	v_cvt_u32_f32_e32 v123, v112
	v_pk_fma_f32 v[112:113], v[116:117], s[28:29], 0.5 op_sel_hi:[1,0,0]
	s_nop 0
	v_cvt_u32_f32_e32 v112, v112
	v_cvt_u32_f32_e32 v113, v113
	v_lshlrev_b32_e32 v112, 8, v112
	v_lshlrev_b32_e32 v113, 8, v113
	v_or_b32_e32 v116, v113, v122
	v_or_b32_e32 v117, v112, v123
	v_pk_fma_f32 v[112:113], v[118:119], s[28:29], 0.5 op_sel_hi:[1,0,0]
	s_nop 0
	v_cvt_u32_f32_sdwa v112, v112 dst_sel:WORD_1 dst_unused:UNUSED_PAD src0_sel:DWORD
	v_cvt_u32_f32_sdwa v113, v113 dst_sel:WORD_1 dst_unused:UNUSED_PAD src0_sel:DWORD
	v_or_b32_e32 v117, v117, v112
	v_or_b32_e32 v116, v116, v113
	v_pk_fma_f32 v[112:113], v[114:115], s[28:29], 0.5 op_sel_hi:[1,0,0]
	v_lshl_add_u64 v[114:115], v[146:147], 0, v[120:121]
	v_cvt_u32_f32_sdwa v112, v112 dst_sel:BYTE_3 dst_unused:UNUSED_PAD src0_sel:DWORD
	v_cvt_u32_f32_sdwa v113, v113 dst_sel:BYTE_3 dst_unused:UNUSED_PAD src0_sel:DWORD
	v_or_b32_e32 v112, v117, v112
	v_or_b32_e32 v113, v116, v113
	global_store_dwordx2 v[114:115], v[112:113], off nt
.LBB0_338:
	s_andn2_saveexec_b64 s[96:97], s[96:97]
	s_cbranch_execz .LBB0_340
	v_pk_add_f32 v[112:113], v[112:113], v[178:179]
	v_pk_add_f32 v[116:117], v[116:117], v[174:175]
	v_pk_add_f32 v[114:115], v[114:115], v[180:181]
	v_mul_f32_e32 v116, 0xbfb8aa3b, v116
	v_exp_f32_e32 v116, v116
	v_mul_f32_e32 v117, 0xbfb8aa3b, v117
	v_exp_f32_e32 v117, v117
	v_pk_add_f32 v[118:119], v[118:119], v[176:177]
	v_add_f32_e32 v116, 1.0, v116
	v_add_f32_e32 v117, 1.0, v117
	v_mul_f32_e32 v118, 0xbfb8aa3b, v118
	v_exp_f32_e32 v118, v118
	v_rcp_f32_e32 v116, v116
	v_add_f32_e32 v118, 1.0, v118
	v_mul_f32_e32 v119, 0xbfb8aa3b, v119
	v_exp_f32_e32 v119, v119
	v_rcp_f32_e32 v117, v117
	v_add_f32_e32 v119, 1.0, v119
	v_mul_f32_e32 v112, 0xbfb8aa3b, v112
	v_exp_f32_e32 v112, v112
	v_rcp_f32_e32 v118, v118
	v_add_f32_e32 v112, 1.0, v112
	v_mul_f32_e32 v116, 0xbf60028a, v116
	v_mul_f32_e32 v117, 0xbf60028a, v117
	v_rcp_f32_e32 v119, v119
	v_mul_f32_e32 v118, 0xbf60028a, v118
	v_mul_f32_e32 v119, 0xbf60028a, v119
	v_rcp_f32_e32 v112, v112
	s_nop 0
	v_mul_f32_e32 v121, 0xbf60028a, v112
	v_mul_f32_e32 v112, 0xbfb8aa3b, v113
	v_exp_f32_e32 v112, v112
	s_nop 0
	v_add_f32_e32 v112, 1.0, v112
	v_rcp_f32_e32 v112, v112
	s_nop 0
	v_mul_f32_e32 v124, 0xbf60028a, v112
	v_mul_f32_e32 v112, 0xbfb8aa3b, v114
	v_exp_f32_e32 v112, v112
	s_nop 0
	v_add_f32_e32 v112, 1.0, v112
	v_rcp_f32_e32 v112, v112
	s_nop 0
	v_mul_f32_e32 v125, 0xbf60028a, v112
	v_mul_f32_e32 v112, 0xbfb8aa3b, v115
	v_exp_f32_e32 v112, v112
	s_nop 0
	v_add_f32_e32 v112, 1.0, v112
	v_rcp_f32_e32 v112, v112
	s_nop 0
	v_mul_f32_e32 v115, 0xbf60028a, v112
	v_lshl_add_u64 v[122:123], v[142:143], 1, v[148:149]
	v_cvt_pk_bf16_f32 v112, v116, v117
	v_cvt_pk_bf16_f32 v113, v118, v119
	v_cvt_pk_bf16_f32 v114, v121, v124
	v_cvt_pk_bf16_f32 v115, v125, v115
	global_store_dwordx4 v[122:123], v[112:115], off offset:256 nt
.LBB0_340:
	s_or_b64 exec, exec, s[96:97]
	s_nop 0
	v_or_b32_e32 v114, 16, v144
	v_ashrrev_i32_e32 v115, 31, v114
	v_lshlrev_b64 v[112:113], 10, v[114:115]
	v_lshl_add_u64 v[112:113], s[80:81], 0, v[112:113]
	s_and_saveexec_b64 s[0:1], s[8:9]
	s_xor_b64 s[96:97], exec, s[0:1]
	s_cbranch_execz .LBB0_342
	v_pk_add_f32 v[104:105], v[104:105], v[170:171]
	v_pk_add_f32 v[108:109], v[108:109], v[166:167]
	v_pk_add_f32 v[118:119], v[106:107], v[172:173]
	v_mul_f32_e32 v106, 0xbfb8aa3b, v108
	v_mul_f32_e32 v104, 0xbfb8aa3b, v104
	v_exp_f32_e32 v108, v106
	v_mul_f32_e32 v106, 0xbfb8aa3b, v109
	v_exp_f32_e32 v109, v104
	v_pk_add_f32 v[110:111], v[110:111], v[168:169]
	v_mul_f32_e32 v104, 0xbfb8aa3b, v105
	v_exp_f32_e32 v116, v106
	v_mul_f32_e32 v106, 0xbfb8aa3b, v110
	v_exp_f32_e32 v117, v104
	v_mul_f32_e32 v104, 0xbfb8aa3b, v118
	v_exp_f32_e32 v110, v106
	v_mul_f32_e32 v106, 0xbfb8aa3b, v111
	v_exp_f32_e32 v111, v104
	v_mul_f32_e32 v104, 0xbfb8aa3b, v119
	v_exp_f32_e32 v107, v104
	v_pk_add_f32 v[104:105], v[108:109], 1.0 op_sel_hi:[1,0]
	v_pk_add_f32 v[110:111], v[110:111], 1.0 op_sel_hi:[1,0]
	v_exp_f32_e32 v106, v106
	v_rcp_f32_e32 v105, v105
	v_pk_add_f32 v[106:107], v[106:107], 1.0 op_sel_hi:[1,0]
	v_rcp_f32_e32 v104, v104
	v_pk_add_f32 v[108:109], v[116:117], 1.0 op_sel_hi:[1,0]
	v_pk_fma_f32 v[104:105], v[104:105], s[28:29], 0.5 op_sel_hi:[1,0,0]
	v_rcp_f32_e32 v109, v109
	v_rcp_f32_e32 v108, v108
	v_rcp_f32_e32 v111, v111
	v_rcp_f32_e32 v110, v110
	v_rcp_f32_e32 v107, v107
	v_rcp_f32_e32 v106, v106
	v_cvt_u32_f32_e32 v116, v105
	v_cvt_u32_f32_e32 v117, v104
	v_pk_fma_f32 v[104:105], v[108:109], s[28:29], 0.5 op_sel_hi:[1,0,0]
	s_nop 0
	v_cvt_u32_f32_e32 v104, v104
	v_cvt_u32_f32_e32 v105, v105
	v_lshlrev_b32_e32 v104, 8, v104
	v_lshlrev_b32_e32 v105, 8, v105
	v_or_b32_e32 v108, v105, v116
	v_or_b32_e32 v109, v104, v117
	v_pk_fma_f32 v[104:105], v[110:111], s[28:29], 0.5 op_sel_hi:[1,0,0]
	s_nop 0
	v_cvt_u32_f32_sdwa v104, v104 dst_sel:WORD_1 dst_unused:UNUSED_PAD src0_sel:DWORD
	v_cvt_u32_f32_sdwa v105, v105 dst_sel:WORD_1 dst_unused:UNUSED_PAD src0_sel:DWORD
	v_or_b32_e32 v109, v109, v104
	v_or_b32_e32 v108, v108, v105
	v_pk_fma_f32 v[104:105], v[106:107], s[28:29], 0.5 op_sel_hi:[1,0,0]
	v_lshl_add_u64 v[106:107], v[112:113], 0, v[136:137]
	v_cvt_u32_f32_sdwa v104, v104 dst_sel:BYTE_3 dst_unused:UNUSED_PAD src0_sel:DWORD
	v_cvt_u32_f32_sdwa v105, v105 dst_sel:BYTE_3 dst_unused:UNUSED_PAD src0_sel:DWORD
	v_or_b32_e32 v104, v109, v104
	v_or_b32_e32 v105, v108, v105
	global_store_dwordx2 v[106:107], v[104:105], off nt

.LBB0_345:
	v_pk_add_f32 v[96:97], v[96:97], v[178:179]
	v_pk_add_f32 v[100:101], v[100:101], v[174:175]
	v_pk_add_f32 v[98:99], v[98:99], v[180:181]
	v_mul_f32_e32 v100, 0xbfb8aa3b, v100
	v_exp_f32_e32 v100, v100
	v_mul_f32_e32 v101, 0xbfb8aa3b, v101
	v_exp_f32_e32 v101, v101
	v_pk_add_f32 v[102:103], v[102:103], v[176:177]
	v_add_f32_e32 v100, 1.0, v100
	v_add_f32_e32 v101, 1.0, v101
	v_mul_f32_e32 v102, 0xbfb8aa3b, v102
	v_exp_f32_e32 v102, v102
	v_rcp_f32_e32 v100, v100
	v_add_f32_e32 v102, 1.0, v102
	v_mul_f32_e32 v103, 0xbfb8aa3b, v103
	v_exp_f32_e32 v103, v103
	v_rcp_f32_e32 v101, v101
	v_add_f32_e32 v103, 1.0, v103
	v_mul_f32_e32 v96, 0xbfb8aa3b, v96
	v_exp_f32_e32 v96, v96
	v_rcp_f32_e32 v102, v102
	v_add_f32_e32 v96, 1.0, v96
	v_mul_f32_e32 v100, 0xbf60028a, v100
	v_mul_f32_e32 v101, 0xbf60028a, v101
	v_rcp_f32_e32 v103, v103
	v_mul_f32_e32 v102, 0xbf60028a, v102
	v_mul_f32_e32 v103, 0xbf60028a, v103
	v_rcp_f32_e32 v96, v96
	s_nop 0
	v_mul_f32_e32 v106, 0xbf60028a, v96
	v_mul_f32_e32 v96, 0xbfb8aa3b, v97
	v_exp_f32_e32 v96, v96
	s_nop 0
	v_add_f32_e32 v96, 1.0, v96
	v_rcp_f32_e32 v96, v96
	s_nop 0
	v_mul_f32_e32 v107, 0xbf60028a, v96
	v_mul_f32_e32 v96, 0xbfb8aa3b, v98
	v_exp_f32_e32 v96, v96
	s_nop 0
	v_add_f32_e32 v96, 1.0, v96
	v_rcp_f32_e32 v96, v96
	s_nop 0
	v_mul_f32_e32 v108, 0xbf60028a, v96
	v_mul_f32_e32 v96, 0xbfb8aa3b, v99
	v_exp_f32_e32 v96, v96
	s_nop 0
	v_add_f32_e32 v96, 1.0, v96
	v_rcp_f32_e32 v96, v96
	s_nop 0
	v_mul_f32_e32 v99, 0xbf60028a, v96
	v_lshl_add_u64 v[104:105], v[142:143], 1, v[114:115]
	v_cvt_pk_bf16_f32 v96, v100, v101
	v_cvt_pk_bf16_f32 v97, v102, v103
	v_cvt_pk_bf16_f32 v98, v106, v107
	v_cvt_pk_bf16_f32 v99, v108, v99
	global_store_dwordx4 v[104:105], v[96:99], off offset:256 nt
.LBB0_346:
	s_or_b64 exec, exec, s[96:97]
	s_nop 0
	v_or_b32_e32 v98, 32, v144
	v_ashrrev_i32_e32 v99, 31, v98
	v_lshlrev_b64 v[96:97], 10, v[98:99]
	v_lshl_add_u64 v[96:97], s[80:81], 0, v[96:97]
	s_and_saveexec_b64 s[0:1], s[8:9]
	s_xor_b64 s[96:97], exec, s[0:1]
	s_cbranch_execz .LBB0_348
	v_pk_add_f32 v[88:89], v[88:89], v[170:171]
	v_pk_add_f32 v[92:93], v[92:93], v[166:167]
	v_pk_add_f32 v[102:103], v[90:91], v[172:173]
	v_mul_f32_e32 v90, 0xbfb8aa3b, v92
	v_mul_f32_e32 v88, 0xbfb8aa3b, v88
	v_exp_f32_e32 v92, v90
	v_mul_f32_e32 v90, 0xbfb8aa3b, v93
	v_exp_f32_e32 v93, v88
	v_pk_add_f32 v[94:95], v[94:95], v[168:169]
	v_mul_f32_e32 v88, 0xbfb8aa3b, v89
	v_exp_f32_e32 v100, v90
	v_mul_f32_e32 v90, 0xbfb8aa3b, v94
	v_exp_f32_e32 v101, v88
	v_mul_f32_e32 v88, 0xbfb8aa3b, v102
	v_exp_f32_e32 v94, v90
	v_mul_f32_e32 v90, 0xbfb8aa3b, v95
	v_exp_f32_e32 v95, v88
	v_mul_f32_e32 v88, 0xbfb8aa3b, v103
	v_exp_f32_e32 v91, v88
	v_pk_add_f32 v[88:89], v[92:93], 1.0 op_sel_hi:[1,0]
	v_pk_add_f32 v[94:95], v[94:95], 1.0 op_sel_hi:[1,0]
	v_exp_f32_e32 v90, v90
	v_rcp_f32_e32 v89, v89
	v_pk_add_f32 v[90:91], v[90:91], 1.0 op_sel_hi:[1,0]
	v_rcp_f32_e32 v88, v88
	v_pk_add_f32 v[92:93], v[100:101], 1.0 op_sel_hi:[1,0]
	v_pk_fma_f32 v[88:89], v[88:89], s[28:29], 0.5 op_sel_hi:[1,0,0]
	v_rcp_f32_e32 v93, v93
	v_rcp_f32_e32 v92, v92
	v_rcp_f32_e32 v95, v95
	v_rcp_f32_e32 v94, v94
	v_rcp_f32_e32 v91, v91
	v_rcp_f32_e32 v90, v90
	v_cvt_u32_f32_e32 v100, v89
	v_cvt_u32_f32_e32 v101, v88
	v_pk_fma_f32 v[88:89], v[92:93], s[28:29], 0.5 op_sel_hi:[1,0,0]
	s_nop 0
	v_cvt_u32_f32_e32 v88, v88
	v_cvt_u32_f32_e32 v89, v89
	v_lshlrev_b32_e32 v88, 8, v88
	v_lshlrev_b32_e32 v89, 8, v89
	v_or_b32_e32 v92, v89, v100
	v_or_b32_e32 v93, v88, v101
	v_pk_fma_f32 v[88:89], v[94:95], s[28:29], 0.5 op_sel_hi:[1,0,0]
	s_nop 0
	v_cvt_u32_f32_sdwa v88, v88 dst_sel:WORD_1 dst_unused:UNUSED_PAD src0_sel:DWORD
	v_cvt_u32_f32_sdwa v89, v89 dst_sel:WORD_1 dst_unused:UNUSED_PAD src0_sel:DWORD
	v_or_b32_e32 v93, v93, v88
	v_or_b32_e32 v92, v92, v89
	v_pk_fma_f32 v[88:89], v[90:91], s[28:29], 0.5 op_sel_hi:[1,0,0]
	v_lshl_add_u64 v[90:91], v[96:97], 0, v[136:137]
	v_cvt_u32_f32_sdwa v88, v88 dst_sel:BYTE_3 dst_unused:UNUSED_PAD src0_sel:DWORD
	v_cvt_u32_f32_sdwa v89, v89 dst_sel:BYTE_3 dst_unused:UNUSED_PAD src0_sel:DWORD
	v_or_b32_e32 v88, v93, v88
	v_or_b32_e32 v89, v92, v89
	global_store_dwordx2 v[90:91], v[88:89], off nt

.LBB0_351:
	v_pk_add_f32 v[80:81], v[80:81], v[178:179]
	v_pk_add_f32 v[84:85], v[84:85], v[174:175]
	v_pk_add_f32 v[82:83], v[82:83], v[180:181]
	v_mul_f32_e32 v84, 0xbfb8aa3b, v84
	v_exp_f32_e32 v84, v84
	v_mul_f32_e32 v85, 0xbfb8aa3b, v85
	v_exp_f32_e32 v85, v85
	v_pk_add_f32 v[86:87], v[86:87], v[176:177]
	v_add_f32_e32 v84, 1.0, v84
	v_add_f32_e32 v85, 1.0, v85
	v_mul_f32_e32 v86, 0xbfb8aa3b, v86
	v_exp_f32_e32 v86, v86
	v_rcp_f32_e32 v84, v84
	v_add_f32_e32 v86, 1.0, v86
	v_mul_f32_e32 v87, 0xbfb8aa3b, v87
	v_exp_f32_e32 v87, v87
	v_rcp_f32_e32 v85, v85
	v_add_f32_e32 v87, 1.0, v87
	v_mul_f32_e32 v80, 0xbfb8aa3b, v80
	v_exp_f32_e32 v80, v80
	v_rcp_f32_e32 v86, v86
	v_add_f32_e32 v80, 1.0, v80
	v_mul_f32_e32 v84, 0xbf60028a, v84
	v_mul_f32_e32 v85, 0xbf60028a, v85
	v_rcp_f32_e32 v87, v87
	v_mul_f32_e32 v86, 0xbf60028a, v86
	v_mul_f32_e32 v87, 0xbf60028a, v87
	v_rcp_f32_e32 v80, v80
	s_nop 0
	v_mul_f32_e32 v90, 0xbf60028a, v80
	v_mul_f32_e32 v80, 0xbfb8aa3b, v81
	v_exp_f32_e32 v80, v80
	s_nop 0
	v_add_f32_e32 v80, 1.0, v80
	v_rcp_f32_e32 v80, v80
	s_nop 0
	v_mul_f32_e32 v91, 0xbf60028a, v80
	v_mul_f32_e32 v80, 0xbfb8aa3b, v82
	v_exp_f32_e32 v80, v80
	s_nop 0
	v_add_f32_e32 v80, 1.0, v80
	v_rcp_f32_e32 v80, v80
	s_nop 0
	v_mul_f32_e32 v92, 0xbf60028a, v80
	v_mul_f32_e32 v80, 0xbfb8aa3b, v83
	v_exp_f32_e32 v80, v80
	s_nop 0
	v_add_f32_e32 v80, 1.0, v80
	v_rcp_f32_e32 v80, v80
	s_nop 0
	v_mul_f32_e32 v83, 0xbf60028a, v80
	v_lshl_add_u64 v[88:89], v[142:143], 1, v[98:99]
	v_cvt_pk_bf16_f32 v80, v84, v85
	v_cvt_pk_bf16_f32 v81, v86, v87
	v_cvt_pk_bf16_f32 v82, v90, v91
	v_cvt_pk_bf16_f32 v83, v92, v83
	global_store_dwordx4 v[88:89], v[80:83], off offset:256 nt
.LBB0_352:
	s_or_b64 exec, exec, s[96:97]
	s_nop 0
	v_or_b32_e32 v82, 48, v144
	v_ashrrev_i32_e32 v83, 31, v82
	v_lshlrev_b64 v[80:81], 10, v[82:83]
	v_lshl_add_u64 v[80:81], s[80:81], 0, v[80:81]
	s_and_saveexec_b64 s[0:1], s[8:9]
	s_xor_b64 s[96:97], exec, s[0:1]
	s_cbranch_execz .LBB0_354
	v_pk_add_f32 v[72:73], v[72:73], v[170:171]
	v_pk_add_f32 v[76:77], v[76:77], v[166:167]
	v_pk_add_f32 v[86:87], v[74:75], v[172:173]
	v_mul_f32_e32 v74, 0xbfb8aa3b, v76
	v_mul_f32_e32 v72, 0xbfb8aa3b, v72
	v_exp_f32_e32 v76, v74
	v_mul_f32_e32 v74, 0xbfb8aa3b, v77
	v_exp_f32_e32 v77, v72
	v_pk_add_f32 v[78:79], v[78:79], v[168:169]
	v_mul_f32_e32 v72, 0xbfb8aa3b, v73
	v_exp_f32_e32 v84, v74
	v_mul_f32_e32 v74, 0xbfb8aa3b, v78
	v_exp_f32_e32 v85, v72
	v_mul_f32_e32 v72, 0xbfb8aa3b, v86
	v_exp_f32_e32 v78, v74
	v_mul_f32_e32 v74, 0xbfb8aa3b, v79
	v_exp_f32_e32 v79, v72
	v_mul_f32_e32 v72, 0xbfb8aa3b, v87
	v_exp_f32_e32 v75, v72
	v_pk_add_f32 v[72:73], v[76:77], 1.0 op_sel_hi:[1,0]
	v_pk_add_f32 v[78:79], v[78:79], 1.0 op_sel_hi:[1,0]
	v_exp_f32_e32 v74, v74
	v_rcp_f32_e32 v73, v73
	v_pk_add_f32 v[74:75], v[74:75], 1.0 op_sel_hi:[1,0]
	v_rcp_f32_e32 v72, v72
	v_pk_add_f32 v[76:77], v[84:85], 1.0 op_sel_hi:[1,0]
	v_pk_fma_f32 v[72:73], v[72:73], s[28:29], 0.5 op_sel_hi:[1,0,0]
	v_rcp_f32_e32 v77, v77
	v_rcp_f32_e32 v76, v76
	v_rcp_f32_e32 v79, v79
	v_rcp_f32_e32 v78, v78
	v_rcp_f32_e32 v75, v75
	v_rcp_f32_e32 v74, v74
	v_cvt_u32_f32_e32 v84, v73
	v_cvt_u32_f32_e32 v85, v72
	v_pk_fma_f32 v[72:73], v[76:77], s[28:29], 0.5 op_sel_hi:[1,0,0]
	s_nop 0
	v_cvt_u32_f32_e32 v72, v72
	v_cvt_u32_f32_e32 v73, v73
	v_lshlrev_b32_e32 v72, 8, v72
	v_lshlrev_b32_e32 v73, 8, v73
	v_or_b32_e32 v76, v73, v84
	v_or_b32_e32 v77, v72, v85
	v_pk_fma_f32 v[72:73], v[78:79], s[28:29], 0.5 op_sel_hi:[1,0,0]
	s_nop 0
	v_cvt_u32_f32_sdwa v72, v72 dst_sel:WORD_1 dst_unused:UNUSED_PAD src0_sel:DWORD
	v_cvt_u32_f32_sdwa v73, v73 dst_sel:WORD_1 dst_unused:UNUSED_PAD src0_sel:DWORD
	v_or_b32_e32 v77, v77, v72
	v_or_b32_e32 v76, v76, v73
	v_pk_fma_f32 v[72:73], v[74:75], s[28:29], 0.5 op_sel_hi:[1,0,0]
	v_lshl_add_u64 v[74:75], v[80:81], 0, v[136:137]
	v_cvt_u32_f32_sdwa v72, v72 dst_sel:BYTE_3 dst_unused:UNUSED_PAD src0_sel:DWORD
	v_cvt_u32_f32_sdwa v73, v73 dst_sel:BYTE_3 dst_unused:UNUSED_PAD src0_sel:DWORD
	v_or_b32_e32 v72, v77, v72
	v_or_b32_e32 v73, v76, v73
	global_store_dwordx2 v[74:75], v[72:73], off nt

.LBB0_357:
	v_pk_add_f32 v[64:65], v[64:65], v[178:179]
	v_pk_add_f32 v[68:69], v[68:69], v[174:175]
	v_pk_add_f32 v[66:67], v[66:67], v[180:181]
	v_mul_f32_e32 v68, 0xbfb8aa3b, v68
	v_exp_f32_e32 v68, v68
	v_mul_f32_e32 v69, 0xbfb8aa3b, v69
	v_exp_f32_e32 v69, v69
	v_pk_add_f32 v[70:71], v[70:71], v[176:177]
	v_add_f32_e32 v68, 1.0, v68
	v_add_f32_e32 v69, 1.0, v69
	v_mul_f32_e32 v70, 0xbfb8aa3b, v70
	v_exp_f32_e32 v70, v70
	v_rcp_f32_e32 v68, v68
	v_add_f32_e32 v70, 1.0, v70
	v_mul_f32_e32 v71, 0xbfb8aa3b, v71
	v_exp_f32_e32 v71, v71
	v_rcp_f32_e32 v69, v69
	v_add_f32_e32 v71, 1.0, v71
	v_mul_f32_e32 v64, 0xbfb8aa3b, v64
	v_exp_f32_e32 v64, v64
	v_rcp_f32_e32 v70, v70
	v_add_f32_e32 v64, 1.0, v64
	v_mul_f32_e32 v68, 0xbf60028a, v68
	v_mul_f32_e32 v69, 0xbf60028a, v69
	v_rcp_f32_e32 v71, v71
	v_mul_f32_e32 v70, 0xbf60028a, v70
	v_mul_f32_e32 v71, 0xbf60028a, v71
	v_rcp_f32_e32 v64, v64
	s_nop 0
	v_mul_f32_e32 v74, 0xbf60028a, v64
	v_mul_f32_e32 v64, 0xbfb8aa3b, v65
	v_exp_f32_e32 v64, v64
	s_nop 0
	v_add_f32_e32 v64, 1.0, v64
	v_rcp_f32_e32 v64, v64
	s_nop 0
	v_mul_f32_e32 v75, 0xbf60028a, v64
	v_mul_f32_e32 v64, 0xbfb8aa3b, v66
	v_exp_f32_e32 v64, v64
	s_nop 0
	v_add_f32_e32 v64, 1.0, v64
	v_rcp_f32_e32 v64, v64
	s_nop 0
	v_mul_f32_e32 v76, 0xbf60028a, v64
	v_mul_f32_e32 v64, 0xbfb8aa3b, v67
	v_exp_f32_e32 v64, v64
	s_nop 0
	v_add_f32_e32 v64, 1.0, v64
	v_rcp_f32_e32 v64, v64
	s_nop 0
	v_mul_f32_e32 v67, 0xbf60028a, v64
	v_lshl_add_u64 v[72:73], v[142:143], 1, v[82:83]
	v_cvt_pk_bf16_f32 v64, v68, v69
	v_cvt_pk_bf16_f32 v65, v70, v71
	v_cvt_pk_bf16_f32 v66, v74, v75
	v_cvt_pk_bf16_f32 v67, v76, v67
	global_store_dwordx4 v[72:73], v[64:67], off offset:256 nt
.LBB0_358:
	s_or_b64 exec, exec, s[96:97]
	s_nop 0
	v_add_u32_e32 v66, 0x80, v144
	v_ashrrev_i32_e32 v67, 31, v66
	v_lshlrev_b64 v[64:65], 10, v[66:67]
	v_lshl_add_u64 v[64:65], s[80:81], 0, v[64:65]
	s_and_saveexec_b64 s[0:1], s[8:9]
	s_xor_b64 s[96:97], exec, s[0:1]
	s_cbranch_execz .LBB0_360
	v_pk_add_f32 v[56:57], v[56:57], v[170:171]
	v_pk_add_f32 v[60:61], v[60:61], v[166:167]
	v_pk_add_f32 v[70:71], v[58:59], v[172:173]
	v_mul_f32_e32 v58, 0xbfb8aa3b, v60
	v_mul_f32_e32 v56, 0xbfb8aa3b, v56
	v_exp_f32_e32 v60, v58
	v_mul_f32_e32 v58, 0xbfb8aa3b, v61
	v_exp_f32_e32 v61, v56
	v_pk_add_f32 v[62:63], v[62:63], v[168:169]
	v_mul_f32_e32 v56, 0xbfb8aa3b, v57
	v_exp_f32_e32 v68, v58
	v_mul_f32_e32 v58, 0xbfb8aa3b, v62
	v_exp_f32_e32 v69, v56
	v_mul_f32_e32 v56, 0xbfb8aa3b, v70
	v_exp_f32_e32 v62, v58
	v_mul_f32_e32 v58, 0xbfb8aa3b, v63
	v_exp_f32_e32 v63, v56
	v_mul_f32_e32 v56, 0xbfb8aa3b, v71
	v_exp_f32_e32 v59, v56
	v_pk_add_f32 v[56:57], v[60:61], 1.0 op_sel_hi:[1,0]
	v_pk_add_f32 v[62:63], v[62:63], 1.0 op_sel_hi:[1,0]
	v_exp_f32_e32 v58, v58
	v_rcp_f32_e32 v57, v57
	v_pk_add_f32 v[58:59], v[58:59], 1.0 op_sel_hi:[1,0]
	v_rcp_f32_e32 v56, v56
	v_pk_add_f32 v[60:61], v[68:69], 1.0 op_sel_hi:[1,0]
	v_pk_fma_f32 v[56:57], v[56:57], s[28:29], 0.5 op_sel_hi:[1,0,0]
	v_rcp_f32_e32 v61, v61
	v_rcp_f32_e32 v60, v60
	v_rcp_f32_e32 v63, v63
	v_rcp_f32_e32 v62, v62
	v_rcp_f32_e32 v59, v59
	v_rcp_f32_e32 v58, v58
	v_cvt_u32_f32_e32 v68, v57
	v_cvt_u32_f32_e32 v69, v56
	v_pk_fma_f32 v[56:57], v[60:61], s[28:29], 0.5 op_sel_hi:[1,0,0]
	s_nop 0
	v_cvt_u32_f32_e32 v56, v56
	v_cvt_u32_f32_e32 v57, v57
	v_lshlrev_b32_e32 v56, 8, v56
	v_lshlrev_b32_e32 v57, 8, v57
	v_or_b32_e32 v60, v57, v68
	v_or_b32_e32 v61, v56, v69
	v_pk_fma_f32 v[56:57], v[62:63], s[28:29], 0.5 op_sel_hi:[1,0,0]
	s_nop 0
	v_cvt_u32_f32_sdwa v56, v56 dst_sel:WORD_1 dst_unused:UNUSED_PAD src0_sel:DWORD
	v_cvt_u32_f32_sdwa v57, v57 dst_sel:WORD_1 dst_unused:UNUSED_PAD src0_sel:DWORD
	v_or_b32_e32 v61, v61, v56
	v_or_b32_e32 v60, v60, v57
	v_pk_fma_f32 v[56:57], v[58:59], s[28:29], 0.5 op_sel_hi:[1,0,0]
	v_lshl_add_u64 v[58:59], v[64:65], 0, v[136:137]
	v_cvt_u32_f32_sdwa v56, v56 dst_sel:BYTE_3 dst_unused:UNUSED_PAD src0_sel:DWORD
	v_cvt_u32_f32_sdwa v57, v57 dst_sel:BYTE_3 dst_unused:UNUSED_PAD src0_sel:DWORD
	v_or_b32_e32 v56, v61, v56
	v_or_b32_e32 v57, v60, v57
	global_store_dwordx2 v[58:59], v[56:57], off nt

.LBB0_363:
	v_pk_add_f32 v[48:49], v[48:49], v[178:179]
	v_pk_add_f32 v[52:53], v[52:53], v[174:175]
	v_pk_add_f32 v[50:51], v[50:51], v[180:181]
	v_mul_f32_e32 v52, 0xbfb8aa3b, v52
	v_exp_f32_e32 v52, v52
	v_mul_f32_e32 v53, 0xbfb8aa3b, v53
	v_exp_f32_e32 v53, v53
	v_pk_add_f32 v[54:55], v[54:55], v[176:177]
	v_add_f32_e32 v52, 1.0, v52
	v_add_f32_e32 v53, 1.0, v53
	v_mul_f32_e32 v54, 0xbfb8aa3b, v54
	v_exp_f32_e32 v54, v54
	v_rcp_f32_e32 v52, v52
	v_add_f32_e32 v54, 1.0, v54
	v_mul_f32_e32 v55, 0xbfb8aa3b, v55
	v_exp_f32_e32 v55, v55
	v_rcp_f32_e32 v53, v53
	v_add_f32_e32 v55, 1.0, v55
	v_mul_f32_e32 v48, 0xbfb8aa3b, v48
	v_exp_f32_e32 v48, v48
	v_rcp_f32_e32 v54, v54
	v_add_f32_e32 v48, 1.0, v48
	v_mul_f32_e32 v52, 0xbf60028a, v52
	v_mul_f32_e32 v53, 0xbf60028a, v53
	v_rcp_f32_e32 v55, v55
	v_mul_f32_e32 v54, 0xbf60028a, v54
	v_mul_f32_e32 v55, 0xbf60028a, v55
	v_rcp_f32_e32 v48, v48
	s_nop 0
	v_mul_f32_e32 v58, 0xbf60028a, v48
	v_mul_f32_e32 v48, 0xbfb8aa3b, v49
	v_exp_f32_e32 v48, v48
	s_nop 0
	v_add_f32_e32 v48, 1.0, v48
	v_rcp_f32_e32 v48, v48
	s_nop 0
	v_mul_f32_e32 v59, 0xbf60028a, v48
	v_mul_f32_e32 v48, 0xbfb8aa3b, v50
	v_exp_f32_e32 v48, v48
	s_nop 0
	v_add_f32_e32 v48, 1.0, v48
	v_rcp_f32_e32 v48, v48
	s_nop 0
	v_mul_f32_e32 v60, 0xbf60028a, v48
	v_mul_f32_e32 v48, 0xbfb8aa3b, v51
	v_exp_f32_e32 v48, v48
	s_nop 0
	v_add_f32_e32 v48, 1.0, v48
	v_rcp_f32_e32 v48, v48
	s_nop 0
	v_mul_f32_e32 v51, 0xbf60028a, v48
	v_lshl_add_u64 v[56:57], v[142:143], 1, v[66:67]
	v_cvt_pk_bf16_f32 v48, v52, v53
	v_cvt_pk_bf16_f32 v49, v54, v55
	v_cvt_pk_bf16_f32 v50, v58, v59
	v_cvt_pk_bf16_f32 v51, v60, v51
	global_store_dwordx4 v[56:57], v[48:51], off offset:256 nt
.LBB0_364:
	s_or_b64 exec, exec, s[96:97]
	s_nop 0
	v_add_u32_e32 v50, 0x90, v144
	v_ashrrev_i32_e32 v51, 31, v50
	v_lshlrev_b64 v[48:49], 10, v[50:51]
	v_lshl_add_u64 v[48:49], s[80:81], 0, v[48:49]
	s_and_saveexec_b64 s[0:1], s[8:9]
	s_xor_b64 s[96:97], exec, s[0:1]
	s_cbranch_execz .LBB0_366
	v_pk_add_f32 v[40:41], v[40:41], v[170:171]
	v_pk_add_f32 v[44:45], v[44:45], v[166:167]
	v_pk_add_f32 v[54:55], v[42:43], v[172:173]
	v_mul_f32_e32 v42, 0xbfb8aa3b, v44
	v_mul_f32_e32 v40, 0xbfb8aa3b, v40
	v_exp_f32_e32 v44, v42
	v_mul_f32_e32 v42, 0xbfb8aa3b, v45
	v_exp_f32_e32 v45, v40
	v_pk_add_f32 v[46:47], v[46:47], v[168:169]
	v_mul_f32_e32 v40, 0xbfb8aa3b, v41
	v_exp_f32_e32 v52, v42
	v_mul_f32_e32 v42, 0xbfb8aa3b, v46
	v_exp_f32_e32 v53, v40
	v_mul_f32_e32 v40, 0xbfb8aa3b, v54
	v_exp_f32_e32 v46, v42
	v_mul_f32_e32 v42, 0xbfb8aa3b, v47
	v_exp_f32_e32 v47, v40
	v_mul_f32_e32 v40, 0xbfb8aa3b, v55
	v_exp_f32_e32 v43, v40
	v_pk_add_f32 v[40:41], v[44:45], 1.0 op_sel_hi:[1,0]
	v_pk_add_f32 v[46:47], v[46:47], 1.0 op_sel_hi:[1,0]
	v_exp_f32_e32 v42, v42
	v_rcp_f32_e32 v41, v41
	v_pk_add_f32 v[42:43], v[42:43], 1.0 op_sel_hi:[1,0]
	v_rcp_f32_e32 v40, v40
	v_pk_add_f32 v[44:45], v[52:53], 1.0 op_sel_hi:[1,0]
	v_pk_fma_f32 v[40:41], v[40:41], s[28:29], 0.5 op_sel_hi:[1,0,0]
	v_rcp_f32_e32 v45, v45
	v_rcp_f32_e32 v44, v44
	v_rcp_f32_e32 v47, v47
	v_rcp_f32_e32 v46, v46
	v_rcp_f32_e32 v43, v43
	v_rcp_f32_e32 v42, v42
	v_cvt_u32_f32_e32 v52, v41
	v_cvt_u32_f32_e32 v53, v40
	v_pk_fma_f32 v[40:41], v[44:45], s[28:29], 0.5 op_sel_hi:[1,0,0]
	s_nop 0
	v_cvt_u32_f32_e32 v40, v40
	v_cvt_u32_f32_e32 v41, v41
	v_lshlrev_b32_e32 v40, 8, v40
	v_lshlrev_b32_e32 v41, 8, v41
	v_or_b32_e32 v44, v41, v52
	v_or_b32_e32 v45, v40, v53
	v_pk_fma_f32 v[40:41], v[46:47], s[28:29], 0.5 op_sel_hi:[1,0,0]
	s_nop 0
	v_cvt_u32_f32_sdwa v40, v40 dst_sel:WORD_1 dst_unused:UNUSED_PAD src0_sel:DWORD
	v_cvt_u32_f32_sdwa v41, v41 dst_sel:WORD_1 dst_unused:UNUSED_PAD src0_sel:DWORD
	v_or_b32_e32 v45, v45, v40
	v_or_b32_e32 v44, v44, v41
	v_pk_fma_f32 v[40:41], v[42:43], s[28:29], 0.5 op_sel_hi:[1,0,0]
	v_lshl_add_u64 v[42:43], v[48:49], 0, v[136:137]
	v_cvt_u32_f32_sdwa v40, v40 dst_sel:BYTE_3 dst_unused:UNUSED_PAD src0_sel:DWORD
	v_cvt_u32_f32_sdwa v41, v41 dst_sel:BYTE_3 dst_unused:UNUSED_PAD src0_sel:DWORD
	v_or_b32_e32 v40, v45, v40
	v_or_b32_e32 v41, v44, v41
	global_store_dwordx2 v[42:43], v[40:41], off nt

.LBB0_369:
	v_pk_add_f32 v[32:33], v[32:33], v[178:179]
	v_pk_add_f32 v[36:37], v[36:37], v[174:175]
	v_pk_add_f32 v[34:35], v[34:35], v[180:181]
	v_mul_f32_e32 v36, 0xbfb8aa3b, v36
	v_exp_f32_e32 v36, v36
	v_mul_f32_e32 v37, 0xbfb8aa3b, v37
	v_exp_f32_e32 v37, v37
	v_pk_add_f32 v[38:39], v[38:39], v[176:177]
	v_add_f32_e32 v36, 1.0, v36
	v_add_f32_e32 v37, 1.0, v37
	v_mul_f32_e32 v38, 0xbfb8aa3b, v38
	v_exp_f32_e32 v38, v38
	v_rcp_f32_e32 v36, v36
	v_add_f32_e32 v38, 1.0, v38
	v_mul_f32_e32 v39, 0xbfb8aa3b, v39
	v_exp_f32_e32 v39, v39
	v_rcp_f32_e32 v37, v37
	v_add_f32_e32 v39, 1.0, v39
	v_mul_f32_e32 v32, 0xbfb8aa3b, v32
	v_exp_f32_e32 v32, v32
	v_rcp_f32_e32 v38, v38
	v_add_f32_e32 v32, 1.0, v32
	v_mul_f32_e32 v36, 0xbf60028a, v36
	v_mul_f32_e32 v37, 0xbf60028a, v37
	v_rcp_f32_e32 v39, v39
	v_mul_f32_e32 v38, 0xbf60028a, v38
	v_mul_f32_e32 v39, 0xbf60028a, v39
	v_rcp_f32_e32 v32, v32
	s_nop 0
	v_mul_f32_e32 v42, 0xbf60028a, v32
	v_mul_f32_e32 v32, 0xbfb8aa3b, v33
	v_exp_f32_e32 v32, v32
	s_nop 0
	v_add_f32_e32 v32, 1.0, v32
	v_rcp_f32_e32 v32, v32
	s_nop 0
	v_mul_f32_e32 v43, 0xbf60028a, v32
	v_mul_f32_e32 v32, 0xbfb8aa3b, v34
	v_exp_f32_e32 v32, v32
	s_nop 0
	v_add_f32_e32 v32, 1.0, v32
	v_rcp_f32_e32 v32, v32
	s_nop 0
	v_mul_f32_e32 v44, 0xbf60028a, v32
	v_mul_f32_e32 v32, 0xbfb8aa3b, v35
	v_exp_f32_e32 v32, v32
	s_nop 0
	v_add_f32_e32 v32, 1.0, v32
	v_rcp_f32_e32 v32, v32
	s_nop 0
	v_mul_f32_e32 v35, 0xbf60028a, v32
	v_lshl_add_u64 v[40:41], v[142:143], 1, v[50:51]
	v_cvt_pk_bf16_f32 v32, v36, v37
	v_cvt_pk_bf16_f32 v33, v38, v39
	v_cvt_pk_bf16_f32 v34, v42, v43
	v_cvt_pk_bf16_f32 v35, v44, v35
	global_store_dwordx4 v[40:41], v[32:35], off offset:256 nt
.LBB0_370:
	s_or_b64 exec, exec, s[96:97]
	s_nop 0
	v_add_u32_e32 v34, 0xa0, v144
	v_ashrrev_i32_e32 v35, 31, v34
	v_lshlrev_b64 v[32:33], 10, v[34:35]
	v_lshl_add_u64 v[32:33], s[80:81], 0, v[32:33]
	s_and_saveexec_b64 s[0:1], s[8:9]
	s_xor_b64 s[96:97], exec, s[0:1]
	s_cbranch_execz .LBB0_372
	v_pk_add_f32 v[24:25], v[24:25], v[170:171]
	v_pk_add_f32 v[28:29], v[28:29], v[166:167]
	v_pk_add_f32 v[38:39], v[26:27], v[172:173]
	v_mul_f32_e32 v26, 0xbfb8aa3b, v28
	v_mul_f32_e32 v24, 0xbfb8aa3b, v24
	v_exp_f32_e32 v28, v26
	v_mul_f32_e32 v26, 0xbfb8aa3b, v29
	v_exp_f32_e32 v29, v24
	v_pk_add_f32 v[30:31], v[30:31], v[168:169]
	v_mul_f32_e32 v24, 0xbfb8aa3b, v25
	v_exp_f32_e32 v36, v26
	v_mul_f32_e32 v26, 0xbfb8aa3b, v30
	v_exp_f32_e32 v37, v24
	v_mul_f32_e32 v24, 0xbfb8aa3b, v38
	v_exp_f32_e32 v30, v26
	v_mul_f32_e32 v26, 0xbfb8aa3b, v31
	v_exp_f32_e32 v31, v24
	v_mul_f32_e32 v24, 0xbfb8aa3b, v39
	v_exp_f32_e32 v27, v24
	v_pk_add_f32 v[24:25], v[28:29], 1.0 op_sel_hi:[1,0]
	v_pk_add_f32 v[30:31], v[30:31], 1.0 op_sel_hi:[1,0]
	v_exp_f32_e32 v26, v26
	v_rcp_f32_e32 v25, v25
	v_pk_add_f32 v[26:27], v[26:27], 1.0 op_sel_hi:[1,0]
	v_rcp_f32_e32 v24, v24
	v_pk_add_f32 v[28:29], v[36:37], 1.0 op_sel_hi:[1,0]
	v_pk_fma_f32 v[24:25], v[24:25], s[28:29], 0.5 op_sel_hi:[1,0,0]
	v_rcp_f32_e32 v29, v29
	v_rcp_f32_e32 v28, v28
	v_rcp_f32_e32 v31, v31
	v_rcp_f32_e32 v30, v30
	v_rcp_f32_e32 v27, v27
	v_rcp_f32_e32 v26, v26
	v_cvt_u32_f32_e32 v36, v25
	v_cvt_u32_f32_e32 v37, v24
	v_pk_fma_f32 v[24:25], v[28:29], s[28:29], 0.5 op_sel_hi:[1,0,0]
	s_nop 0
	v_cvt_u32_f32_e32 v24, v24
	v_cvt_u32_f32_e32 v25, v25
	v_lshlrev_b32_e32 v24, 8, v24
	v_lshlrev_b32_e32 v25, 8, v25
	v_or_b32_e32 v28, v25, v36
	v_or_b32_e32 v29, v24, v37
	v_pk_fma_f32 v[24:25], v[30:31], s[28:29], 0.5 op_sel_hi:[1,0,0]
	s_nop 0
	v_cvt_u32_f32_sdwa v24, v24 dst_sel:WORD_1 dst_unused:UNUSED_PAD src0_sel:DWORD
	v_cvt_u32_f32_sdwa v25, v25 dst_sel:WORD_1 dst_unused:UNUSED_PAD src0_sel:DWORD
	v_or_b32_e32 v29, v29, v24
	v_or_b32_e32 v28, v28, v25
	v_pk_fma_f32 v[24:25], v[26:27], s[28:29], 0.5 op_sel_hi:[1,0,0]
	v_lshl_add_u64 v[26:27], v[32:33], 0, v[136:137]
	v_cvt_u32_f32_sdwa v24, v24 dst_sel:BYTE_3 dst_unused:UNUSED_PAD src0_sel:DWORD
	v_cvt_u32_f32_sdwa v25, v25 dst_sel:BYTE_3 dst_unused:UNUSED_PAD src0_sel:DWORD
	v_or_b32_e32 v24, v29, v24
	v_or_b32_e32 v25, v28, v25
	global_store_dwordx2 v[26:27], v[24:25], off nt

.LBB0_375:
	v_pk_add_f32 v[16:17], v[16:17], v[178:179]
	v_pk_add_f32 v[20:21], v[20:21], v[174:175]
	v_pk_add_f32 v[18:19], v[18:19], v[180:181]
	v_mul_f32_e32 v20, 0xbfb8aa3b, v20
	v_exp_f32_e32 v20, v20
	v_mul_f32_e32 v21, 0xbfb8aa3b, v21
	v_exp_f32_e32 v21, v21
	v_pk_add_f32 v[22:23], v[22:23], v[176:177]
	v_add_f32_e32 v20, 1.0, v20
	v_add_f32_e32 v21, 1.0, v21
	v_mul_f32_e32 v22, 0xbfb8aa3b, v22
	v_exp_f32_e32 v22, v22
	v_rcp_f32_e32 v20, v20
	v_add_f32_e32 v22, 1.0, v22
	v_mul_f32_e32 v23, 0xbfb8aa3b, v23
	v_exp_f32_e32 v23, v23
	v_rcp_f32_e32 v21, v21
	v_add_f32_e32 v23, 1.0, v23
	v_mul_f32_e32 v16, 0xbfb8aa3b, v16
	v_exp_f32_e32 v16, v16
	v_rcp_f32_e32 v22, v22
	v_add_f32_e32 v16, 1.0, v16
	v_mul_f32_e32 v20, 0xbf60028a, v20
	v_mul_f32_e32 v21, 0xbf60028a, v21
	v_rcp_f32_e32 v23, v23
	v_mul_f32_e32 v22, 0xbf60028a, v22
	v_mul_f32_e32 v23, 0xbf60028a, v23
	v_rcp_f32_e32 v16, v16
	s_nop 0
	v_mul_f32_e32 v26, 0xbf60028a, v16
	v_mul_f32_e32 v16, 0xbfb8aa3b, v17
	v_exp_f32_e32 v16, v16
	s_nop 0
	v_add_f32_e32 v16, 1.0, v16
	v_rcp_f32_e32 v16, v16
	s_nop 0
	v_mul_f32_e32 v27, 0xbf60028a, v16
	v_mul_f32_e32 v16, 0xbfb8aa3b, v18
	v_exp_f32_e32 v16, v16
	s_nop 0
	v_add_f32_e32 v16, 1.0, v16
	v_rcp_f32_e32 v16, v16
	s_nop 0
	v_mul_f32_e32 v28, 0xbf60028a, v16
	v_mul_f32_e32 v16, 0xbfb8aa3b, v19
	v_exp_f32_e32 v16, v16
	s_nop 0
	v_add_f32_e32 v16, 1.0, v16
	v_rcp_f32_e32 v16, v16
	s_nop 0
	v_mul_f32_e32 v19, 0xbf60028a, v16
	v_lshl_add_u64 v[24:25], v[142:143], 1, v[34:35]
	v_cvt_pk_bf16_f32 v16, v20, v21
	v_cvt_pk_bf16_f32 v17, v22, v23
	v_cvt_pk_bf16_f32 v18, v26, v27
	v_cvt_pk_bf16_f32 v19, v28, v19
	global_store_dwordx4 v[24:25], v[16:19], off offset:256 nt
.LBB0_376:
	s_or_b64 exec, exec, s[96:97]
	s_nop 0
	v_add_u32_e32 v18, 0xb0, v144
	v_ashrrev_i32_e32 v19, 31, v18
	v_lshlrev_b64 v[16:17], 10, v[18:19]
	v_lshl_add_u64 v[16:17], s[80:81], 0, v[16:17]
	s_and_saveexec_b64 s[0:1], s[8:9]
	s_xor_b64 s[8:9], exec, s[0:1]
	s_cbranch_execz .LBB0_378
	v_pk_add_f32 v[8:9], v[8:9], v[170:171]
	v_pk_add_f32 v[12:13], v[12:13], v[166:167]
	v_pk_add_f32 v[22:23], v[10:11], v[172:173]
	v_mul_f32_e32 v10, 0xbfb8aa3b, v12
	v_mul_f32_e32 v8, 0xbfb8aa3b, v8
	v_exp_f32_e32 v12, v10
	v_mul_f32_e32 v10, 0xbfb8aa3b, v13
	v_exp_f32_e32 v13, v8
	v_pk_add_f32 v[14:15], v[14:15], v[168:169]
	v_mul_f32_e32 v8, 0xbfb8aa3b, v9
	v_exp_f32_e32 v20, v10
	v_mul_f32_e32 v10, 0xbfb8aa3b, v14
	v_exp_f32_e32 v21, v8
	v_mul_f32_e32 v8, 0xbfb8aa3b, v22
	v_exp_f32_e32 v14, v10
	v_mul_f32_e32 v10, 0xbfb8aa3b, v15
	v_exp_f32_e32 v15, v8
	v_mul_f32_e32 v8, 0xbfb8aa3b, v23
	v_exp_f32_e32 v11, v8
	v_pk_add_f32 v[8:9], v[12:13], 1.0 op_sel_hi:[1,0]
	v_pk_add_f32 v[14:15], v[14:15], 1.0 op_sel_hi:[1,0]
	v_exp_f32_e32 v10, v10
	v_rcp_f32_e32 v9, v9
	v_pk_add_f32 v[10:11], v[10:11], 1.0 op_sel_hi:[1,0]
	v_rcp_f32_e32 v8, v8
	v_pk_add_f32 v[12:13], v[20:21], 1.0 op_sel_hi:[1,0]
	v_pk_fma_f32 v[8:9], v[8:9], s[28:29], 0.5 op_sel_hi:[1,0,0]
	v_rcp_f32_e32 v13, v13
	v_rcp_f32_e32 v12, v12
	v_rcp_f32_e32 v15, v15
	v_rcp_f32_e32 v14, v14
	v_rcp_f32_e32 v11, v11
	v_rcp_f32_e32 v10, v10
	v_cvt_u32_f32_e32 v20, v9
	v_cvt_u32_f32_e32 v21, v8
	v_pk_fma_f32 v[8:9], v[12:13], s[28:29], 0.5 op_sel_hi:[1,0,0]
	s_nop 0
	v_cvt_u32_f32_e32 v8, v8
	v_cvt_u32_f32_e32 v9, v9
	v_lshlrev_b32_e32 v8, 8, v8
	v_lshlrev_b32_e32 v9, 8, v9
	v_or_b32_e32 v12, v9, v20
	v_or_b32_e32 v13, v8, v21
	v_pk_fma_f32 v[8:9], v[14:15], s[28:29], 0.5 op_sel_hi:[1,0,0]
	s_nop 0
	v_cvt_u32_f32_sdwa v8, v8 dst_sel:WORD_1 dst_unused:UNUSED_PAD src0_sel:DWORD
	v_cvt_u32_f32_sdwa v9, v9 dst_sel:WORD_1 dst_unused:UNUSED_PAD src0_sel:DWORD
	v_or_b32_e32 v13, v13, v8
	v_or_b32_e32 v12, v12, v9
	v_pk_fma_f32 v[8:9], v[10:11], s[28:29], 0.5 op_sel_hi:[1,0,0]
	v_lshl_add_u64 v[10:11], v[16:17], 0, v[136:137]
	v_cvt_u32_f32_sdwa v8, v8 dst_sel:BYTE_3 dst_unused:UNUSED_PAD src0_sel:DWORD
	v_cvt_u32_f32_sdwa v9, v9 dst_sel:BYTE_3 dst_unused:UNUSED_PAD src0_sel:DWORD
	v_or_b32_e32 v8, v13, v8
	v_or_b32_e32 v9, v12, v9
	global_store_dwordx2 v[10:11], v[8:9], off nt

.LBB0_382:
	v_pk_add_f32 v[104:105], v[104:105], v[170:171]
	v_pk_add_f32 v[108:109], v[108:109], v[166:167]
	v_pk_add_f32 v[106:107], v[106:107], v[172:173]
	v_mul_f32_e32 v108, 0xbfb8aa3b, v108
	v_exp_f32_e32 v108, v108
	v_mul_f32_e32 v109, 0xbfb8aa3b, v109
	v_exp_f32_e32 v109, v109
	v_pk_add_f32 v[110:111], v[110:111], v[168:169]
	v_add_f32_e32 v108, 1.0, v108
	v_add_f32_e32 v109, 1.0, v109
	v_mul_f32_e32 v110, 0xbfb8aa3b, v110
	v_exp_f32_e32 v110, v110
	v_rcp_f32_e32 v108, v108
	v_add_f32_e32 v110, 1.0, v110
	v_mul_f32_e32 v111, 0xbfb8aa3b, v111
	v_exp_f32_e32 v111, v111
	v_rcp_f32_e32 v109, v109
	v_add_f32_e32 v111, 1.0, v111
	v_mul_f32_e32 v104, 0xbfb8aa3b, v104
	v_exp_f32_e32 v104, v104
	v_rcp_f32_e32 v110, v110
	v_add_f32_e32 v104, 1.0, v104
	v_mul_f32_e32 v108, 0xbf60028a, v108
	v_mul_f32_e32 v109, 0xbf60028a, v109
	v_rcp_f32_e32 v111, v111
	v_mul_f32_e32 v110, 0xbf60028a, v110
	v_mul_f32_e32 v111, 0xbf60028a, v111
	v_rcp_f32_e32 v104, v104
	s_nop 0
	v_mul_f32_e32 v118, 0xbf60028a, v104
	v_mul_f32_e32 v104, 0xbfb8aa3b, v105
	v_exp_f32_e32 v104, v104
	s_nop 0
	v_add_f32_e32 v104, 1.0, v104
	v_rcp_f32_e32 v104, v104
	s_nop 0
	v_mul_f32_e32 v119, 0xbf60028a, v104
	v_mul_f32_e32 v104, 0xbfb8aa3b, v106
	v_exp_f32_e32 v104, v104
	s_nop 0
	v_add_f32_e32 v104, 1.0, v104
	v_rcp_f32_e32 v104, v104
	s_nop 0
	v_mul_f32_e32 v121, 0xbf60028a, v104
	v_mul_f32_e32 v104, 0xbfb8aa3b, v107
	v_exp_f32_e32 v104, v104
	s_nop 0
	v_add_f32_e32 v104, 1.0, v104
	v_rcp_f32_e32 v104, v104
	s_nop 0
	v_mul_f32_e32 v107, 0xbf60028a, v104
	v_lshl_add_u64 v[116:117], v[142:143], 1, v[114:115]
	v_cvt_pk_bf16_f32 v104, v108, v109
	v_cvt_pk_bf16_f32 v105, v110, v111
	v_cvt_pk_bf16_f32 v106, v118, v119
	v_cvt_pk_bf16_f32 v107, v121, v107
	global_store_dwordx4 v[116:117], v[104:107], off nt
	s_or_b64 exec, exec, s[96:97]
	s_and_saveexec_b64 s[0:1], s[10:11]
	s_xor_b64 s[96:97], exec, s[0:1]
	s_cbranch_execz .LBB0_344
.LBB0_383:
	v_mov_b32_e32 v121, v137
	v_pk_add_f32 v[96:97], v[96:97], v[178:179]
	v_pk_add_f32 v[100:101], v[100:101], v[174:175]
	v_pk_add_f32 v[106:107], v[98:99], v[180:181]
	v_mul_f32_e32 v98, 0xbfb8aa3b, v100
	v_mul_f32_e32 v96, 0xbfb8aa3b, v96
	v_exp_f32_e32 v100, v98
	v_mul_f32_e32 v98, 0xbfb8aa3b, v101
	v_exp_f32_e32 v101, v96
	v_pk_add_f32 v[102:103], v[102:103], v[176:177]
	v_mul_f32_e32 v96, 0xbfb8aa3b, v97
	v_exp_f32_e32 v104, v98
	v_mul_f32_e32 v98, 0xbfb8aa3b, v102
	v_exp_f32_e32 v105, v96
	v_mul_f32_e32 v96, 0xbfb8aa3b, v106
	v_exp_f32_e32 v102, v98
	v_mul_f32_e32 v98, 0xbfb8aa3b, v103
	v_exp_f32_e32 v103, v96
	v_mul_f32_e32 v96, 0xbfb8aa3b, v107
	v_exp_f32_e32 v99, v96
	v_pk_add_f32 v[96:97], v[100:101], 1.0 op_sel_hi:[1,0]
	v_pk_add_f32 v[102:103], v[102:103], 1.0 op_sel_hi:[1,0]
	v_exp_f32_e32 v98, v98
	v_rcp_f32_e32 v97, v97
	v_pk_add_f32 v[98:99], v[98:99], 1.0 op_sel_hi:[1,0]
	v_rcp_f32_e32 v96, v96
	v_pk_add_f32 v[100:101], v[104:105], 1.0 op_sel_hi:[1,0]
	v_pk_fma_f32 v[96:97], v[96:97], s[28:29], 0.5 op_sel_hi:[1,0,0]
	v_rcp_f32_e32 v101, v101
	v_rcp_f32_e32 v100, v100
	v_rcp_f32_e32 v103, v103
	v_rcp_f32_e32 v102, v102
	v_rcp_f32_e32 v99, v99
	v_rcp_f32_e32 v98, v98
	v_cvt_u32_f32_e32 v104, v97
	v_cvt_u32_f32_e32 v105, v96
	v_pk_fma_f32 v[96:97], v[100:101], s[28:29], 0.5 op_sel_hi:[1,0,0]
	s_nop 0
	v_cvt_u32_f32_e32 v96, v96
	v_cvt_u32_f32_e32 v97, v97
	v_lshlrev_b32_e32 v96, 8, v96
	v_lshlrev_b32_e32 v97, 8, v97
	v_or_b32_e32 v100, v97, v104
	v_or_b32_e32 v101, v96, v105
	v_pk_fma_f32 v[96:97], v[102:103], s[28:29], 0.5 op_sel_hi:[1,0,0]
	s_nop 0
	v_cvt_u32_f32_sdwa v96, v96 dst_sel:WORD_1 dst_unused:UNUSED_PAD src0_sel:DWORD
	v_cvt_u32_f32_sdwa v97, v97 dst_sel:WORD_1 dst_unused:UNUSED_PAD src0_sel:DWORD
	v_or_b32_e32 v101, v101, v96
	v_or_b32_e32 v100, v100, v97
	v_pk_fma_f32 v[96:97], v[98:99], s[28:29], 0.5 op_sel_hi:[1,0,0]
	v_lshl_add_u64 v[98:99], v[112:113], 0, v[120:121]
	v_cvt_u32_f32_sdwa v96, v96 dst_sel:BYTE_3 dst_unused:UNUSED_PAD src0_sel:DWORD
	v_cvt_u32_f32_sdwa v97, v97 dst_sel:BYTE_3 dst_unused:UNUSED_PAD src0_sel:DWORD
	v_or_b32_e32 v96, v101, v96
	v_or_b32_e32 v97, v100, v97
	global_store_dwordx2 v[98:99], v[96:97], off nt
	s_andn2_saveexec_b64 s[96:97], s[96:97]
	s_cbranch_execnz .LBB0_345
	s_branch .LBB0_346
.LBB0_384:
	v_pk_add_f32 v[88:89], v[88:89], v[170:171]
	v_pk_add_f32 v[92:93], v[92:93], v[166:167]
	v_pk_add_f32 v[90:91], v[90:91], v[172:173]
	v_mul_f32_e32 v92, 0xbfb8aa3b, v92
	v_exp_f32_e32 v92, v92
	v_mul_f32_e32 v93, 0xbfb8aa3b, v93
	v_exp_f32_e32 v93, v93
	v_pk_add_f32 v[94:95], v[94:95], v[168:169]
	v_add_f32_e32 v92, 1.0, v92
	v_add_f32_e32 v93, 1.0, v93
	v_mul_f32_e32 v94, 0xbfb8aa3b, v94
	v_exp_f32_e32 v94, v94
	v_rcp_f32_e32 v92, v92
	v_add_f32_e32 v94, 1.0, v94
	v_mul_f32_e32 v95, 0xbfb8aa3b, v95
	v_exp_f32_e32 v95, v95
	v_rcp_f32_e32 v93, v93
	v_add_f32_e32 v95, 1.0, v95
	v_mul_f32_e32 v88, 0xbfb8aa3b, v88
	v_exp_f32_e32 v88, v88
	v_rcp_f32_e32 v94, v94
	v_add_f32_e32 v88, 1.0, v88
	v_mul_f32_e32 v92, 0xbf60028a, v92
	v_mul_f32_e32 v93, 0xbf60028a, v93
	v_rcp_f32_e32 v95, v95
	v_mul_f32_e32 v94, 0xbf60028a, v94
	v_mul_f32_e32 v95, 0xbf60028a, v95
	v_rcp_f32_e32 v88, v88
	s_nop 0
	v_mul_f32_e32 v102, 0xbf60028a, v88
	v_mul_f32_e32 v88, 0xbfb8aa3b, v89
	v_exp_f32_e32 v88, v88
	s_nop 0
	v_add_f32_e32 v88, 1.0, v88
	v_rcp_f32_e32 v88, v88
	s_nop 0
	v_mul_f32_e32 v103, 0xbf60028a, v88
	v_mul_f32_e32 v88, 0xbfb8aa3b, v90
	v_exp_f32_e32 v88, v88
	s_nop 0
	v_add_f32_e32 v88, 1.0, v88
	v_rcp_f32_e32 v88, v88
	s_nop 0
	v_mul_f32_e32 v104, 0xbf60028a, v88
	v_mul_f32_e32 v88, 0xbfb8aa3b, v91
	v_exp_f32_e32 v88, v88
	s_nop 0
	v_add_f32_e32 v88, 1.0, v88
	v_rcp_f32_e32 v88, v88
	s_nop 0
	v_mul_f32_e32 v91, 0xbf60028a, v88
	v_lshl_add_u64 v[100:101], v[142:143], 1, v[98:99]
	v_cvt_pk_bf16_f32 v88, v92, v93
	v_cvt_pk_bf16_f32 v89, v94, v95
	v_cvt_pk_bf16_f32 v90, v102, v103
	v_cvt_pk_bf16_f32 v91, v104, v91
	global_store_dwordx4 v[100:101], v[88:91], off nt
	s_or_b64 exec, exec, s[96:97]
	s_and_saveexec_b64 s[0:1], s[10:11]
	s_xor_b64 s[96:97], exec, s[0:1]
	s_cbranch_execz .LBB0_350
.LBB0_385:
	v_mov_b32_e32 v121, v137
	v_pk_add_f32 v[80:81], v[80:81], v[178:179]
	v_pk_add_f32 v[84:85], v[84:85], v[174:175]
	v_pk_add_f32 v[90:91], v[82:83], v[180:181]
	v_mul_f32_e32 v82, 0xbfb8aa3b, v84
	v_mul_f32_e32 v80, 0xbfb8aa3b, v80
	v_exp_f32_e32 v84, v82
	v_mul_f32_e32 v82, 0xbfb8aa3b, v85
	v_exp_f32_e32 v85, v80
	v_pk_add_f32 v[86:87], v[86:87], v[176:177]
	v_mul_f32_e32 v80, 0xbfb8aa3b, v81
	v_exp_f32_e32 v88, v82
	v_mul_f32_e32 v82, 0xbfb8aa3b, v86
	v_exp_f32_e32 v89, v80
	v_mul_f32_e32 v80, 0xbfb8aa3b, v90
	v_exp_f32_e32 v86, v82
	v_mul_f32_e32 v82, 0xbfb8aa3b, v87
	v_exp_f32_e32 v87, v80
	v_mul_f32_e32 v80, 0xbfb8aa3b, v91
	v_exp_f32_e32 v83, v80
	v_pk_add_f32 v[80:81], v[84:85], 1.0 op_sel_hi:[1,0]
	v_pk_add_f32 v[86:87], v[86:87], 1.0 op_sel_hi:[1,0]
	v_exp_f32_e32 v82, v82
	v_rcp_f32_e32 v81, v81
	v_pk_add_f32 v[82:83], v[82:83], 1.0 op_sel_hi:[1,0]
	v_rcp_f32_e32 v80, v80
	v_pk_add_f32 v[84:85], v[88:89], 1.0 op_sel_hi:[1,0]
	v_pk_fma_f32 v[80:81], v[80:81], s[28:29], 0.5 op_sel_hi:[1,0,0]
	v_rcp_f32_e32 v85, v85
	v_rcp_f32_e32 v84, v84
	v_rcp_f32_e32 v87, v87
	v_rcp_f32_e32 v86, v86
	v_rcp_f32_e32 v83, v83
	v_rcp_f32_e32 v82, v82
	v_cvt_u32_f32_e32 v88, v81
	v_cvt_u32_f32_e32 v89, v80
	v_pk_fma_f32 v[80:81], v[84:85], s[28:29], 0.5 op_sel_hi:[1,0,0]
	s_nop 0
	v_cvt_u32_f32_e32 v80, v80
	v_cvt_u32_f32_e32 v81, v81
	v_lshlrev_b32_e32 v80, 8, v80
	v_lshlrev_b32_e32 v81, 8, v81
	v_or_b32_e32 v84, v81, v88
	v_or_b32_e32 v85, v80, v89
	v_pk_fma_f32 v[80:81], v[86:87], s[28:29], 0.5 op_sel_hi:[1,0,0]
	s_nop 0
	v_cvt_u32_f32_sdwa v80, v80 dst_sel:WORD_1 dst_unused:UNUSED_PAD src0_sel:DWORD
	v_cvt_u32_f32_sdwa v81, v81 dst_sel:WORD_1 dst_unused:UNUSED_PAD src0_sel:DWORD
	v_or_b32_e32 v85, v85, v80
	v_or_b32_e32 v84, v84, v81
	v_pk_fma_f32 v[80:81], v[82:83], s[28:29], 0.5 op_sel_hi:[1,0,0]
	v_lshl_add_u64 v[82:83], v[96:97], 0, v[120:121]
	v_cvt_u32_f32_sdwa v80, v80 dst_sel:BYTE_3 dst_unused:UNUSED_PAD src0_sel:DWORD
	v_cvt_u32_f32_sdwa v81, v81 dst_sel:BYTE_3 dst_unused:UNUSED_PAD src0_sel:DWORD
	v_or_b32_e32 v80, v85, v80
	v_or_b32_e32 v81, v84, v81
	global_store_dwordx2 v[82:83], v[80:81], off nt
	s_andn2_saveexec_b64 s[96:97], s[96:97]
	s_cbranch_execnz .LBB0_351
	s_branch .LBB0_352
.LBB0_386:
	v_pk_add_f32 v[72:73], v[72:73], v[170:171]
	v_pk_add_f32 v[76:77], v[76:77], v[166:167]
	v_pk_add_f32 v[74:75], v[74:75], v[172:173]
	v_mul_f32_e32 v76, 0xbfb8aa3b, v76
	v_exp_f32_e32 v76, v76
	v_mul_f32_e32 v77, 0xbfb8aa3b, v77
	v_exp_f32_e32 v77, v77
	v_pk_add_f32 v[78:79], v[78:79], v[168:169]
	v_add_f32_e32 v76, 1.0, v76
	v_add_f32_e32 v77, 1.0, v77
	v_mul_f32_e32 v78, 0xbfb8aa3b, v78
	v_exp_f32_e32 v78, v78
	v_rcp_f32_e32 v76, v76
	v_add_f32_e32 v78, 1.0, v78
	v_mul_f32_e32 v79, 0xbfb8aa3b, v79
	v_exp_f32_e32 v79, v79
	v_rcp_f32_e32 v77, v77
	v_add_f32_e32 v79, 1.0, v79
	v_mul_f32_e32 v72, 0xbfb8aa3b, v72
	v_exp_f32_e32 v72, v72
	v_rcp_f32_e32 v78, v78
	v_add_f32_e32 v72, 1.0, v72
	v_mul_f32_e32 v76, 0xbf60028a, v76
	v_mul_f32_e32 v77, 0xbf60028a, v77
	v_rcp_f32_e32 v79, v79
	v_mul_f32_e32 v78, 0xbf60028a, v78
	v_mul_f32_e32 v79, 0xbf60028a, v79
	v_rcp_f32_e32 v72, v72
	s_nop 0
	v_mul_f32_e32 v86, 0xbf60028a, v72
	v_mul_f32_e32 v72, 0xbfb8aa3b, v73
	v_exp_f32_e32 v72, v72
	s_nop 0
	v_add_f32_e32 v72, 1.0, v72
	v_rcp_f32_e32 v72, v72
	s_nop 0
	v_mul_f32_e32 v87, 0xbf60028a, v72
	v_mul_f32_e32 v72, 0xbfb8aa3b, v74
	v_exp_f32_e32 v72, v72
	s_nop 0
	v_add_f32_e32 v72, 1.0, v72
	v_rcp_f32_e32 v72, v72
	s_nop 0
	v_mul_f32_e32 v88, 0xbf60028a, v72
	v_mul_f32_e32 v72, 0xbfb8aa3b, v75
	v_exp_f32_e32 v72, v72
	s_nop 0
	v_add_f32_e32 v72, 1.0, v72
	v_rcp_f32_e32 v72, v72
	s_nop 0
	v_mul_f32_e32 v75, 0xbf60028a, v72
	v_lshl_add_u64 v[84:85], v[142:143], 1, v[82:83]
	v_cvt_pk_bf16_f32 v72, v76, v77
	v_cvt_pk_bf16_f32 v73, v78, v79
	v_cvt_pk_bf16_f32 v74, v86, v87
	v_cvt_pk_bf16_f32 v75, v88, v75
	global_store_dwordx4 v[84:85], v[72:75], off nt
	s_or_b64 exec, exec, s[96:97]
	s_and_saveexec_b64 s[0:1], s[10:11]
	s_xor_b64 s[96:97], exec, s[0:1]
	s_cbranch_execz .LBB0_356
.LBB0_387:
	v_mov_b32_e32 v121, v137
	v_pk_add_f32 v[64:65], v[64:65], v[178:179]
	v_pk_add_f32 v[68:69], v[68:69], v[174:175]
	v_pk_add_f32 v[74:75], v[66:67], v[180:181]
	v_mul_f32_e32 v66, 0xbfb8aa3b, v68
	v_mul_f32_e32 v64, 0xbfb8aa3b, v64
	v_exp_f32_e32 v68, v66
	v_mul_f32_e32 v66, 0xbfb8aa3b, v69
	v_exp_f32_e32 v69, v64
	v_pk_add_f32 v[70:71], v[70:71], v[176:177]
	v_mul_f32_e32 v64, 0xbfb8aa3b, v65
	v_exp_f32_e32 v72, v66
	v_mul_f32_e32 v66, 0xbfb8aa3b, v70
	v_exp_f32_e32 v73, v64
	v_mul_f32_e32 v64, 0xbfb8aa3b, v74
	v_exp_f32_e32 v70, v66
	v_mul_f32_e32 v66, 0xbfb8aa3b, v71
	v_exp_f32_e32 v71, v64
	v_mul_f32_e32 v64, 0xbfb8aa3b, v75
	v_exp_f32_e32 v67, v64
	v_pk_add_f32 v[64:65], v[68:69], 1.0 op_sel_hi:[1,0]
	v_pk_add_f32 v[70:71], v[70:71], 1.0 op_sel_hi:[1,0]
	v_exp_f32_e32 v66, v66
	v_rcp_f32_e32 v65, v65
	v_pk_add_f32 v[66:67], v[66:67], 1.0 op_sel_hi:[1,0]
	v_rcp_f32_e32 v64, v64
	v_pk_add_f32 v[68:69], v[72:73], 1.0 op_sel_hi:[1,0]
	v_pk_fma_f32 v[64:65], v[64:65], s[28:29], 0.5 op_sel_hi:[1,0,0]
	v_rcp_f32_e32 v69, v69
	v_rcp_f32_e32 v68, v68
	v_rcp_f32_e32 v71, v71
	v_rcp_f32_e32 v70, v70
	v_rcp_f32_e32 v67, v67
	v_rcp_f32_e32 v66, v66
	v_cvt_u32_f32_e32 v72, v65
	v_cvt_u32_f32_e32 v73, v64
	v_pk_fma_f32 v[64:65], v[68:69], s[28:29], 0.5 op_sel_hi:[1,0,0]
	s_nop 0
	v_cvt_u32_f32_e32 v64, v64
	v_cvt_u32_f32_e32 v65, v65
	v_lshlrev_b32_e32 v64, 8, v64
	v_lshlrev_b32_e32 v65, 8, v65
	v_or_b32_e32 v68, v65, v72
	v_or_b32_e32 v69, v64, v73
	v_pk_fma_f32 v[64:65], v[70:71], s[28:29], 0.5 op_sel_hi:[1,0,0]
	s_nop 0
	v_cvt_u32_f32_sdwa v64, v64 dst_sel:WORD_1 dst_unused:UNUSED_PAD src0_sel:DWORD
	v_cvt_u32_f32_sdwa v65, v65 dst_sel:WORD_1 dst_unused:UNUSED_PAD src0_sel:DWORD
	v_or_b32_e32 v69, v69, v64
	v_or_b32_e32 v68, v68, v65
	v_pk_fma_f32 v[64:65], v[66:67], s[28:29], 0.5 op_sel_hi:[1,0,0]
	v_lshl_add_u64 v[66:67], v[80:81], 0, v[120:121]
	v_cvt_u32_f32_sdwa v64, v64 dst_sel:BYTE_3 dst_unused:UNUSED_PAD src0_sel:DWORD
	v_cvt_u32_f32_sdwa v65, v65 dst_sel:BYTE_3 dst_unused:UNUSED_PAD src0_sel:DWORD
	v_or_b32_e32 v64, v69, v64
	v_or_b32_e32 v65, v68, v65
	global_store_dwordx2 v[66:67], v[64:65], off nt
	s_andn2_saveexec_b64 s[96:97], s[96:97]
	s_cbranch_execnz .LBB0_357
	s_branch .LBB0_358
.LBB0_388:
	v_pk_add_f32 v[56:57], v[56:57], v[170:171]
	v_pk_add_f32 v[60:61], v[60:61], v[166:167]
	v_pk_add_f32 v[58:59], v[58:59], v[172:173]
	v_mul_f32_e32 v60, 0xbfb8aa3b, v60
	v_exp_f32_e32 v60, v60
	v_mul_f32_e32 v61, 0xbfb8aa3b, v61
	v_exp_f32_e32 v61, v61
	v_pk_add_f32 v[62:63], v[62:63], v[168:169]
	v_add_f32_e32 v60, 1.0, v60
	v_add_f32_e32 v61, 1.0, v61
	v_mul_f32_e32 v62, 0xbfb8aa3b, v62
	v_exp_f32_e32 v62, v62
	v_rcp_f32_e32 v60, v60
	v_add_f32_e32 v62, 1.0, v62
	v_mul_f32_e32 v63, 0xbfb8aa3b, v63
	v_exp_f32_e32 v63, v63
	v_rcp_f32_e32 v61, v61
	v_add_f32_e32 v63, 1.0, v63
	v_mul_f32_e32 v56, 0xbfb8aa3b, v56
	v_exp_f32_e32 v56, v56
	v_rcp_f32_e32 v62, v62
	v_add_f32_e32 v56, 1.0, v56
	v_mul_f32_e32 v60, 0xbf60028a, v60
	v_mul_f32_e32 v61, 0xbf60028a, v61
	v_rcp_f32_e32 v63, v63
	v_mul_f32_e32 v62, 0xbf60028a, v62
	v_mul_f32_e32 v63, 0xbf60028a, v63
	v_rcp_f32_e32 v56, v56
	s_nop 0
	v_mul_f32_e32 v70, 0xbf60028a, v56
	v_mul_f32_e32 v56, 0xbfb8aa3b, v57
	v_exp_f32_e32 v56, v56
	s_nop 0
	v_add_f32_e32 v56, 1.0, v56
	v_rcp_f32_e32 v56, v56
	s_nop 0
	v_mul_f32_e32 v71, 0xbf60028a, v56
	v_mul_f32_e32 v56, 0xbfb8aa3b, v58
	v_exp_f32_e32 v56, v56
	s_nop 0
	v_add_f32_e32 v56, 1.0, v56
	v_rcp_f32_e32 v56, v56
	s_nop 0
	v_mul_f32_e32 v72, 0xbf60028a, v56
	v_mul_f32_e32 v56, 0xbfb8aa3b, v59
	v_exp_f32_e32 v56, v56
	s_nop 0
	v_add_f32_e32 v56, 1.0, v56
	v_rcp_f32_e32 v56, v56
	s_nop 0
	v_mul_f32_e32 v59, 0xbf60028a, v56
	v_lshl_add_u64 v[68:69], v[142:143], 1, v[66:67]
	v_cvt_pk_bf16_f32 v56, v60, v61
	v_cvt_pk_bf16_f32 v57, v62, v63
	v_cvt_pk_bf16_f32 v58, v70, v71
	v_cvt_pk_bf16_f32 v59, v72, v59
	global_store_dwordx4 v[68:69], v[56:59], off nt
	s_or_b64 exec, exec, s[96:97]
	s_and_saveexec_b64 s[0:1], s[10:11]
	s_xor_b64 s[96:97], exec, s[0:1]
	s_cbranch_execz .LBB0_362
.LBB0_389:
	v_mov_b32_e32 v121, v137
	v_pk_add_f32 v[48:49], v[48:49], v[178:179]
	v_pk_add_f32 v[52:53], v[52:53], v[174:175]
	v_pk_add_f32 v[58:59], v[50:51], v[180:181]
	v_mul_f32_e32 v50, 0xbfb8aa3b, v52
	v_mul_f32_e32 v48, 0xbfb8aa3b, v48
	v_exp_f32_e32 v52, v50
	v_mul_f32_e32 v50, 0xbfb8aa3b, v53
	v_exp_f32_e32 v53, v48
	v_pk_add_f32 v[54:55], v[54:55], v[176:177]
	v_mul_f32_e32 v48, 0xbfb8aa3b, v49
	v_exp_f32_e32 v56, v50
	v_mul_f32_e32 v50, 0xbfb8aa3b, v54
	v_exp_f32_e32 v57, v48
	v_mul_f32_e32 v48, 0xbfb8aa3b, v58
	v_exp_f32_e32 v54, v50
	v_mul_f32_e32 v50, 0xbfb8aa3b, v55
	v_exp_f32_e32 v55, v48
	v_mul_f32_e32 v48, 0xbfb8aa3b, v59
	v_exp_f32_e32 v51, v48
	v_pk_add_f32 v[48:49], v[52:53], 1.0 op_sel_hi:[1,0]
	v_pk_add_f32 v[54:55], v[54:55], 1.0 op_sel_hi:[1,0]
	v_exp_f32_e32 v50, v50
	v_rcp_f32_e32 v49, v49
	v_pk_add_f32 v[50:51], v[50:51], 1.0 op_sel_hi:[1,0]
	v_rcp_f32_e32 v48, v48
	v_pk_add_f32 v[52:53], v[56:57], 1.0 op_sel_hi:[1,0]
	v_pk_fma_f32 v[48:49], v[48:49], s[28:29], 0.5 op_sel_hi:[1,0,0]
	v_rcp_f32_e32 v53, v53
	v_rcp_f32_e32 v52, v52
	v_rcp_f32_e32 v55, v55
	v_rcp_f32_e32 v54, v54
	v_rcp_f32_e32 v51, v51
	v_rcp_f32_e32 v50, v50
	v_cvt_u32_f32_e32 v56, v49
	v_cvt_u32_f32_e32 v57, v48
	v_pk_fma_f32 v[48:49], v[52:53], s[28:29], 0.5 op_sel_hi:[1,0,0]
	s_nop 0
	v_cvt_u32_f32_e32 v48, v48
	v_cvt_u32_f32_e32 v49, v49
	v_lshlrev_b32_e32 v48, 8, v48
	v_lshlrev_b32_e32 v49, 8, v49
	v_or_b32_e32 v52, v49, v56
	v_or_b32_e32 v53, v48, v57
	v_pk_fma_f32 v[48:49], v[54:55], s[28:29], 0.5 op_sel_hi:[1,0,0]
	s_nop 0
	v_cvt_u32_f32_sdwa v48, v48 dst_sel:WORD_1 dst_unused:UNUSED_PAD src0_sel:DWORD
	v_cvt_u32_f32_sdwa v49, v49 dst_sel:WORD_1 dst_unused:UNUSED_PAD src0_sel:DWORD
	v_or_b32_e32 v53, v53, v48
	v_or_b32_e32 v52, v52, v49
	v_pk_fma_f32 v[48:49], v[50:51], s[28:29], 0.5 op_sel_hi:[1,0,0]
	v_lshl_add_u64 v[50:51], v[64:65], 0, v[120:121]
	v_cvt_u32_f32_sdwa v48, v48 dst_sel:BYTE_3 dst_unused:UNUSED_PAD src0_sel:DWORD
	v_cvt_u32_f32_sdwa v49, v49 dst_sel:BYTE_3 dst_unused:UNUSED_PAD src0_sel:DWORD
	v_or_b32_e32 v48, v53, v48
	v_or_b32_e32 v49, v52, v49
	global_store_dwordx2 v[50:51], v[48:49], off nt
	s_andn2_saveexec_b64 s[96:97], s[96:97]
	s_cbranch_execnz .LBB0_363
	s_branch .LBB0_364
.LBB0_390:
	v_pk_add_f32 v[40:41], v[40:41], v[170:171]
	v_pk_add_f32 v[44:45], v[44:45], v[166:167]
	v_pk_add_f32 v[42:43], v[42:43], v[172:173]
	v_mul_f32_e32 v44, 0xbfb8aa3b, v44
	v_exp_f32_e32 v44, v44
	v_mul_f32_e32 v45, 0xbfb8aa3b, v45
	v_exp_f32_e32 v45, v45
	v_pk_add_f32 v[46:47], v[46:47], v[168:169]
	v_add_f32_e32 v44, 1.0, v44
	v_add_f32_e32 v45, 1.0, v45
	v_mul_f32_e32 v46, 0xbfb8aa3b, v46
	v_exp_f32_e32 v46, v46
	v_rcp_f32_e32 v44, v44
	v_add_f32_e32 v46, 1.0, v46
	v_mul_f32_e32 v47, 0xbfb8aa3b, v47
	v_exp_f32_e32 v47, v47
	v_rcp_f32_e32 v45, v45
	v_add_f32_e32 v47, 1.0, v47
	v_mul_f32_e32 v40, 0xbfb8aa3b, v40
	v_exp_f32_e32 v40, v40
	v_rcp_f32_e32 v46, v46
	v_add_f32_e32 v40, 1.0, v40
	v_mul_f32_e32 v44, 0xbf60028a, v44
	v_mul_f32_e32 v45, 0xbf60028a, v45
	v_rcp_f32_e32 v47, v47
	v_mul_f32_e32 v46, 0xbf60028a, v46
	v_mul_f32_e32 v47, 0xbf60028a, v47
	v_rcp_f32_e32 v40, v40
	s_nop 0
	v_mul_f32_e32 v54, 0xbf60028a, v40
	v_mul_f32_e32 v40, 0xbfb8aa3b, v41
	v_exp_f32_e32 v40, v40
	s_nop 0
	v_add_f32_e32 v40, 1.0, v40
	v_rcp_f32_e32 v40, v40
	s_nop 0
	v_mul_f32_e32 v55, 0xbf60028a, v40
	v_mul_f32_e32 v40, 0xbfb8aa3b, v42
	v_exp_f32_e32 v40, v40
	s_nop 0
	v_add_f32_e32 v40, 1.0, v40
	v_rcp_f32_e32 v40, v40
	s_nop 0
	v_mul_f32_e32 v56, 0xbf60028a, v40
	v_mul_f32_e32 v40, 0xbfb8aa3b, v43
	v_exp_f32_e32 v40, v40
	s_nop 0
	v_add_f32_e32 v40, 1.0, v40
	v_rcp_f32_e32 v40, v40
	s_nop 0
	v_mul_f32_e32 v43, 0xbf60028a, v40
	v_lshl_add_u64 v[52:53], v[142:143], 1, v[50:51]
	v_cvt_pk_bf16_f32 v40, v44, v45
	v_cvt_pk_bf16_f32 v41, v46, v47
	v_cvt_pk_bf16_f32 v42, v54, v55
	v_cvt_pk_bf16_f32 v43, v56, v43
	global_store_dwordx4 v[52:53], v[40:43], off nt
	s_or_b64 exec, exec, s[96:97]
	s_and_saveexec_b64 s[0:1], s[10:11]
	s_xor_b64 s[96:97], exec, s[0:1]
	s_cbranch_execz .LBB0_368
.LBB0_391:
	v_mov_b32_e32 v121, v137
	v_pk_add_f32 v[32:33], v[32:33], v[178:179]
	v_pk_add_f32 v[36:37], v[36:37], v[174:175]
	v_pk_add_f32 v[42:43], v[34:35], v[180:181]
	v_mul_f32_e32 v34, 0xbfb8aa3b, v36
	v_mul_f32_e32 v32, 0xbfb8aa3b, v32
	v_exp_f32_e32 v36, v34
	v_mul_f32_e32 v34, 0xbfb8aa3b, v37
	v_exp_f32_e32 v37, v32
	v_pk_add_f32 v[38:39], v[38:39], v[176:177]
	v_mul_f32_e32 v32, 0xbfb8aa3b, v33
	v_exp_f32_e32 v40, v34
	v_mul_f32_e32 v34, 0xbfb8aa3b, v38
	v_exp_f32_e32 v41, v32
	v_mul_f32_e32 v32, 0xbfb8aa3b, v42
	v_exp_f32_e32 v38, v34
	v_mul_f32_e32 v34, 0xbfb8aa3b, v39
	v_exp_f32_e32 v39, v32
	v_mul_f32_e32 v32, 0xbfb8aa3b, v43
	v_exp_f32_e32 v35, v32
	v_pk_add_f32 v[32:33], v[36:37], 1.0 op_sel_hi:[1,0]
	v_pk_add_f32 v[38:39], v[38:39], 1.0 op_sel_hi:[1,0]
	v_exp_f32_e32 v34, v34
	v_rcp_f32_e32 v33, v33
	v_pk_add_f32 v[34:35], v[34:35], 1.0 op_sel_hi:[1,0]
	v_rcp_f32_e32 v32, v32
	v_pk_add_f32 v[36:37], v[40:41], 1.0 op_sel_hi:[1,0]
	v_pk_fma_f32 v[32:33], v[32:33], s[28:29], 0.5 op_sel_hi:[1,0,0]
	v_rcp_f32_e32 v37, v37
	v_rcp_f32_e32 v36, v36
	v_rcp_f32_e32 v39, v39
	v_rcp_f32_e32 v38, v38
	v_rcp_f32_e32 v35, v35
	v_rcp_f32_e32 v34, v34
	v_cvt_u32_f32_e32 v40, v33
	v_cvt_u32_f32_e32 v41, v32
	v_pk_fma_f32 v[32:33], v[36:37], s[28:29], 0.5 op_sel_hi:[1,0,0]
	s_nop 0
	v_cvt_u32_f32_e32 v32, v32
	v_cvt_u32_f32_e32 v33, v33
	v_lshlrev_b32_e32 v32, 8, v32
	v_lshlrev_b32_e32 v33, 8, v33
	v_or_b32_e32 v36, v33, v40
	v_or_b32_e32 v37, v32, v41
	v_pk_fma_f32 v[32:33], v[38:39], s[28:29], 0.5 op_sel_hi:[1,0,0]
	s_nop 0
	v_cvt_u32_f32_sdwa v32, v32 dst_sel:WORD_1 dst_unused:UNUSED_PAD src0_sel:DWORD
	v_cvt_u32_f32_sdwa v33, v33 dst_sel:WORD_1 dst_unused:UNUSED_PAD src0_sel:DWORD
	v_or_b32_e32 v37, v37, v32
	v_or_b32_e32 v36, v36, v33
	v_pk_fma_f32 v[32:33], v[34:35], s[28:29], 0.5 op_sel_hi:[1,0,0]
	v_lshl_add_u64 v[34:35], v[48:49], 0, v[120:121]
	v_cvt_u32_f32_sdwa v32, v32 dst_sel:BYTE_3 dst_unused:UNUSED_PAD src0_sel:DWORD
	v_cvt_u32_f32_sdwa v33, v33 dst_sel:BYTE_3 dst_unused:UNUSED_PAD src0_sel:DWORD
	v_or_b32_e32 v32, v37, v32
	v_or_b32_e32 v33, v36, v33
	global_store_dwordx2 v[34:35], v[32:33], off nt
	s_andn2_saveexec_b64 s[96:97], s[96:97]
	s_cbranch_execnz .LBB0_369
	s_branch .LBB0_370
.LBB0_392:
	v_pk_add_f32 v[24:25], v[24:25], v[170:171]
	v_pk_add_f32 v[28:29], v[28:29], v[166:167]
	v_pk_add_f32 v[26:27], v[26:27], v[172:173]
	v_mul_f32_e32 v28, 0xbfb8aa3b, v28
	v_exp_f32_e32 v28, v28
	v_mul_f32_e32 v29, 0xbfb8aa3b, v29
	v_exp_f32_e32 v29, v29
	v_pk_add_f32 v[30:31], v[30:31], v[168:169]
	v_add_f32_e32 v28, 1.0, v28
	v_add_f32_e32 v29, 1.0, v29
	v_mul_f32_e32 v30, 0xbfb8aa3b, v30
	v_exp_f32_e32 v30, v30
	v_rcp_f32_e32 v28, v28
	v_add_f32_e32 v30, 1.0, v30
	v_mul_f32_e32 v31, 0xbfb8aa3b, v31
	v_exp_f32_e32 v31, v31
	v_rcp_f32_e32 v29, v29
	v_add_f32_e32 v31, 1.0, v31
	v_mul_f32_e32 v24, 0xbfb8aa3b, v24
	v_exp_f32_e32 v24, v24
	v_rcp_f32_e32 v30, v30
	v_add_f32_e32 v24, 1.0, v24
	v_mul_f32_e32 v28, 0xbf60028a, v28
	v_mul_f32_e32 v29, 0xbf60028a, v29
	v_rcp_f32_e32 v31, v31
	v_mul_f32_e32 v30, 0xbf60028a, v30
	v_mul_f32_e32 v31, 0xbf60028a, v31
	v_rcp_f32_e32 v24, v24
	s_nop 0
	v_mul_f32_e32 v38, 0xbf60028a, v24
	v_mul_f32_e32 v24, 0xbfb8aa3b, v25
	v_exp_f32_e32 v24, v24
	s_nop 0
	v_add_f32_e32 v24, 1.0, v24
	v_rcp_f32_e32 v24, v24
	s_nop 0
	v_mul_f32_e32 v39, 0xbf60028a, v24
	v_mul_f32_e32 v24, 0xbfb8aa3b, v26
	v_exp_f32_e32 v24, v24
	s_nop 0
	v_add_f32_e32 v24, 1.0, v24
	v_rcp_f32_e32 v24, v24
	s_nop 0
	v_mul_f32_e32 v40, 0xbf60028a, v24
	v_mul_f32_e32 v24, 0xbfb8aa3b, v27
	v_exp_f32_e32 v24, v24
	s_nop 0
	v_add_f32_e32 v24, 1.0, v24
	v_rcp_f32_e32 v24, v24
	s_nop 0
	v_mul_f32_e32 v27, 0xbf60028a, v24
	v_lshl_add_u64 v[36:37], v[142:143], 1, v[34:35]
	v_cvt_pk_bf16_f32 v24, v28, v29
	v_cvt_pk_bf16_f32 v25, v30, v31
	v_cvt_pk_bf16_f32 v26, v38, v39
	v_cvt_pk_bf16_f32 v27, v40, v27
	global_store_dwordx4 v[36:37], v[24:27], off nt
	s_or_b64 exec, exec, s[96:97]
	s_and_saveexec_b64 s[0:1], s[10:11]
	s_xor_b64 s[96:97], exec, s[0:1]
	s_cbranch_execz .LBB0_374
.LBB0_393:
	v_mov_b32_e32 v121, v137
	v_pk_add_f32 v[16:17], v[16:17], v[178:179]
	v_pk_add_f32 v[20:21], v[20:21], v[174:175]
	v_pk_add_f32 v[26:27], v[18:19], v[180:181]
	v_mul_f32_e32 v18, 0xbfb8aa3b, v20
	v_mul_f32_e32 v16, 0xbfb8aa3b, v16
	v_exp_f32_e32 v20, v18
	v_mul_f32_e32 v18, 0xbfb8aa3b, v21
	v_exp_f32_e32 v21, v16
	v_pk_add_f32 v[22:23], v[22:23], v[176:177]
	v_mul_f32_e32 v16, 0xbfb8aa3b, v17
	v_exp_f32_e32 v24, v18
	v_mul_f32_e32 v18, 0xbfb8aa3b, v22
	v_exp_f32_e32 v25, v16
	v_mul_f32_e32 v16, 0xbfb8aa3b, v26
	v_exp_f32_e32 v22, v18
	v_mul_f32_e32 v18, 0xbfb8aa3b, v23
	v_exp_f32_e32 v23, v16
	v_mul_f32_e32 v16, 0xbfb8aa3b, v27
	v_exp_f32_e32 v19, v16
	v_pk_add_f32 v[16:17], v[20:21], 1.0 op_sel_hi:[1,0]
	v_pk_add_f32 v[22:23], v[22:23], 1.0 op_sel_hi:[1,0]
	v_exp_f32_e32 v18, v18
	v_rcp_f32_e32 v17, v17
	v_pk_add_f32 v[18:19], v[18:19], 1.0 op_sel_hi:[1,0]
	v_rcp_f32_e32 v16, v16
	v_pk_add_f32 v[20:21], v[24:25], 1.0 op_sel_hi:[1,0]
	v_pk_fma_f32 v[16:17], v[16:17], s[28:29], 0.5 op_sel_hi:[1,0,0]
	v_rcp_f32_e32 v21, v21
	v_rcp_f32_e32 v20, v20
	v_rcp_f32_e32 v23, v23
	v_rcp_f32_e32 v22, v22
	v_rcp_f32_e32 v19, v19
	v_rcp_f32_e32 v18, v18
	v_cvt_u32_f32_e32 v24, v17
	v_cvt_u32_f32_e32 v25, v16
	v_pk_fma_f32 v[16:17], v[20:21], s[28:29], 0.5 op_sel_hi:[1,0,0]
	s_nop 0
	v_cvt_u32_f32_e32 v16, v16
	v_cvt_u32_f32_e32 v17, v17
	v_lshlrev_b32_e32 v16, 8, v16
	v_lshlrev_b32_e32 v17, 8, v17
	v_or_b32_e32 v20, v17, v24
	v_or_b32_e32 v21, v16, v25
	v_pk_fma_f32 v[16:17], v[22:23], s[28:29], 0.5 op_sel_hi:[1,0,0]
	s_nop 0
	v_cvt_u32_f32_sdwa v16, v16 dst_sel:WORD_1 dst_unused:UNUSED_PAD src0_sel:DWORD
	v_cvt_u32_f32_sdwa v17, v17 dst_sel:WORD_1 dst_unused:UNUSED_PAD src0_sel:DWORD
	v_or_b32_e32 v21, v21, v16
	v_or_b32_e32 v20, v20, v17
	v_pk_fma_f32 v[16:17], v[18:19], s[28:29], 0.5 op_sel_hi:[1,0,0]
	v_lshl_add_u64 v[18:19], v[32:33], 0, v[120:121]
	v_cvt_u32_f32_sdwa v16, v16 dst_sel:BYTE_3 dst_unused:UNUSED_PAD src0_sel:DWORD
	v_cvt_u32_f32_sdwa v17, v17 dst_sel:BYTE_3 dst_unused:UNUSED_PAD src0_sel:DWORD
	v_or_b32_e32 v16, v21, v16
	v_or_b32_e32 v17, v20, v17
	global_store_dwordx2 v[18:19], v[16:17], off nt
	s_andn2_saveexec_b64 s[96:97], s[96:97]
	s_cbranch_execnz .LBB0_375
	s_branch .LBB0_376
.LBB0_394:
	v_pk_add_f32 v[8:9], v[8:9], v[170:171]
	v_pk_add_f32 v[12:13], v[12:13], v[166:167]
	v_pk_add_f32 v[10:11], v[10:11], v[172:173]
	v_mul_f32_e32 v12, 0xbfb8aa3b, v12
	v_exp_f32_e32 v12, v12
	v_mul_f32_e32 v13, 0xbfb8aa3b, v13
	v_exp_f32_e32 v13, v13
	v_pk_add_f32 v[14:15], v[14:15], v[168:169]
	v_add_f32_e32 v12, 1.0, v12
	v_add_f32_e32 v13, 1.0, v13
	v_mul_f32_e32 v14, 0xbfb8aa3b, v14
	v_exp_f32_e32 v14, v14
	v_rcp_f32_e32 v12, v12
	v_add_f32_e32 v14, 1.0, v14
	v_mul_f32_e32 v15, 0xbfb8aa3b, v15
	v_exp_f32_e32 v15, v15
	v_rcp_f32_e32 v13, v13
	v_add_f32_e32 v15, 1.0, v15
	v_mul_f32_e32 v8, 0xbfb8aa3b, v8
	v_exp_f32_e32 v8, v8
	v_rcp_f32_e32 v14, v14
	v_add_f32_e32 v8, 1.0, v8
	v_mul_f32_e32 v12, 0xbf60028a, v12
	v_mul_f32_e32 v13, 0xbf60028a, v13
	v_rcp_f32_e32 v15, v15
	v_mul_f32_e32 v14, 0xbf60028a, v14
	v_mul_f32_e32 v15, 0xbf60028a, v15
	v_rcp_f32_e32 v8, v8
	s_nop 0
	v_mul_f32_e32 v22, 0xbf60028a, v8
	v_mul_f32_e32 v8, 0xbfb8aa3b, v9
	v_exp_f32_e32 v8, v8
	s_nop 0
	v_add_f32_e32 v8, 1.0, v8
	v_rcp_f32_e32 v8, v8
	s_nop 0
	v_mul_f32_e32 v23, 0xbf60028a, v8
	v_mul_f32_e32 v8, 0xbfb8aa3b, v10
	v_exp_f32_e32 v8, v8
	s_nop 0
	v_add_f32_e32 v8, 1.0, v8
	v_rcp_f32_e32 v8, v8
	s_nop 0
	v_mul_f32_e32 v24, 0xbf60028a, v8
	v_mul_f32_e32 v8, 0xbfb8aa3b, v11
	v_exp_f32_e32 v8, v8
	s_nop 0
	v_add_f32_e32 v8, 1.0, v8
	v_rcp_f32_e32 v8, v8
	s_nop 0
	v_mul_f32_e32 v11, 0xbf60028a, v8
	v_lshl_add_u64 v[20:21], v[142:143], 1, v[18:19]
	v_cvt_pk_bf16_f32 v8, v12, v13
	v_cvt_pk_bf16_f32 v9, v14, v15
	v_cvt_pk_bf16_f32 v10, v22, v23
	v_cvt_pk_bf16_f32 v11, v24, v11
	global_store_dwordx4 v[20:21], v[8:11], off nt
	s_or_b64 exec, exec, s[8:9]
	s_and_saveexec_b64 s[0:1], s[10:11]
	s_xor_b64 s[8:9], exec, s[0:1]
	s_cbranch_execz .LBB0_380
.LBB0_395:
	v_mov_b32_e32 v121, v137
	v_pk_add_f32 v[0:1], v[0:1], v[178:179]
	v_pk_add_f32 v[4:5], v[4:5], v[174:175]
	v_pk_add_f32 v[10:11], v[2:3], v[180:181]
	v_mul_f32_e32 v2, 0xbfb8aa3b, v4
	v_mul_f32_e32 v0, 0xbfb8aa3b, v0
	v_exp_f32_e32 v4, v2
	v_mul_f32_e32 v2, 0xbfb8aa3b, v5
	v_exp_f32_e32 v5, v0
	v_pk_add_f32 v[6:7], v[6:7], v[176:177]
	v_mul_f32_e32 v0, 0xbfb8aa3b, v1
	v_exp_f32_e32 v8, v2
	v_mul_f32_e32 v2, 0xbfb8aa3b, v6
	v_exp_f32_e32 v9, v0
	v_mul_f32_e32 v0, 0xbfb8aa3b, v10
	v_exp_f32_e32 v6, v2
	v_mul_f32_e32 v2, 0xbfb8aa3b, v7
	v_exp_f32_e32 v7, v0
	v_mul_f32_e32 v0, 0xbfb8aa3b, v11
	v_exp_f32_e32 v3, v0
	v_pk_add_f32 v[0:1], v[4:5], 1.0 op_sel_hi:[1,0]
	v_pk_add_f32 v[6:7], v[6:7], 1.0 op_sel_hi:[1,0]
	v_exp_f32_e32 v2, v2
	v_rcp_f32_e32 v1, v1
	v_pk_add_f32 v[2:3], v[2:3], 1.0 op_sel_hi:[1,0]
	v_rcp_f32_e32 v0, v0
	v_pk_add_f32 v[4:5], v[8:9], 1.0 op_sel_hi:[1,0]
	v_pk_fma_f32 v[0:1], v[0:1], s[28:29], 0.5 op_sel_hi:[1,0,0]
	v_rcp_f32_e32 v5, v5
	v_rcp_f32_e32 v4, v4
	v_rcp_f32_e32 v7, v7
	v_rcp_f32_e32 v6, v6
	v_rcp_f32_e32 v3, v3
	v_rcp_f32_e32 v2, v2
	v_cvt_u32_f32_e32 v8, v1
	v_cvt_u32_f32_e32 v9, v0
	v_pk_fma_f32 v[0:1], v[4:5], s[28:29], 0.5 op_sel_hi:[1,0,0]
	s_nop 0
	v_cvt_u32_f32_e32 v0, v0
	v_cvt_u32_f32_e32 v1, v1
	v_lshlrev_b32_e32 v0, 8, v0
	v_lshlrev_b32_e32 v1, 8, v1
	v_or_b32_e32 v4, v1, v8
	v_or_b32_e32 v5, v0, v9
	v_pk_fma_f32 v[0:1], v[6:7], s[28:29], 0.5 op_sel_hi:[1,0,0]
	s_nop 0
	v_cvt_u32_f32_sdwa v0, v0 dst_sel:WORD_1 dst_unused:UNUSED_PAD src0_sel:DWORD
	v_cvt_u32_f32_sdwa v1, v1 dst_sel:WORD_1 dst_unused:UNUSED_PAD src0_sel:DWORD
	v_or_b32_e32 v5, v5, v0
	v_or_b32_e32 v4, v4, v1
	v_pk_fma_f32 v[0:1], v[2:3], s[28:29], 0.5 op_sel_hi:[1,0,0]
	v_lshl_add_u64 v[2:3], v[16:17], 0, v[120:121]
	v_cvt_u32_f32_sdwa v0, v0 dst_sel:BYTE_3 dst_unused:UNUSED_PAD src0_sel:DWORD
	v_cvt_u32_f32_sdwa v1, v1 dst_sel:BYTE_3 dst_unused:UNUSED_PAD src0_sel:DWORD
	v_or_b32_e32 v0, v5, v0
	v_or_b32_e32 v1, v4, v1
	global_store_dwordx2 v[2:3], v[0:1], off nt
	s_andn2_saveexec_b64 s[8:9], s[8:9]
	s_cbranch_execz .LBB0_381
.LBB0_396:
	v_pk_add_f32 v[0:1], v[0:1], v[178:179]
	v_pk_add_f32 v[4:5], v[4:5], v[174:175]
	v_pk_add_f32 v[2:3], v[2:3], v[180:181]
	v_mul_f32_e32 v4, 0xbfb8aa3b, v4
	v_exp_f32_e32 v4, v4
	v_mul_f32_e32 v5, 0xbfb8aa3b, v5
	v_exp_f32_e32 v5, v5
	v_pk_add_f32 v[6:7], v[6:7], v[176:177]
	v_add_f32_e32 v4, 1.0, v4
	v_add_f32_e32 v5, 1.0, v5
	v_mul_f32_e32 v6, 0xbfb8aa3b, v6
	v_exp_f32_e32 v6, v6
	v_rcp_f32_e32 v4, v4
	v_add_f32_e32 v6, 1.0, v6
	v_mul_f32_e32 v7, 0xbfb8aa3b, v7
	v_exp_f32_e32 v7, v7
	v_rcp_f32_e32 v5, v5
	v_add_f32_e32 v7, 1.0, v7
	v_mul_f32_e32 v0, 0xbfb8aa3b, v0
	v_exp_f32_e32 v0, v0
	v_rcp_f32_e32 v6, v6
	v_add_f32_e32 v0, 1.0, v0
	v_mul_f32_e32 v4, 0xbf60028a, v4
	v_mul_f32_e32 v5, 0xbf60028a, v5
	v_rcp_f32_e32 v7, v7
	v_mul_f32_e32 v6, 0xbf60028a, v6
	v_mul_f32_e32 v7, 0xbf60028a, v7
	v_rcp_f32_e32 v0, v0
	s_nop 0
	v_mul_f32_e32 v10, 0xbf60028a, v0
	v_mul_f32_e32 v0, 0xbfb8aa3b, v1
	v_exp_f32_e32 v0, v0
	s_nop 0
	v_add_f32_e32 v0, 1.0, v0
	v_rcp_f32_e32 v0, v0
	s_nop 0
	v_mul_f32_e32 v11, 0xbf60028a, v0
	v_mul_f32_e32 v0, 0xbfb8aa3b, v2
	v_exp_f32_e32 v0, v0
	s_nop 0
	v_add_f32_e32 v0, 1.0, v0
	v_rcp_f32_e32 v0, v0
	s_nop 0
	v_mul_f32_e32 v12, 0xbf60028a, v0
	v_mul_f32_e32 v0, 0xbfb8aa3b, v3
	v_exp_f32_e32 v0, v0
	s_nop 0
	v_add_f32_e32 v0, 1.0, v0
	v_rcp_f32_e32 v0, v0
	s_nop 0
	v_mul_f32_e32 v3, 0xbf60028a, v0
	v_lshl_add_u64 v[8:9], v[142:143], 1, v[18:19]
	v_cvt_pk_bf16_f32 v0, v4, v5
	v_cvt_pk_bf16_f32 v1, v6, v7
	v_cvt_pk_bf16_f32 v2, v10, v11
	v_cvt_pk_bf16_f32 v3, v12, v3
	global_store_dwordx4 v[8:9], v[0:3], off offset:256 nt
	s_or_b64 exec, exec, s[8:9]
	s_andn2_b64 vcc, exec, s[6:7]
	s_mov_b64 s[0:1], -1
	s_cbranch_vccnz .LBB0_323

.LBB0_973:
	s_lshl_b32 s4, s20, 8
	v_add_u32_e32 v144, s4, v146
	v_ashrrev_i32_e32 v145, 31, v144
	v_lshl_or_b32 v160, s40, 8, v155
	v_lshlrev_b64 v[144:145], 11, v[144:145]
	v_ashrrev_i32_e32 v161, 31, v160
	v_lshl_add_u64 v[162:163], s[82:83], 0, v[144:145]
	v_lshlrev_b64 v[144:145], 1, v[160:161]
	v_lshl_add_u64 v[160:161], v[162:163], 0, v[144:145]
	v_cvt_pk_bf16_f32 v124, v124, v125
	v_cvt_pk_bf16_f32 v125, v126, v127
	v_cvt_pk_bf16_f32 v126, v120, v121
	v_cvt_pk_bf16_f32 v127, v122, v123
	global_store_dwordx4 v[160:161], v[124:127], off nt
	v_cvt_pk_bf16_f32 v112, v112, v113
	v_cvt_pk_bf16_f32 v113, v114, v115
	v_cvt_pk_bf16_f32 v114, v104, v105
	v_add_u32_e32 v104, s4, v148
	v_ashrrev_i32_e32 v105, 31, v104
	v_lshlrev_b64 v[104:105], 11, v[104:105]
	v_lshl_add_u64 v[104:105], s[82:83], 0, v[104:105]
	v_cvt_pk_bf16_f32 v115, v106, v107
	global_store_dwordx4 v[160:161], v[112:115], off offset:256 nt
	s_andn2_b64 vcc, exec, s[6:7]
	s_nop 0
	v_lshl_add_u64 v[112:113], v[104:105], 0, v[144:145]
	v_cvt_pk_bf16_f32 v104, v116, v117
	v_cvt_pk_bf16_f32 v105, v118, v119
	v_cvt_pk_bf16_f32 v106, v108, v109
	v_cvt_pk_bf16_f32 v107, v110, v111
	global_store_dwordx4 v[112:113], v[104:107], off nt
	v_cvt_pk_bf16_f32 v96, v96, v97
	v_cvt_pk_bf16_f32 v97, v98, v99
	v_cvt_pk_bf16_f32 v98, v88, v89
	v_add_u32_e32 v88, s4, v149
	v_ashrrev_i32_e32 v89, 31, v88
	v_lshlrev_b64 v[88:89], 11, v[88:89]
	v_lshl_add_u64 v[88:89], s[82:83], 0, v[88:89]
	v_cvt_pk_bf16_f32 v99, v90, v91
	global_store_dwordx4 v[112:113], v[96:99], off offset:256 nt
	s_nop 1
	v_lshl_add_u64 v[96:97], v[88:89], 0, v[144:145]
	v_cvt_pk_bf16_f32 v88, v100, v101
	v_cvt_pk_bf16_f32 v89, v102, v103
	v_cvt_pk_bf16_f32 v90, v92, v93
	v_cvt_pk_bf16_f32 v91, v94, v95
	global_store_dwordx4 v[96:97], v[88:91], off nt
	v_cvt_pk_bf16_f32 v80, v80, v81
	v_cvt_pk_bf16_f32 v81, v82, v83
	v_cvt_pk_bf16_f32 v82, v72, v73
	v_add_u32_e32 v72, s4, v150
	v_ashrrev_i32_e32 v73, 31, v72
	v_lshlrev_b64 v[72:73], 11, v[72:73]
	v_lshl_add_u64 v[72:73], s[82:83], 0, v[72:73]
	v_cvt_pk_bf16_f32 v83, v74, v75
	global_store_dwordx4 v[96:97], v[80:83], off offset:256 nt
	s_nop 1
	v_lshl_add_u64 v[80:81], v[72:73], 0, v[144:145]
	v_cvt_pk_bf16_f32 v72, v84, v85
	v_cvt_pk_bf16_f32 v73, v86, v87
	v_cvt_pk_bf16_f32 v74, v76, v77
	v_cvt_pk_bf16_f32 v75, v78, v79
	global_store_dwordx4 v[80:81], v[72:75], off nt
	v_cvt_pk_bf16_f32 v68, v68, v69
	v_cvt_pk_bf16_f32 v69, v70, v71
	v_cvt_pk_bf16_f32 v70, v64, v65
	v_add_u32_e32 v64, s4, v151
	v_ashrrev_i32_e32 v65, 31, v64
	v_lshlrev_b64 v[64:65], 11, v[64:65]
	v_lshl_add_u64 v[64:65], s[82:83], 0, v[64:65]
	v_lshl_add_u64 v[64:65], v[64:65], 0, v[144:145]
	v_cvt_pk_bf16_f32 v71, v66, v67
	global_store_dwordx4 v[80:81], v[68:71], off offset:256 nt
	v_cvt_pk_bf16_f32 v60, v60, v61
	v_cvt_pk_bf16_f32 v61, v62, v63
	v_cvt_pk_bf16_f32 v62, v56, v57
	v_cvt_pk_bf16_f32 v63, v58, v59
	global_store_dwordx4 v[64:65], v[60:63], off nt
	v_cvt_pk_bf16_f32 v48, v48, v49
	v_cvt_pk_bf16_f32 v49, v50, v51
	v_cvt_pk_bf16_f32 v50, v40, v41
	v_add_u32_e32 v40, s4, v152
	v_ashrrev_i32_e32 v41, 31, v40
	v_lshlrev_b64 v[40:41], 11, v[40:41]
	v_lshl_add_u64 v[40:41], s[82:83], 0, v[40:41]
	v_cvt_pk_bf16_f32 v51, v42, v43
	global_store_dwordx4 v[64:65], v[48:51], off offset:256 nt
	s_nop 1
	v_lshl_add_u64 v[48:49], v[40:41], 0, v[144:145]
	v_cvt_pk_bf16_f32 v40, v52, v53
	v_cvt_pk_bf16_f32 v41, v54, v55
	v_cvt_pk_bf16_f32 v42, v44, v45
	v_cvt_pk_bf16_f32 v43, v46, v47
	global_store_dwordx4 v[48:49], v[40:43], off nt
	v_cvt_pk_bf16_f32 v32, v32, v33
	v_cvt_pk_bf16_f32 v33, v34, v35
	v_cvt_pk_bf16_f32 v34, v24, v25
	v_add_u32_e32 v24, s4, v153
	v_ashrrev_i32_e32 v25, 31, v24
	v_lshlrev_b64 v[24:25], 11, v[24:25]
	v_lshl_add_u64 v[24:25], s[82:83], 0, v[24:25]
	v_cvt_pk_bf16_f32 v35, v26, v27
	global_store_dwordx4 v[48:49], v[32:35], off offset:256 nt
	s_nop 1
	v_lshl_add_u64 v[32:33], v[24:25], 0, v[144:145]
	v_cvt_pk_bf16_f32 v24, v36, v37
	v_cvt_pk_bf16_f32 v25, v38, v39
	v_cvt_pk_bf16_f32 v26, v28, v29
	v_cvt_pk_bf16_f32 v27, v30, v31
	global_store_dwordx4 v[32:33], v[24:27], off nt
	v_cvt_pk_bf16_f32 v16, v16, v17
	v_cvt_pk_bf16_f32 v17, v18, v19
	v_cvt_pk_bf16_f32 v18, v8, v9
	v_add_u32_e32 v8, s4, v154
	v_ashrrev_i32_e32 v9, 31, v8
	v_lshlrev_b64 v[8:9], 11, v[8:9]
	v_lshl_add_u64 v[8:9], s[82:83], 0, v[8:9]
	v_cvt_pk_bf16_f32 v19, v10, v11
	global_store_dwordx4 v[32:33], v[16:19], off offset:256 nt
	s_mov_b64 s[4:5], -1
	s_nop 0
	v_lshl_add_u64 v[16:17], v[8:9], 0, v[144:145]
	v_cvt_pk_bf16_f32 v8, v20, v21
	v_cvt_pk_bf16_f32 v9, v22, v23
	v_cvt_pk_bf16_f32 v10, v12, v13
	v_cvt_pk_bf16_f32 v11, v14, v15
	global_store_dwordx4 v[16:17], v[8:11], off nt
	v_cvt_pk_bf16_f32 v4, v4, v5
	v_cvt_pk_bf16_f32 v5, v6, v7
	v_cvt_pk_bf16_f32 v6, v0, v1
	v_cvt_pk_bf16_f32 v7, v2, v3
	global_store_dwordx4 v[16:17], v[4:7], off offset:256 nt
	s_cbranch_vccnz .LBB0_962
	s_andn2_b64 vcc, exec, s[0:1]
	s_cbranch_vccnz .LBB0_961
	s_barrier
	s_branch .LBB0_961

.LBB0_1100:
	v_mul_f32_e32 v125, 0xbfb8aa3b, v125
	v_exp_f32_e32 v156, v125
	v_mul_f32_e32 v125, 0xbfb8aa3b, v126
	v_mul_f32_e32 v124, 0xbfb8aa3b, v124
	v_exp_f32_e32 v126, v125
	v_mul_f32_e32 v125, 0xbfb8aa3b, v127
	v_mul_f32_e32 v120, 0xbfb8aa3b, v120
	v_exp_f32_e32 v124, v124
	v_exp_f32_e32 v158, v125
	v_exp_f32_e32 v125, v120
	v_mul_f32_e32 v120, 0xbfb8aa3b, v121
	v_exp_f32_e32 v157, v120
	v_mul_f32_e32 v122, 0xbfb8aa3b, v122
	v_pk_add_f32 v[120:121], v[124:125], 1.0 op_sel_hi:[1,0]
	v_exp_f32_e32 v127, v122
	v_mul_f32_e32 v122, 0xbfb8aa3b, v123
	v_exp_f32_e32 v159, v122
	v_lshl_add_u32 v146, s22, 8, v148
	v_rcp_f32_e32 v121, v121
	v_ashrrev_i32_e32 v147, 31, v146
	v_pk_add_f32 v[122:123], v[156:157], 1.0 op_sel_hi:[1,0]
	v_lshlrev_b64 v[154:155], 10, v[146:147]
	v_rcp_f32_e32 v120, v120
	s_nop 0
	v_pk_fma_f32 v[120:121], v[120:121], s[12:13], 0.5 op_sel_hi:[1,0,0]
	v_rcp_f32_e32 v123, v123
	v_lshl_or_b32 v144, s41, 8, v150
	v_rcp_f32_e32 v122, v122
	s_nop 0
	v_pk_fma_f32 v[122:123], v[122:123], s[12:13], 0.5 op_sel_hi:[1,0,0]
	v_cvt_u32_f32_e32 v124, v121
	v_cvt_u32_f32_e32 v125, v120
	v_pk_add_f32 v[120:121], v[126:127], 1.0 op_sel_hi:[1,0]
	v_cvt_u32_f32_e32 v122, v122
	v_cvt_u32_f32_e32 v123, v123
	v_lshlrev_b32_e32 v122, 8, v122
	v_or_b32_e32 v125, v122, v125
	v_lshlrev_b32_e32 v123, 8, v123
	v_or_b32_e32 v124, v123, v124
	v_rcp_f32_e32 v121, v121
	v_mul_f32_e32 v117, 0xbfb8aa3b, v117
	v_rcp_f32_e32 v120, v120
	v_pk_add_f32 v[122:123], v[158:159], 1.0 op_sel_hi:[1,0]
	v_pk_fma_f32 v[120:121], v[120:121], s[12:13], 0.5 op_sel_hi:[1,0,0]
	s_nop 0
	v_cvt_u32_f32_sdwa v145, v120 dst_sel:WORD_1 dst_unused:UNUSED_PAD src0_sel:DWORD
	v_cvt_u32_f32_sdwa v147, v121 dst_sel:WORD_1 dst_unused:UNUSED_PAD src0_sel:DWORD
	v_mul_f32_e32 v116, 0xbfb8aa3b, v116
	v_rcp_f32_e32 v121, v123
	v_mul_f32_e32 v112, 0xbfb8aa3b, v112
	v_rcp_f32_e32 v120, v122
	s_nop 0
	v_pk_fma_f32 v[120:121], v[120:121], s[12:13], 0.5 op_sel_hi:[1,0,0]
	v_or_b32_e32 v122, v124, v147
	v_cvt_u32_f32_sdwa v121, v121 dst_sel:BYTE_3 dst_unused:UNUSED_PAD src0_sel:DWORD
	v_cvt_u32_f32_sdwa v120, v120 dst_sel:BYTE_3 dst_unused:UNUSED_PAD src0_sel:DWORD
	v_or_b32_e32 v123, v125, v145
	v_ashrrev_i32_e32 v145, 31, v144
	v_or_b32_e32 v121, v122, v121
	v_or_b32_e32 v120, v123, v120
	v_lshl_add_u64 v[122:123], s[80:81], 0, v[154:155]
	v_lshl_add_u64 v[122:123], v[122:123], 0, v[144:145]
	global_store_dwordx2 v[122:123], v[120:121], off nt
	v_exp_f32_e32 v120, v117
	v_mul_f32_e32 v117, 0xbfb8aa3b, v118
	v_exp_f32_e32 v118, v117
	v_mul_f32_e32 v117, 0xbfb8aa3b, v119
	v_exp_f32_e32 v116, v116
	v_exp_f32_e32 v124, v117
	v_exp_f32_e32 v117, v112
	v_mul_f32_e32 v112, 0xbfb8aa3b, v113
	v_exp_f32_e32 v121, v112
	v_mul_f32_e32 v114, 0xbfb8aa3b, v114
	v_pk_add_f32 v[112:113], v[116:117], 1.0 op_sel_hi:[1,0]
	v_exp_f32_e32 v119, v114
	v_mul_f32_e32 v114, 0xbfb8aa3b, v115
	v_exp_f32_e32 v125, v114
	v_mul_f32_e32 v109, 0xbfb8aa3b, v109
	v_rcp_f32_e32 v113, v113
	v_mul_f32_e32 v108, 0xbfb8aa3b, v108
	v_pk_add_f32 v[114:115], v[120:121], 1.0 op_sel_hi:[1,0]
	v_rcp_f32_e32 v112, v112
	s_nop 0
	v_pk_fma_f32 v[112:113], v[112:113], s[12:13], 0.5 op_sel_hi:[1,0,0]
	v_mul_f32_e32 v104, 0xbfb8aa3b, v104
	v_rcp_f32_e32 v115, v115
	v_exp_f32_e32 v108, v108
	v_rcp_f32_e32 v114, v114
	s_nop 0
	v_pk_fma_f32 v[114:115], v[114:115], s[12:13], 0.5 op_sel_hi:[1,0,0]
	v_cvt_u32_f32_e32 v116, v113
	v_cvt_u32_f32_e32 v117, v112
	v_pk_add_f32 v[112:113], v[118:119], 1.0 op_sel_hi:[1,0]
	v_cvt_u32_f32_e32 v114, v114
	v_cvt_u32_f32_e32 v115, v115
	v_lshlrev_b32_e32 v114, 8, v114
	v_or_b32_e32 v117, v114, v117
	v_lshlrev_b32_e32 v115, 8, v115
	v_or_b32_e32 v116, v115, v116
	v_rcp_f32_e32 v113, v113
	v_mul_f32_e32 v106, 0xbfb8aa3b, v106
	v_rcp_f32_e32 v112, v112
	v_pk_add_f32 v[114:115], v[124:125], 1.0 op_sel_hi:[1,0]
	v_pk_fma_f32 v[112:113], v[112:113], s[12:13], 0.5 op_sel_hi:[1,0,0]
	s_nop 0
	v_cvt_u32_f32_sdwa v120, v112 dst_sel:WORD_1 dst_unused:UNUSED_PAD src0_sel:DWORD
	v_cvt_u32_f32_sdwa v121, v113 dst_sel:WORD_1 dst_unused:UNUSED_PAD src0_sel:DWORD
	v_mul_f32_e32 v101, 0xbfb8aa3b, v101
	v_rcp_f32_e32 v113, v115
	v_mul_f32_e32 v100, 0xbfb8aa3b, v100
	v_rcp_f32_e32 v112, v114
	s_nop 0
	v_pk_fma_f32 v[112:113], v[112:113], s[12:13], 0.5 op_sel_hi:[1,0,0]
	v_or_b32_e32 v114, v116, v121
	v_cvt_u32_f32_sdwa v113, v113 dst_sel:BYTE_3 dst_unused:UNUSED_PAD src0_sel:DWORD
	v_cvt_u32_f32_sdwa v112, v112 dst_sel:BYTE_3 dst_unused:UNUSED_PAD src0_sel:DWORD
	v_or_b32_e32 v115, v117, v120
	v_mul_f32_e32 v96, 0xbfb8aa3b, v96
	v_or_b32_e32 v113, v114, v113
	v_exp_f32_e32 v114, v109
	v_mul_f32_e32 v109, 0xbfb8aa3b, v110
	v_exp_f32_e32 v110, v109
	v_mul_f32_e32 v109, 0xbfb8aa3b, v111
	v_exp_f32_e32 v116, v109
	v_exp_f32_e32 v109, v104
	v_mul_f32_e32 v104, 0xbfb8aa3b, v105
	v_or_b32_e32 v112, v115, v112
	v_exp_f32_e32 v115, v104
	v_pk_add_f32 v[104:105], v[108:109], 1.0 op_sel_hi:[1,0]
	v_exp_f32_e32 v111, v106
	v_mul_f32_e32 v106, 0xbfb8aa3b, v107
	v_exp_f32_e32 v117, v106
	global_store_dwordx2 v[122:123], v[112:113], off offset:128 nt
	v_rcp_f32_e32 v105, v105
	v_or_b32_e32 v112, 16, v146
	v_pk_add_f32 v[106:107], v[114:115], 1.0 op_sel_hi:[1,0]
	v_rcp_f32_e32 v104, v104
	s_nop 0
	v_pk_fma_f32 v[104:105], v[104:105], s[12:13], 0.5 op_sel_hi:[1,0,0]
	v_ashrrev_i32_e32 v113, 31, v112
	v_rcp_f32_e32 v107, v107
	v_lshlrev_b64 v[112:113], 10, v[112:113]
	v_rcp_f32_e32 v106, v106
	s_nop 0
	v_pk_fma_f32 v[106:107], v[106:107], s[12:13], 0.5 op_sel_hi:[1,0,0]
	v_cvt_u32_f32_e32 v108, v105
	v_cvt_u32_f32_e32 v109, v104
	v_pk_add_f32 v[104:105], v[110:111], 1.0 op_sel_hi:[1,0]
	v_cvt_u32_f32_e32 v106, v106
	v_cvt_u32_f32_e32 v107, v107
	v_lshlrev_b32_e32 v106, 8, v106
	v_or_b32_e32 v109, v106, v109
	v_lshlrev_b32_e32 v107, 8, v107
	v_or_b32_e32 v108, v107, v108
	v_rcp_f32_e32 v105, v105
	v_exp_f32_e32 v100, v100
	v_rcp_f32_e32 v104, v104
	v_pk_add_f32 v[106:107], v[116:117], 1.0 op_sel_hi:[1,0]
	v_pk_fma_f32 v[104:105], v[104:105], s[12:13], 0.5 op_sel_hi:[1,0,0]
	s_nop 0
	v_cvt_u32_f32_sdwa v114, v104 dst_sel:WORD_1 dst_unused:UNUSED_PAD src0_sel:DWORD
	v_cvt_u32_f32_sdwa v115, v105 dst_sel:WORD_1 dst_unused:UNUSED_PAD src0_sel:DWORD
	v_mul_f32_e32 v98, 0xbfb8aa3b, v98
	v_rcp_f32_e32 v105, v107
	v_mul_f32_e32 v93, 0xbfb8aa3b, v93
	v_rcp_f32_e32 v104, v106
	s_nop 0
	v_pk_fma_f32 v[104:105], v[104:105], s[12:13], 0.5 op_sel_hi:[1,0,0]
	v_or_b32_e32 v106, v108, v115
	v_cvt_u32_f32_sdwa v105, v105 dst_sel:BYTE_3 dst_unused:UNUSED_PAD src0_sel:DWORD
	v_cvt_u32_f32_sdwa v104, v104 dst_sel:BYTE_3 dst_unused:UNUSED_PAD src0_sel:DWORD
	v_or_b32_e32 v107, v109, v114
	v_mul_f32_e32 v92, 0xbfb8aa3b, v92
	v_or_b32_e32 v105, v106, v105
	v_or_b32_e32 v104, v107, v104
	v_lshl_add_u64 v[106:107], s[80:81], 0, v[112:113]
	v_lshl_add_u64 v[106:107], v[106:107], 0, v[144:145]
	global_store_dwordx2 v[106:107], v[104:105], off nt
	v_exp_f32_e32 v104, v101
	v_mul_f32_e32 v101, 0xbfb8aa3b, v102
	v_exp_f32_e32 v102, v101
	v_mul_f32_e32 v101, 0xbfb8aa3b, v103
	v_exp_f32_e32 v108, v101
	v_exp_f32_e32 v101, v96
	v_mul_f32_e32 v96, 0xbfb8aa3b, v97
	v_exp_f32_e32 v105, v96
	v_exp_f32_e32 v103, v98
	v_pk_add_f32 v[96:97], v[100:101], 1.0 op_sel_hi:[1,0]
	v_mul_f32_e32 v98, 0xbfb8aa3b, v99
	v_exp_f32_e32 v109, v98
	v_mul_f32_e32 v88, 0xbfb8aa3b, v88
	v_exp_f32_e32 v92, v92
	v_rcp_f32_e32 v97, v97
	v_mul_f32_e32 v90, 0xbfb8aa3b, v90
	v_pk_add_f32 v[98:99], v[104:105], 1.0 op_sel_hi:[1,0]
	v_rcp_f32_e32 v96, v96
	s_nop 0
	v_pk_fma_f32 v[96:97], v[96:97], s[12:13], 0.5 op_sel_hi:[1,0,0]
	v_mul_f32_e32 v85, 0xbfb8aa3b, v85
	v_rcp_f32_e32 v99, v99
	v_mul_f32_e32 v84, 0xbfb8aa3b, v84
	v_rcp_f32_e32 v98, v98
	s_nop 0
	v_pk_fma_f32 v[98:99], v[98:99], s[12:13], 0.5 op_sel_hi:[1,0,0]
	v_cvt_u32_f32_e32 v100, v97
	v_cvt_u32_f32_e32 v101, v96
	v_pk_add_f32 v[96:97], v[102:103], 1.0 op_sel_hi:[1,0]
	v_cvt_u32_f32_e32 v98, v98
	v_cvt_u32_f32_e32 v99, v99
	v_lshlrev_b32_e32 v98, 8, v98
	v_or_b32_e32 v101, v98, v101
	v_lshlrev_b32_e32 v99, 8, v99
	v_or_b32_e32 v100, v99, v100
	v_rcp_f32_e32 v97, v97
	v_mul_f32_e32 v80, 0xbfb8aa3b, v80
	v_rcp_f32_e32 v96, v96
	v_pk_add_f32 v[98:99], v[108:109], 1.0 op_sel_hi:[1,0]
	v_pk_fma_f32 v[96:97], v[96:97], s[12:13], 0.5 op_sel_hi:[1,0,0]
	s_nop 0
	v_cvt_u32_f32_sdwa v104, v96 dst_sel:WORD_1 dst_unused:UNUSED_PAD src0_sel:DWORD
	v_cvt_u32_f32_sdwa v105, v97 dst_sel:WORD_1 dst_unused:UNUSED_PAD src0_sel:DWORD
	v_exp_f32_e32 v84, v84
	v_rcp_f32_e32 v97, v99
	v_mul_f32_e32 v82, 0xbfb8aa3b, v82
	v_rcp_f32_e32 v96, v98
	s_nop 0
	v_pk_fma_f32 v[96:97], v[96:97], s[12:13], 0.5 op_sel_hi:[1,0,0]
	v_or_b32_e32 v98, v100, v105
	v_cvt_u32_f32_sdwa v97, v97 dst_sel:BYTE_3 dst_unused:UNUSED_PAD src0_sel:DWORD
	v_cvt_u32_f32_sdwa v96, v96 dst_sel:BYTE_3 dst_unused:UNUSED_PAD src0_sel:DWORD
	v_or_b32_e32 v99, v101, v104
	v_mul_f32_e32 v77, 0xbfb8aa3b, v77
	v_or_b32_e32 v97, v98, v97
	v_exp_f32_e32 v98, v93
	v_mul_f32_e32 v93, 0xbfb8aa3b, v94
	v_exp_f32_e32 v94, v93
	v_mul_f32_e32 v93, 0xbfb8aa3b, v95
	v_exp_f32_e32 v100, v93
	v_exp_f32_e32 v93, v88
	v_mul_f32_e32 v88, 0xbfb8aa3b, v89
	v_or_b32_e32 v96, v99, v96
	v_exp_f32_e32 v99, v88
	v_pk_add_f32 v[88:89], v[92:93], 1.0 op_sel_hi:[1,0]
	v_exp_f32_e32 v95, v90
	v_mul_f32_e32 v90, 0xbfb8aa3b, v91
	v_exp_f32_e32 v101, v90
	global_store_dwordx2 v[106:107], v[96:97], off offset:128 nt
	v_rcp_f32_e32 v89, v89
	v_or_b32_e32 v96, 32, v146
	v_pk_add_f32 v[90:91], v[98:99], 1.0 op_sel_hi:[1,0]
	v_rcp_f32_e32 v88, v88
	s_nop 0
	v_pk_fma_f32 v[88:89], v[88:89], s[12:13], 0.5 op_sel_hi:[1,0,0]
	v_ashrrev_i32_e32 v97, 31, v96
	v_rcp_f32_e32 v91, v91
	v_lshlrev_b64 v[96:97], 10, v[96:97]
	v_rcp_f32_e32 v90, v90
	s_nop 0
	v_pk_fma_f32 v[90:91], v[90:91], s[12:13], 0.5 op_sel_hi:[1,0,0]
	v_cvt_u32_f32_e32 v92, v89
	v_cvt_u32_f32_e32 v93, v88
	v_pk_add_f32 v[88:89], v[94:95], 1.0 op_sel_hi:[1,0]
	v_cvt_u32_f32_e32 v90, v90
	v_cvt_u32_f32_e32 v91, v91
	v_lshlrev_b32_e32 v90, 8, v90
	v_or_b32_e32 v93, v90, v93
	v_lshlrev_b32_e32 v91, 8, v91
	v_or_b32_e32 v92, v91, v92
	v_rcp_f32_e32 v89, v89
	v_mul_f32_e32 v76, 0xbfb8aa3b, v76
	v_rcp_f32_e32 v88, v88
	v_pk_add_f32 v[90:91], v[100:101], 1.0 op_sel_hi:[1,0]
	v_pk_fma_f32 v[88:89], v[88:89], s[12:13], 0.5 op_sel_hi:[1,0,0]
	s_nop 0
	v_cvt_u32_f32_sdwa v98, v88 dst_sel:WORD_1 dst_unused:UNUSED_PAD src0_sel:DWORD
	v_cvt_u32_f32_sdwa v99, v89 dst_sel:WORD_1 dst_unused:UNUSED_PAD src0_sel:DWORD
	v_mul_f32_e32 v72, 0xbfb8aa3b, v72
	v_rcp_f32_e32 v89, v91
	v_exp_f32_e32 v76, v76
	v_rcp_f32_e32 v88, v90
	s_nop 0
	v_pk_fma_f32 v[88:89], v[88:89], s[12:13], 0.5 op_sel_hi:[1,0,0]
	v_or_b32_e32 v90, v92, v99
	v_cvt_u32_f32_sdwa v89, v89 dst_sel:BYTE_3 dst_unused:UNUSED_PAD src0_sel:DWORD
	v_cvt_u32_f32_sdwa v88, v88 dst_sel:BYTE_3 dst_unused:UNUSED_PAD src0_sel:DWORD
	v_or_b32_e32 v91, v93, v98
	v_mul_f32_e32 v74, 0xbfb8aa3b, v74
	v_or_b32_e32 v89, v90, v89
	v_or_b32_e32 v88, v91, v88
	v_lshl_add_u64 v[90:91], s[80:81], 0, v[96:97]
	v_lshl_add_u64 v[90:91], v[90:91], 0, v[144:145]
	global_store_dwordx2 v[90:91], v[88:89], off nt
	v_exp_f32_e32 v88, v85
	v_mul_f32_e32 v85, 0xbfb8aa3b, v86
	v_exp_f32_e32 v86, v85
	v_mul_f32_e32 v85, 0xbfb8aa3b, v87
	v_exp_f32_e32 v92, v85
	v_exp_f32_e32 v85, v80
	v_mul_f32_e32 v80, 0xbfb8aa3b, v81
	v_exp_f32_e32 v89, v80
	v_exp_f32_e32 v87, v82
	v_pk_add_f32 v[80:81], v[84:85], 1.0 op_sel_hi:[1,0]
	v_mul_f32_e32 v82, 0xbfb8aa3b, v83
	v_exp_f32_e32 v93, v82
	v_mul_f32_e32 v69, 0xbfb8aa3b, v69
	v_mul_f32_e32 v68, 0xbfb8aa3b, v68
	v_rcp_f32_e32 v81, v81
	v_mul_f32_e32 v64, 0xbfb8aa3b, v64
	v_pk_add_f32 v[82:83], v[88:89], 1.0 op_sel_hi:[1,0]
	v_rcp_f32_e32 v80, v80
	s_nop 0
	v_pk_fma_f32 v[80:81], v[80:81], s[12:13], 0.5 op_sel_hi:[1,0,0]
	v_exp_f32_e32 v68, v68
	v_rcp_f32_e32 v83, v83
	v_mul_f32_e32 v66, 0xbfb8aa3b, v66
	v_rcp_f32_e32 v82, v82
	s_nop 0
	v_pk_fma_f32 v[82:83], v[82:83], s[12:13], 0.5 op_sel_hi:[1,0,0]
	v_cvt_u32_f32_e32 v84, v81
	v_cvt_u32_f32_e32 v85, v80
	v_pk_add_f32 v[80:81], v[86:87], 1.0 op_sel_hi:[1,0]
	v_cvt_u32_f32_e32 v82, v82
	v_cvt_u32_f32_e32 v83, v83
	v_lshlrev_b32_e32 v82, 8, v82
	v_or_b32_e32 v85, v82, v85
	v_lshlrev_b32_e32 v83, 8, v83
	v_or_b32_e32 v84, v83, v84
	v_rcp_f32_e32 v81, v81
	v_mul_f32_e32 v61, 0xbfb8aa3b, v61
	v_rcp_f32_e32 v80, v80
	v_pk_add_f32 v[82:83], v[92:93], 1.0 op_sel_hi:[1,0]
	v_pk_fma_f32 v[80:81], v[80:81], s[12:13], 0.5 op_sel_hi:[1,0,0]
	s_nop 0
	v_cvt_u32_f32_sdwa v88, v80 dst_sel:WORD_1 dst_unused:UNUSED_PAD src0_sel:DWORD
	v_cvt_u32_f32_sdwa v89, v81 dst_sel:WORD_1 dst_unused:UNUSED_PAD src0_sel:DWORD
	v_mul_f32_e32 v60, 0xbfb8aa3b, v60
	v_rcp_f32_e32 v81, v83
	v_mul_f32_e32 v56, 0xbfb8aa3b, v56
	v_rcp_f32_e32 v80, v82
	s_nop 0
	v_pk_fma_f32 v[80:81], v[80:81], s[12:13], 0.5 op_sel_hi:[1,0,0]
	v_or_b32_e32 v82, v84, v89
	v_cvt_u32_f32_sdwa v81, v81 dst_sel:BYTE_3 dst_unused:UNUSED_PAD src0_sel:DWORD
	v_cvt_u32_f32_sdwa v80, v80 dst_sel:BYTE_3 dst_unused:UNUSED_PAD src0_sel:DWORD
	v_or_b32_e32 v83, v85, v88
	v_exp_f32_e32 v60, v60
	v_or_b32_e32 v81, v82, v81
	v_exp_f32_e32 v82, v77
	v_mul_f32_e32 v77, 0xbfb8aa3b, v78
	v_exp_f32_e32 v78, v77
	v_mul_f32_e32 v77, 0xbfb8aa3b, v79
	v_exp_f32_e32 v84, v77
	v_exp_f32_e32 v77, v72
	v_mul_f32_e32 v72, 0xbfb8aa3b, v73
	v_or_b32_e32 v80, v83, v80
	v_exp_f32_e32 v83, v72
	v_pk_add_f32 v[72:73], v[76:77], 1.0 op_sel_hi:[1,0]
	v_exp_f32_e32 v79, v74
	v_mul_f32_e32 v74, 0xbfb8aa3b, v75
	v_exp_f32_e32 v85, v74
	global_store_dwordx2 v[90:91], v[80:81], off offset:128 nt
	v_rcp_f32_e32 v73, v73
	v_or_b32_e32 v80, 48, v146
	v_pk_add_f32 v[74:75], v[82:83], 1.0 op_sel_hi:[1,0]
	v_rcp_f32_e32 v72, v72
	s_nop 0
	v_pk_fma_f32 v[72:73], v[72:73], s[12:13], 0.5 op_sel_hi:[1,0,0]
	v_ashrrev_i32_e32 v81, 31, v80
	v_rcp_f32_e32 v75, v75
	v_lshlrev_b64 v[80:81], 10, v[80:81]
	v_rcp_f32_e32 v74, v74
	s_nop 0
	v_pk_fma_f32 v[74:75], v[74:75], s[12:13], 0.5 op_sel_hi:[1,0,0]
	v_cvt_u32_f32_e32 v76, v73
	v_cvt_u32_f32_e32 v77, v72
	v_pk_add_f32 v[72:73], v[78:79], 1.0 op_sel_hi:[1,0]
	v_cvt_u32_f32_e32 v74, v74
	v_cvt_u32_f32_e32 v75, v75
	v_lshlrev_b32_e32 v74, 8, v74
	v_or_b32_e32 v77, v74, v77
	v_lshlrev_b32_e32 v75, 8, v75
	v_or_b32_e32 v76, v75, v76
	v_rcp_f32_e32 v73, v73
	v_mul_f32_e32 v58, 0xbfb8aa3b, v58
	v_rcp_f32_e32 v72, v72
	v_pk_add_f32 v[74:75], v[84:85], 1.0 op_sel_hi:[1,0]
	v_pk_fma_f32 v[72:73], v[72:73], s[12:13], 0.5 op_sel_hi:[1,0,0]
	s_nop 0
	v_cvt_u32_f32_sdwa v82, v72 dst_sel:WORD_1 dst_unused:UNUSED_PAD src0_sel:DWORD
	v_cvt_u32_f32_sdwa v83, v73 dst_sel:WORD_1 dst_unused:UNUSED_PAD src0_sel:DWORD
	v_mul_f32_e32 v53, 0xbfb8aa3b, v53
	v_rcp_f32_e32 v73, v75
	v_mul_f32_e32 v52, 0xbfb8aa3b, v52
	v_rcp_f32_e32 v72, v74
	s_nop 0
	v_pk_fma_f32 v[72:73], v[72:73], s[12:13], 0.5 op_sel_hi:[1,0,0]
	v_or_b32_e32 v74, v76, v83
	v_cvt_u32_f32_sdwa v73, v73 dst_sel:BYTE_3 dst_unused:UNUSED_PAD src0_sel:DWORD
	v_cvt_u32_f32_sdwa v72, v72 dst_sel:BYTE_3 dst_unused:UNUSED_PAD src0_sel:DWORD
	v_or_b32_e32 v75, v77, v82
	v_mul_f32_e32 v48, 0xbfb8aa3b, v48
	v_or_b32_e32 v73, v74, v73
	v_or_b32_e32 v72, v75, v72
	v_lshl_add_u64 v[74:75], s[80:81], 0, v[80:81]
	v_lshl_add_u64 v[74:75], v[74:75], 0, v[144:145]
	global_store_dwordx2 v[74:75], v[72:73], off nt
	v_exp_f32_e32 v72, v69
	v_mul_f32_e32 v69, 0xbfb8aa3b, v70
	v_exp_f32_e32 v70, v69
	v_mul_f32_e32 v69, 0xbfb8aa3b, v71
	v_exp_f32_e32 v76, v69
	v_exp_f32_e32 v69, v64
	v_mul_f32_e32 v64, 0xbfb8aa3b, v65
	v_exp_f32_e32 v73, v64
	v_exp_f32_e32 v71, v66
	v_pk_add_f32 v[64:65], v[68:69], 1.0 op_sel_hi:[1,0]
	v_mul_f32_e32 v66, 0xbfb8aa3b, v67
	v_exp_f32_e32 v77, v66
	v_exp_f32_e32 v52, v52
	v_mul_f32_e32 v50, 0xbfb8aa3b, v50
	v_rcp_f32_e32 v65, v65
	v_mul_f32_e32 v45, 0xbfb8aa3b, v45
	v_pk_add_f32 v[66:67], v[72:73], 1.0 op_sel_hi:[1,0]
	v_rcp_f32_e32 v64, v64
	s_nop 0
	v_pk_fma_f32 v[64:65], v[64:65], s[12:13], 0.5 op_sel_hi:[1,0,0]
	v_mul_f32_e32 v44, 0xbfb8aa3b, v44
	v_rcp_f32_e32 v67, v67
	v_mul_f32_e32 v40, 0xbfb8aa3b, v40
	v_rcp_f32_e32 v66, v66
	s_nop 0
	v_pk_fma_f32 v[66:67], v[66:67], s[12:13], 0.5 op_sel_hi:[1,0,0]
	v_cvt_u32_f32_e32 v68, v65
	v_cvt_u32_f32_e32 v69, v64
	v_pk_add_f32 v[64:65], v[70:71], 1.0 op_sel_hi:[1,0]
	v_cvt_u32_f32_e32 v66, v66
	v_cvt_u32_f32_e32 v67, v67
	v_lshlrev_b32_e32 v66, 8, v66
	v_or_b32_e32 v69, v66, v69
	v_lshlrev_b32_e32 v67, 8, v67
	v_or_b32_e32 v68, v67, v68
	v_rcp_f32_e32 v65, v65
	v_exp_f32_e32 v44, v44
	v_rcp_f32_e32 v64, v64
	v_pk_add_f32 v[66:67], v[76:77], 1.0 op_sel_hi:[1,0]
	v_pk_fma_f32 v[64:65], v[64:65], s[12:13], 0.5 op_sel_hi:[1,0,0]
	s_nop 0
	v_cvt_u32_f32_sdwa v72, v64 dst_sel:WORD_1 dst_unused:UNUSED_PAD src0_sel:DWORD
	v_cvt_u32_f32_sdwa v73, v65 dst_sel:WORD_1 dst_unused:UNUSED_PAD src0_sel:DWORD
	v_mul_f32_e32 v42, 0xbfb8aa3b, v42
	v_rcp_f32_e32 v65, v67
	v_mul_f32_e32 v37, 0xbfb8aa3b, v37
	v_rcp_f32_e32 v64, v66
	s_nop 0
	v_pk_fma_f32 v[64:65], v[64:65], s[12:13], 0.5 op_sel_hi:[1,0,0]
	v_or_b32_e32 v66, v68, v73
	v_cvt_u32_f32_sdwa v65, v65 dst_sel:BYTE_3 dst_unused:UNUSED_PAD src0_sel:DWORD
	v_cvt_u32_f32_sdwa v64, v64 dst_sel:BYTE_3 dst_unused:UNUSED_PAD src0_sel:DWORD
	v_or_b32_e32 v67, v69, v72
	v_mul_f32_e32 v36, 0xbfb8aa3b, v36
	v_or_b32_e32 v65, v66, v65
	v_exp_f32_e32 v66, v61
	v_mul_f32_e32 v61, 0xbfb8aa3b, v62
	v_exp_f32_e32 v62, v61
	v_mul_f32_e32 v61, 0xbfb8aa3b, v63
	v_exp_f32_e32 v68, v61
	v_exp_f32_e32 v61, v56
	v_mul_f32_e32 v56, 0xbfb8aa3b, v57
	v_or_b32_e32 v64, v67, v64
	v_exp_f32_e32 v67, v56
	v_pk_add_f32 v[56:57], v[60:61], 1.0 op_sel_hi:[1,0]
	v_exp_f32_e32 v63, v58
	v_mul_f32_e32 v58, 0xbfb8aa3b, v59
	v_exp_f32_e32 v69, v58
	global_store_dwordx2 v[74:75], v[64:65], off offset:128 nt
	v_rcp_f32_e32 v57, v57
	v_add_u32_e32 v64, 0x80, v146
	v_pk_add_f32 v[58:59], v[66:67], 1.0 op_sel_hi:[1,0]
	v_rcp_f32_e32 v56, v56
	s_nop 0
	v_pk_fma_f32 v[56:57], v[56:57], s[12:13], 0.5 op_sel_hi:[1,0,0]
	v_ashrrev_i32_e32 v65, 31, v64
	v_rcp_f32_e32 v59, v59
	v_lshlrev_b64 v[64:65], 10, v[64:65]
	v_rcp_f32_e32 v58, v58
	s_nop 0
	v_pk_fma_f32 v[58:59], v[58:59], s[12:13], 0.5 op_sel_hi:[1,0,0]
	v_cvt_u32_f32_e32 v60, v57
	v_cvt_u32_f32_e32 v61, v56
	v_pk_add_f32 v[56:57], v[62:63], 1.0 op_sel_hi:[1,0]
	v_cvt_u32_f32_e32 v58, v58
	v_cvt_u32_f32_e32 v59, v59
	v_lshlrev_b32_e32 v58, 8, v58
	v_or_b32_e32 v61, v58, v61
	v_lshlrev_b32_e32 v59, 8, v59
	v_or_b32_e32 v60, v59, v60
	v_rcp_f32_e32 v57, v57
	v_mul_f32_e32 v32, 0xbfb8aa3b, v32
	v_rcp_f32_e32 v56, v56
	v_pk_add_f32 v[58:59], v[68:69], 1.0 op_sel_hi:[1,0]
	v_pk_fma_f32 v[56:57], v[56:57], s[12:13], 0.5 op_sel_hi:[1,0,0]
	s_nop 0
	v_cvt_u32_f32_sdwa v66, v56 dst_sel:WORD_1 dst_unused:UNUSED_PAD src0_sel:DWORD
	v_cvt_u32_f32_sdwa v67, v57 dst_sel:WORD_1 dst_unused:UNUSED_PAD src0_sel:DWORD
	v_exp_f32_e32 v36, v36
	v_rcp_f32_e32 v57, v59
	v_mul_f32_e32 v34, 0xbfb8aa3b, v34
	v_rcp_f32_e32 v56, v58
	s_nop 0
	v_pk_fma_f32 v[56:57], v[56:57], s[12:13], 0.5 op_sel_hi:[1,0,0]
	v_or_b32_e32 v58, v60, v67
	v_cvt_u32_f32_sdwa v57, v57 dst_sel:BYTE_3 dst_unused:UNUSED_PAD src0_sel:DWORD
	v_cvt_u32_f32_sdwa v56, v56 dst_sel:BYTE_3 dst_unused:UNUSED_PAD src0_sel:DWORD
	v_or_b32_e32 v59, v61, v66
	v_mul_f32_e32 v29, 0xbfb8aa3b, v29
	v_or_b32_e32 v57, v58, v57
	v_or_b32_e32 v56, v59, v56
	v_lshl_add_u64 v[58:59], s[80:81], 0, v[64:65]
	v_lshl_add_u64 v[58:59], v[58:59], 0, v[144:145]
	global_store_dwordx2 v[58:59], v[56:57], off nt
	v_exp_f32_e32 v56, v53
	v_mul_f32_e32 v53, 0xbfb8aa3b, v54
	v_exp_f32_e32 v54, v53
	v_mul_f32_e32 v53, 0xbfb8aa3b, v55
	v_exp_f32_e32 v60, v53
	v_exp_f32_e32 v53, v48
	v_mul_f32_e32 v48, 0xbfb8aa3b, v49
	v_exp_f32_e32 v57, v48
	v_exp_f32_e32 v55, v50
	v_pk_add_f32 v[48:49], v[52:53], 1.0 op_sel_hi:[1,0]
	v_mul_f32_e32 v50, 0xbfb8aa3b, v51
	v_exp_f32_e32 v61, v50
	v_mul_f32_e32 v28, 0xbfb8aa3b, v28
	v_mul_f32_e32 v24, 0xbfb8aa3b, v24
	v_rcp_f32_e32 v49, v49
	v_exp_f32_e32 v28, v28
	v_pk_add_f32 v[50:51], v[56:57], 1.0 op_sel_hi:[1,0]
	v_rcp_f32_e32 v48, v48
	s_nop 0
	v_pk_fma_f32 v[48:49], v[48:49], s[12:13], 0.5 op_sel_hi:[1,0,0]
	v_mul_f32_e32 v26, 0xbfb8aa3b, v26
	v_rcp_f32_e32 v51, v51
	v_mul_f32_e32 v21, 0xbfb8aa3b, v21
	v_rcp_f32_e32 v50, v50
	s_nop 0
	v_pk_fma_f32 v[50:51], v[50:51], s[12:13], 0.5 op_sel_hi:[1,0,0]
	v_cvt_u32_f32_e32 v52, v49
	v_cvt_u32_f32_e32 v53, v48
	v_pk_add_f32 v[48:49], v[54:55], 1.0 op_sel_hi:[1,0]
	v_cvt_u32_f32_e32 v50, v50
	v_cvt_u32_f32_e32 v51, v51
	v_lshlrev_b32_e32 v50, 8, v50
	v_or_b32_e32 v53, v50, v53
	v_lshlrev_b32_e32 v51, 8, v51
	v_or_b32_e32 v52, v51, v52
	v_rcp_f32_e32 v49, v49
	v_mul_f32_e32 v20, 0xbfb8aa3b, v20
	v_rcp_f32_e32 v48, v48
	v_pk_add_f32 v[50:51], v[60:61], 1.0 op_sel_hi:[1,0]
	v_pk_fma_f32 v[48:49], v[48:49], s[12:13], 0.5 op_sel_hi:[1,0,0]
	s_nop 0
	v_cvt_u32_f32_sdwa v56, v48 dst_sel:WORD_1 dst_unused:UNUSED_PAD src0_sel:DWORD
	v_cvt_u32_f32_sdwa v57, v49 dst_sel:WORD_1 dst_unused:UNUSED_PAD src0_sel:DWORD
	v_mul_f32_e32 v16, 0xbfb8aa3b, v16
	v_rcp_f32_e32 v49, v51
	v_exp_f32_e32 v20, v20
	v_rcp_f32_e32 v48, v50
	s_nop 0
	v_pk_fma_f32 v[48:49], v[48:49], s[12:13], 0.5 op_sel_hi:[1,0,0]
	v_or_b32_e32 v50, v52, v57
	v_cvt_u32_f32_sdwa v49, v49 dst_sel:BYTE_3 dst_unused:UNUSED_PAD src0_sel:DWORD
	v_cvt_u32_f32_sdwa v48, v48 dst_sel:BYTE_3 dst_unused:UNUSED_PAD src0_sel:DWORD
	v_or_b32_e32 v51, v53, v56
	v_mul_f32_e32 v18, 0xbfb8aa3b, v18
	v_or_b32_e32 v49, v50, v49
	v_exp_f32_e32 v50, v45
	v_mul_f32_e32 v45, 0xbfb8aa3b, v46
	v_exp_f32_e32 v46, v45
	v_mul_f32_e32 v45, 0xbfb8aa3b, v47
	v_exp_f32_e32 v52, v45
	v_exp_f32_e32 v45, v40
	v_mul_f32_e32 v40, 0xbfb8aa3b, v41
	v_or_b32_e32 v48, v51, v48
	v_exp_f32_e32 v51, v40
	v_pk_add_f32 v[40:41], v[44:45], 1.0 op_sel_hi:[1,0]
	v_exp_f32_e32 v47, v42
	v_mul_f32_e32 v42, 0xbfb8aa3b, v43
	v_exp_f32_e32 v53, v42
	global_store_dwordx2 v[58:59], v[48:49], off offset:128 nt
	v_rcp_f32_e32 v41, v41
	v_add_u32_e32 v48, 0x90, v146
	v_pk_add_f32 v[42:43], v[50:51], 1.0 op_sel_hi:[1,0]
	v_rcp_f32_e32 v40, v40
	s_nop 0
	v_pk_fma_f32 v[40:41], v[40:41], s[12:13], 0.5 op_sel_hi:[1,0,0]
	v_ashrrev_i32_e32 v49, 31, v48
	v_rcp_f32_e32 v43, v43
	v_lshlrev_b64 v[48:49], 10, v[48:49]
	v_rcp_f32_e32 v42, v42
	s_nop 0
	v_pk_fma_f32 v[42:43], v[42:43], s[12:13], 0.5 op_sel_hi:[1,0,0]
	v_cvt_u32_f32_e32 v44, v41
	v_cvt_u32_f32_e32 v45, v40
	v_pk_add_f32 v[40:41], v[46:47], 1.0 op_sel_hi:[1,0]
	v_cvt_u32_f32_e32 v42, v42
	v_cvt_u32_f32_e32 v43, v43
	v_lshlrev_b32_e32 v42, 8, v42
	v_or_b32_e32 v45, v42, v45
	v_lshlrev_b32_e32 v43, 8, v43
	v_or_b32_e32 v44, v43, v44
	v_rcp_f32_e32 v41, v41
	v_mul_f32_e32 v13, 0xbfb8aa3b, v13
	v_rcp_f32_e32 v40, v40
	v_pk_add_f32 v[42:43], v[52:53], 1.0 op_sel_hi:[1,0]
	v_pk_fma_f32 v[40:41], v[40:41], s[12:13], 0.5 op_sel_hi:[1,0,0]
	s_nop 0
	v_cvt_u32_f32_sdwa v50, v40 dst_sel:WORD_1 dst_unused:UNUSED_PAD src0_sel:DWORD
	v_cvt_u32_f32_sdwa v51, v41 dst_sel:WORD_1 dst_unused:UNUSED_PAD src0_sel:DWORD
	v_mul_f32_e32 v12, 0xbfb8aa3b, v12
	v_rcp_f32_e32 v41, v43
	v_mul_f32_e32 v8, 0xbfb8aa3b, v8
	v_rcp_f32_e32 v40, v42
	s_nop 0
	v_pk_fma_f32 v[40:41], v[40:41], s[12:13], 0.5 op_sel_hi:[1,0,0]
	v_or_b32_e32 v42, v44, v51
	v_cvt_u32_f32_sdwa v41, v41 dst_sel:BYTE_3 dst_unused:UNUSED_PAD src0_sel:DWORD
	v_cvt_u32_f32_sdwa v40, v40 dst_sel:BYTE_3 dst_unused:UNUSED_PAD src0_sel:DWORD
	v_or_b32_e32 v43, v45, v50
	v_exp_f32_e32 v12, v12
	v_or_b32_e32 v41, v42, v41
	v_or_b32_e32 v40, v43, v40
	v_lshl_add_u64 v[42:43], s[80:81], 0, v[48:49]
	v_lshl_add_u64 v[42:43], v[42:43], 0, v[144:145]
	global_store_dwordx2 v[42:43], v[40:41], off nt
	v_exp_f32_e32 v40, v37
	v_mul_f32_e32 v37, 0xbfb8aa3b, v38
	v_exp_f32_e32 v38, v37
	v_mul_f32_e32 v37, 0xbfb8aa3b, v39
	v_exp_f32_e32 v44, v37
	v_exp_f32_e32 v37, v32
	v_mul_f32_e32 v32, 0xbfb8aa3b, v33
	v_exp_f32_e32 v41, v32
	v_exp_f32_e32 v39, v34
	v_pk_add_f32 v[32:33], v[36:37], 1.0 op_sel_hi:[1,0]
	v_mul_f32_e32 v34, 0xbfb8aa3b, v35
	v_exp_f32_e32 v45, v34
	v_mul_f32_e32 v10, 0xbfb8aa3b, v10
	v_mul_f32_e32 v5, 0xbfb8aa3b, v5
	v_rcp_f32_e32 v33, v33
	v_mul_f32_e32 v4, 0xbfb8aa3b, v4
	v_pk_add_f32 v[34:35], v[40:41], 1.0 op_sel_hi:[1,0]
	v_rcp_f32_e32 v32, v32
	s_nop 0
	v_pk_fma_f32 v[32:33], v[32:33], s[12:13], 0.5 op_sel_hi:[1,0,0]
	v_mul_f32_e32 v0, 0xbfb8aa3b, v0
	v_rcp_f32_e32 v35, v35
	v_exp_f32_e32 v4, v4
	v_rcp_f32_e32 v34, v34
	s_nop 0
	v_pk_fma_f32 v[34:35], v[34:35], s[12:13], 0.5 op_sel_hi:[1,0,0]
	v_cvt_u32_f32_e32 v36, v33
	v_cvt_u32_f32_e32 v37, v32
	v_pk_add_f32 v[32:33], v[38:39], 1.0 op_sel_hi:[1,0]
	v_cvt_u32_f32_e32 v34, v34
	v_cvt_u32_f32_e32 v35, v35
	v_lshlrev_b32_e32 v34, 8, v34
	v_or_b32_e32 v37, v34, v37
	v_lshlrev_b32_e32 v35, 8, v35
	v_or_b32_e32 v36, v35, v36
	v_rcp_f32_e32 v33, v33
	v_mul_f32_e32 v2, 0xbfb8aa3b, v2
	v_rcp_f32_e32 v32, v32
	v_pk_add_f32 v[34:35], v[44:45], 1.0 op_sel_hi:[1,0]
	v_pk_fma_f32 v[32:33], v[32:33], s[12:13], 0.5 op_sel_hi:[1,0,0]
	s_nop 0
	v_cvt_u32_f32_sdwa v40, v32 dst_sel:WORD_1 dst_unused:UNUSED_PAD src0_sel:DWORD
	v_cvt_u32_f32_sdwa v41, v33 dst_sel:WORD_1 dst_unused:UNUSED_PAD src0_sel:DWORD
	v_rcp_f32_e32 v33, v35
	v_rcp_f32_e32 v32, v34
	s_nop 0
	v_pk_fma_f32 v[32:33], v[32:33], s[12:13], 0.5 op_sel_hi:[1,0,0]
	v_or_b32_e32 v34, v36, v41
	v_cvt_u32_f32_sdwa v33, v33 dst_sel:BYTE_3 dst_unused:UNUSED_PAD src0_sel:DWORD
	v_cvt_u32_f32_sdwa v32, v32 dst_sel:BYTE_3 dst_unused:UNUSED_PAD src0_sel:DWORD
	v_or_b32_e32 v35, v37, v40
	v_or_b32_e32 v33, v34, v33
	v_exp_f32_e32 v34, v29
	v_mul_f32_e32 v29, 0xbfb8aa3b, v30
	v_exp_f32_e32 v30, v29
	v_mul_f32_e32 v29, 0xbfb8aa3b, v31
	v_exp_f32_e32 v36, v29
	v_exp_f32_e32 v29, v24
	v_mul_f32_e32 v24, 0xbfb8aa3b, v25
	v_or_b32_e32 v32, v35, v32
	v_exp_f32_e32 v35, v24
	v_pk_add_f32 v[24:25], v[28:29], 1.0 op_sel_hi:[1,0]
	v_exp_f32_e32 v31, v26
	v_mul_f32_e32 v26, 0xbfb8aa3b, v27
	v_exp_f32_e32 v37, v26
	global_store_dwordx2 v[42:43], v[32:33], off offset:128 nt
	v_rcp_f32_e32 v25, v25
	v_add_u32_e32 v32, 0xa0, v146
	v_pk_add_f32 v[26:27], v[34:35], 1.0 op_sel_hi:[1,0]
	v_rcp_f32_e32 v24, v24
	s_nop 0
	v_pk_fma_f32 v[24:25], v[24:25], s[12:13], 0.5 op_sel_hi:[1,0,0]
	v_ashrrev_i32_e32 v33, 31, v32
	v_rcp_f32_e32 v27, v27
	v_lshlrev_b64 v[32:33], 10, v[32:33]
	v_rcp_f32_e32 v26, v26
	s_nop 0
	v_pk_fma_f32 v[26:27], v[26:27], s[12:13], 0.5 op_sel_hi:[1,0,0]
	v_cvt_u32_f32_e32 v28, v25
	v_cvt_u32_f32_e32 v29, v24
	v_pk_add_f32 v[24:25], v[30:31], 1.0 op_sel_hi:[1,0]
	v_cvt_u32_f32_e32 v26, v26
	v_cvt_u32_f32_e32 v27, v27
	v_lshlrev_b32_e32 v26, 8, v26
	v_or_b32_e32 v29, v26, v29
	v_lshlrev_b32_e32 v27, 8, v27
	v_or_b32_e32 v28, v27, v28
	v_rcp_f32_e32 v25, v25
	v_rcp_f32_e32 v24, v24
	v_pk_add_f32 v[26:27], v[36:37], 1.0 op_sel_hi:[1,0]
	v_pk_fma_f32 v[24:25], v[24:25], s[12:13], 0.5 op_sel_hi:[1,0,0]
	s_nop 0
	v_cvt_u32_f32_sdwa v34, v24 dst_sel:WORD_1 dst_unused:UNUSED_PAD src0_sel:DWORD
	v_cvt_u32_f32_sdwa v35, v25 dst_sel:WORD_1 dst_unused:UNUSED_PAD src0_sel:DWORD
	v_rcp_f32_e32 v25, v27
	v_rcp_f32_e32 v24, v26
	s_nop 0
	v_pk_fma_f32 v[24:25], v[24:25], s[12:13], 0.5 op_sel_hi:[1,0,0]
	v_or_b32_e32 v26, v28, v35
	v_cvt_u32_f32_sdwa v25, v25 dst_sel:BYTE_3 dst_unused:UNUSED_PAD src0_sel:DWORD
	v_cvt_u32_f32_sdwa v24, v24 dst_sel:BYTE_3 dst_unused:UNUSED_PAD src0_sel:DWORD
	v_or_b32_e32 v27, v29, v34
	v_or_b32_e32 v25, v26, v25
	v_or_b32_e32 v24, v27, v24
	v_lshl_add_u64 v[26:27], s[80:81], 0, v[32:33]
	v_lshl_add_u64 v[26:27], v[26:27], 0, v[144:145]
	global_store_dwordx2 v[26:27], v[24:25], off nt
	v_exp_f32_e32 v24, v21
	v_mul_f32_e32 v21, 0xbfb8aa3b, v22
	v_exp_f32_e32 v22, v21
	v_mul_f32_e32 v21, 0xbfb8aa3b, v23
	v_exp_f32_e32 v28, v21
	v_exp_f32_e32 v21, v16
	v_mul_f32_e32 v16, 0xbfb8aa3b, v17
	v_exp_f32_e32 v25, v16
	v_exp_f32_e32 v23, v18
	v_pk_add_f32 v[16:17], v[20:21], 1.0 op_sel_hi:[1,0]
	v_mul_f32_e32 v18, 0xbfb8aa3b, v19
	v_exp_f32_e32 v29, v18
	v_rcp_f32_e32 v17, v17
	v_pk_add_f32 v[18:19], v[24:25], 1.0 op_sel_hi:[1,0]
	v_rcp_f32_e32 v16, v16
	s_nop 0
	v_pk_fma_f32 v[16:17], v[16:17], s[12:13], 0.5 op_sel_hi:[1,0,0]
	v_rcp_f32_e32 v19, v19
	v_rcp_f32_e32 v18, v18
	s_nop 0
	v_pk_fma_f32 v[18:19], v[18:19], s[12:13], 0.5 op_sel_hi:[1,0,0]
	v_cvt_u32_f32_e32 v20, v17
	v_cvt_u32_f32_e32 v21, v16
	v_pk_add_f32 v[16:17], v[22:23], 1.0 op_sel_hi:[1,0]
	v_cvt_u32_f32_e32 v18, v18
	v_cvt_u32_f32_e32 v19, v19
	v_lshlrev_b32_e32 v18, 8, v18
	v_or_b32_e32 v21, v18, v21
	v_lshlrev_b32_e32 v19, 8, v19
	v_or_b32_e32 v20, v19, v20
	v_rcp_f32_e32 v17, v17
	v_rcp_f32_e32 v16, v16
	v_pk_add_f32 v[18:19], v[28:29], 1.0 op_sel_hi:[1,0]
	v_pk_fma_f32 v[16:17], v[16:17], s[12:13], 0.5 op_sel_hi:[1,0,0]
	s_nop 0
	v_cvt_u32_f32_sdwa v24, v16 dst_sel:WORD_1 dst_unused:UNUSED_PAD src0_sel:DWORD
	v_cvt_u32_f32_sdwa v25, v17 dst_sel:WORD_1 dst_unused:UNUSED_PAD src0_sel:DWORD
	v_rcp_f32_e32 v17, v19
	v_rcp_f32_e32 v16, v18
	s_nop 0
	v_pk_fma_f32 v[16:17], v[16:17], s[12:13], 0.5 op_sel_hi:[1,0,0]
	v_or_b32_e32 v18, v20, v25
	v_cvt_u32_f32_sdwa v17, v17 dst_sel:BYTE_3 dst_unused:UNUSED_PAD src0_sel:DWORD
	v_cvt_u32_f32_sdwa v16, v16 dst_sel:BYTE_3 dst_unused:UNUSED_PAD src0_sel:DWORD
	v_or_b32_e32 v19, v21, v24
	v_or_b32_e32 v17, v18, v17
	v_exp_f32_e32 v18, v13
	v_mul_f32_e32 v13, 0xbfb8aa3b, v14
	v_exp_f32_e32 v14, v13
	v_mul_f32_e32 v13, 0xbfb8aa3b, v15
	v_exp_f32_e32 v20, v13
	v_exp_f32_e32 v13, v8
	v_mul_f32_e32 v8, 0xbfb8aa3b, v9
	v_or_b32_e32 v16, v19, v16
	v_exp_f32_e32 v19, v8
	v_pk_add_f32 v[8:9], v[12:13], 1.0 op_sel_hi:[1,0]
	v_exp_f32_e32 v15, v10
	v_mul_f32_e32 v10, 0xbfb8aa3b, v11
	v_exp_f32_e32 v21, v10
	global_store_dwordx2 v[26:27], v[16:17], off offset:128 nt
	v_rcp_f32_e32 v9, v9
	v_add_u32_e32 v16, 0xb0, v146
	v_pk_add_f32 v[10:11], v[18:19], 1.0 op_sel_hi:[1,0]
	v_rcp_f32_e32 v8, v8
	s_nop 0
	v_pk_fma_f32 v[8:9], v[8:9], s[12:13], 0.5 op_sel_hi:[1,0,0]
	v_ashrrev_i32_e32 v17, 31, v16
	v_rcp_f32_e32 v11, v11
	v_lshlrev_b64 v[16:17], 10, v[16:17]
	v_rcp_f32_e32 v10, v10
	s_nop 0
	v_pk_fma_f32 v[10:11], v[10:11], s[12:13], 0.5 op_sel_hi:[1,0,0]
	v_cvt_u32_f32_e32 v12, v9
	v_cvt_u32_f32_e32 v13, v8
	v_pk_add_f32 v[8:9], v[14:15], 1.0 op_sel_hi:[1,0]
	v_cvt_u32_f32_e32 v10, v10
	v_cvt_u32_f32_e32 v11, v11
	v_lshlrev_b32_e32 v10, 8, v10
	v_or_b32_e32 v13, v10, v13
	v_lshlrev_b32_e32 v11, 8, v11
	v_or_b32_e32 v12, v11, v12
	v_rcp_f32_e32 v9, v9
	v_rcp_f32_e32 v8, v8
	v_pk_add_f32 v[10:11], v[20:21], 1.0 op_sel_hi:[1,0]
	v_pk_fma_f32 v[8:9], v[8:9], s[12:13], 0.5 op_sel_hi:[1,0,0]
	s_nop 0
	v_cvt_u32_f32_sdwa v18, v8 dst_sel:WORD_1 dst_unused:UNUSED_PAD src0_sel:DWORD
	v_cvt_u32_f32_sdwa v19, v9 dst_sel:WORD_1 dst_unused:UNUSED_PAD src0_sel:DWORD
	v_rcp_f32_e32 v9, v11
	v_rcp_f32_e32 v8, v10
	s_nop 0
	v_pk_fma_f32 v[8:9], v[8:9], s[12:13], 0.5 op_sel_hi:[1,0,0]
	v_or_b32_e32 v10, v12, v19
	v_cvt_u32_f32_sdwa v9, v9 dst_sel:BYTE_3 dst_unused:UNUSED_PAD src0_sel:DWORD
	v_cvt_u32_f32_sdwa v8, v8 dst_sel:BYTE_3 dst_unused:UNUSED_PAD src0_sel:DWORD
	v_or_b32_e32 v11, v13, v18
	v_or_b32_e32 v9, v10, v9
	v_or_b32_e32 v8, v11, v8
	v_lshl_add_u64 v[10:11], s[80:81], 0, v[16:17]
	v_lshl_add_u64 v[10:11], v[10:11], 0, v[144:145]
	global_store_dwordx2 v[10:11], v[8:9], off nt
	v_exp_f32_e32 v8, v5
	v_mul_f32_e32 v5, 0xbfb8aa3b, v6
	v_exp_f32_e32 v6, v5
	v_mul_f32_e32 v5, 0xbfb8aa3b, v7
	v_exp_f32_e32 v12, v5
	v_exp_f32_e32 v5, v0
	v_mul_f32_e32 v0, 0xbfb8aa3b, v1
	v_exp_f32_e32 v9, v0
	v_exp_f32_e32 v7, v2
	v_pk_add_f32 v[0:1], v[4:5], 1.0 op_sel_hi:[1,0]
	v_mul_f32_e32 v2, 0xbfb8aa3b, v3
	v_exp_f32_e32 v13, v2
	v_rcp_f32_e32 v1, v1
	v_pk_add_f32 v[2:3], v[8:9], 1.0 op_sel_hi:[1,0]
	v_rcp_f32_e32 v0, v0
	s_nop 0
	v_pk_fma_f32 v[0:1], v[0:1], s[12:13], 0.5 op_sel_hi:[1,0,0]
	v_rcp_f32_e32 v3, v3
	v_rcp_f32_e32 v2, v2
	s_nop 0
	v_pk_fma_f32 v[2:3], v[2:3], s[12:13], 0.5 op_sel_hi:[1,0,0]
	v_cvt_u32_f32_e32 v4, v1
	v_cvt_u32_f32_e32 v5, v0
	v_pk_add_f32 v[0:1], v[6:7], 1.0 op_sel_hi:[1,0]
	v_cvt_u32_f32_e32 v2, v2
	v_cvt_u32_f32_e32 v3, v3
	v_lshlrev_b32_e32 v2, 8, v2
	v_or_b32_e32 v5, v2, v5
	v_lshlrev_b32_e32 v3, 8, v3
	v_or_b32_e32 v4, v3, v4
	v_rcp_f32_e32 v1, v1
	v_rcp_f32_e32 v0, v0
	v_pk_add_f32 v[2:3], v[12:13], 1.0 op_sel_hi:[1,0]
	v_pk_fma_f32 v[0:1], v[0:1], s[12:13], 0.5 op_sel_hi:[1,0,0]
	s_nop 0
	v_cvt_u32_f32_sdwa v8, v0 dst_sel:WORD_1 dst_unused:UNUSED_PAD src0_sel:DWORD
	v_cvt_u32_f32_sdwa v9, v1 dst_sel:WORD_1 dst_unused:UNUSED_PAD src0_sel:DWORD
	v_rcp_f32_e32 v1, v3
	s_mov_b64 s[4:5], -1
	v_rcp_f32_e32 v0, v2
	s_nop 0
	v_pk_fma_f32 v[0:1], v[0:1], s[12:13], 0.5 op_sel_hi:[1,0,0]
	v_or_b32_e32 v2, v4, v9
	v_cvt_u32_f32_sdwa v1, v1 dst_sel:BYTE_3 dst_unused:UNUSED_PAD src0_sel:DWORD
	v_cvt_u32_f32_sdwa v0, v0 dst_sel:BYTE_3 dst_unused:UNUSED_PAD src0_sel:DWORD
	v_or_b32_e32 v3, v5, v8
	s_andn2_b64 vcc, exec, s[6:7]
	v_or_b32_e32 v1, v2, v1
	v_or_b32_e32 v0, v3, v0
	global_store_dwordx2 v[10:11], v[0:1], off offset:128 nt
	s_cbranch_vccnz .LBB0_1089
	s_andn2_b64 vcc, exec, s[0:1]
	s_cbranch_vccnz .LBB0_1088
	s_barrier
	s_branch .LBB0_1088

.LBB0_1556:
	s_lshl_b32 s4, s20, 8
	v_add_u32_e32 v144, s4, v146
	v_ashrrev_i32_e32 v145, 31, v144
	v_lshl_or_b32 v160, s40, 8, v155
	v_lshlrev_b64 v[144:145], 11, v[144:145]
	v_ashrrev_i32_e32 v161, 31, v160
	v_lshl_add_u64 v[162:163], s[86:87], 0, v[144:145]
	v_lshlrev_b64 v[144:145], 1, v[160:161]
	v_lshl_add_u64 v[160:161], v[162:163], 0, v[144:145]
	v_cvt_pk_bf16_f32 v124, v124, v125
	v_cvt_pk_bf16_f32 v125, v126, v127
	v_cvt_pk_bf16_f32 v126, v120, v121
	v_cvt_pk_bf16_f32 v127, v122, v123
	global_store_dwordx4 v[160:161], v[124:127], off nt
	v_cvt_pk_bf16_f32 v112, v112, v113
	v_cvt_pk_bf16_f32 v113, v114, v115
	v_cvt_pk_bf16_f32 v114, v104, v105
	v_add_u32_e32 v104, s4, v148
	v_ashrrev_i32_e32 v105, 31, v104
	v_lshlrev_b64 v[104:105], 11, v[104:105]
	v_lshl_add_u64 v[104:105], s[86:87], 0, v[104:105]
	v_cvt_pk_bf16_f32 v115, v106, v107
	global_store_dwordx4 v[160:161], v[112:115], off offset:256 nt
	s_andn2_b64 vcc, exec, s[6:7]
	s_nop 0
	v_lshl_add_u64 v[112:113], v[104:105], 0, v[144:145]
	v_cvt_pk_bf16_f32 v104, v116, v117
	v_cvt_pk_bf16_f32 v105, v118, v119
	v_cvt_pk_bf16_f32 v106, v108, v109
	v_cvt_pk_bf16_f32 v107, v110, v111
	global_store_dwordx4 v[112:113], v[104:107], off nt
	v_cvt_pk_bf16_f32 v96, v96, v97
	v_cvt_pk_bf16_f32 v97, v98, v99
	v_cvt_pk_bf16_f32 v98, v88, v89
	v_add_u32_e32 v88, s4, v149
	v_ashrrev_i32_e32 v89, 31, v88
	v_lshlrev_b64 v[88:89], 11, v[88:89]
	v_lshl_add_u64 v[88:89], s[86:87], 0, v[88:89]
	v_cvt_pk_bf16_f32 v99, v90, v91
	global_store_dwordx4 v[112:113], v[96:99], off offset:256 nt
	s_nop 1
	v_lshl_add_u64 v[96:97], v[88:89], 0, v[144:145]
	v_cvt_pk_bf16_f32 v88, v100, v101
	v_cvt_pk_bf16_f32 v89, v102, v103
	v_cvt_pk_bf16_f32 v90, v92, v93
	v_cvt_pk_bf16_f32 v91, v94, v95
	global_store_dwordx4 v[96:97], v[88:91], off nt
	v_cvt_pk_bf16_f32 v80, v80, v81
	v_cvt_pk_bf16_f32 v81, v82, v83
	v_cvt_pk_bf16_f32 v82, v72, v73
	v_add_u32_e32 v72, s4, v150
	v_ashrrev_i32_e32 v73, 31, v72
	v_lshlrev_b64 v[72:73], 11, v[72:73]
	v_lshl_add_u64 v[72:73], s[86:87], 0, v[72:73]
	v_cvt_pk_bf16_f32 v83, v74, v75
	global_store_dwordx4 v[96:97], v[80:83], off offset:256 nt
	s_nop 1
	v_lshl_add_u64 v[80:81], v[72:73], 0, v[144:145]
	v_cvt_pk_bf16_f32 v72, v84, v85
	v_cvt_pk_bf16_f32 v73, v86, v87
	v_cvt_pk_bf16_f32 v74, v76, v77
	v_cvt_pk_bf16_f32 v75, v78, v79
	global_store_dwordx4 v[80:81], v[72:75], off nt
	v_cvt_pk_bf16_f32 v68, v68, v69
	v_cvt_pk_bf16_f32 v69, v70, v71
	v_cvt_pk_bf16_f32 v70, v64, v65
	v_add_u32_e32 v64, s4, v151
	v_ashrrev_i32_e32 v65, 31, v64
	v_lshlrev_b64 v[64:65], 11, v[64:65]
	v_lshl_add_u64 v[64:65], s[86:87], 0, v[64:65]
	v_lshl_add_u64 v[64:65], v[64:65], 0, v[144:145]
	v_cvt_pk_bf16_f32 v71, v66, v67
	global_store_dwordx4 v[80:81], v[68:71], off offset:256 nt
	v_cvt_pk_bf16_f32 v60, v60, v61
	v_cvt_pk_bf16_f32 v61, v62, v63
	v_cvt_pk_bf16_f32 v62, v56, v57
	v_cvt_pk_bf16_f32 v63, v58, v59
	global_store_dwordx4 v[64:65], v[60:63], off nt
	v_cvt_pk_bf16_f32 v48, v48, v49
	v_cvt_pk_bf16_f32 v49, v50, v51
	v_cvt_pk_bf16_f32 v50, v40, v41
	v_add_u32_e32 v40, s4, v152
	v_ashrrev_i32_e32 v41, 31, v40
	v_lshlrev_b64 v[40:41], 11, v[40:41]
	v_lshl_add_u64 v[40:41], s[86:87], 0, v[40:41]
	v_cvt_pk_bf16_f32 v51, v42, v43
	global_store_dwordx4 v[64:65], v[48:51], off offset:256 nt
	s_nop 1
	v_lshl_add_u64 v[48:49], v[40:41], 0, v[144:145]
	v_cvt_pk_bf16_f32 v40, v52, v53
	v_cvt_pk_bf16_f32 v41, v54, v55
	v_cvt_pk_bf16_f32 v42, v44, v45
	v_cvt_pk_bf16_f32 v43, v46, v47
	global_store_dwordx4 v[48:49], v[40:43], off nt
	v_cvt_pk_bf16_f32 v32, v32, v33
	v_cvt_pk_bf16_f32 v33, v34, v35
	v_cvt_pk_bf16_f32 v34, v24, v25
	v_add_u32_e32 v24, s4, v153
	v_ashrrev_i32_e32 v25, 31, v24
	v_lshlrev_b64 v[24:25], 11, v[24:25]
	v_lshl_add_u64 v[24:25], s[86:87], 0, v[24:25]
	v_cvt_pk_bf16_f32 v35, v26, v27
	global_store_dwordx4 v[48:49], v[32:35], off offset:256 nt
	s_nop 1
	v_lshl_add_u64 v[32:33], v[24:25], 0, v[144:145]
	v_cvt_pk_bf16_f32 v24, v36, v37
	v_cvt_pk_bf16_f32 v25, v38, v39
	v_cvt_pk_bf16_f32 v26, v28, v29
	v_cvt_pk_bf16_f32 v27, v30, v31
	global_store_dwordx4 v[32:33], v[24:27], off nt
	v_cvt_pk_bf16_f32 v16, v16, v17
	v_cvt_pk_bf16_f32 v17, v18, v19
	v_cvt_pk_bf16_f32 v18, v8, v9
	v_add_u32_e32 v8, s4, v154
	v_ashrrev_i32_e32 v9, 31, v8
	v_lshlrev_b64 v[8:9], 11, v[8:9]
	v_lshl_add_u64 v[8:9], s[86:87], 0, v[8:9]
	v_cvt_pk_bf16_f32 v19, v10, v11
	global_store_dwordx4 v[32:33], v[16:19], off offset:256 nt
	s_mov_b64 s[4:5], -1
	s_nop 0
	v_lshl_add_u64 v[16:17], v[8:9], 0, v[144:145]
	v_cvt_pk_bf16_f32 v8, v20, v21
	v_cvt_pk_bf16_f32 v9, v22, v23
	v_cvt_pk_bf16_f32 v10, v12, v13
	v_cvt_pk_bf16_f32 v11, v14, v15
	global_store_dwordx4 v[16:17], v[8:11], off nt
	v_cvt_pk_bf16_f32 v4, v4, v5
	v_cvt_pk_bf16_f32 v5, v6, v7
	v_cvt_pk_bf16_f32 v6, v0, v1
	v_cvt_pk_bf16_f32 v7, v2, v3
	global_store_dwordx4 v[16:17], v[4:7], off offset:256 nt
	s_cbranch_vccnz .LBB0_1545
	s_andn2_b64 vcc, exec, s[0:1]
	s_cbranch_vccnz .LBB0_1544
	s_barrier
	s_branch .LBB0_1544

.LBB0_1683:
	s_lshl_b32 s4, s20, 8
	v_add_u32_e32 v140, s4, v142
	v_ashrrev_i32_e32 v141, 31, v140
	v_lshl_or_b32 v156, s62, 8, v151
	v_lshlrev_b64 v[140:141], 11, v[140:141]
	v_ashrrev_i32_e32 v157, 31, v156
	v_lshl_add_u64 v[158:159], s[80:81], 0, v[140:141]
	v_lshlrev_b64 v[140:141], 1, v[156:157]
	v_lshl_add_u64 v[156:157], v[158:159], 0, v[140:141]
	v_cvt_pk_bf16_f32 v124, v124, v125
	v_cvt_pk_bf16_f32 v125, v126, v127
	v_cvt_pk_bf16_f32 v126, v120, v121
	v_cvt_pk_bf16_f32 v127, v122, v123
	global_store_dwordx4 v[156:157], v[124:127], off nt
	v_cvt_pk_bf16_f32 v112, v112, v113
	v_cvt_pk_bf16_f32 v113, v114, v115
	v_cvt_pk_bf16_f32 v114, v104, v105
	v_add_u32_e32 v104, s4, v144
	v_ashrrev_i32_e32 v105, 31, v104
	v_lshlrev_b64 v[104:105], 11, v[104:105]
	v_lshl_add_u64 v[104:105], s[80:81], 0, v[104:105]
	v_cvt_pk_bf16_f32 v115, v106, v107
	global_store_dwordx4 v[156:157], v[112:115], off offset:256 nt
	s_andn2_b64 vcc, exec, s[6:7]
	s_nop 0
	v_lshl_add_u64 v[112:113], v[104:105], 0, v[140:141]
	v_cvt_pk_bf16_f32 v104, v116, v117
	v_cvt_pk_bf16_f32 v105, v118, v119
	v_cvt_pk_bf16_f32 v106, v108, v109
	v_cvt_pk_bf16_f32 v107, v110, v111
	global_store_dwordx4 v[112:113], v[104:107], off nt
	v_cvt_pk_bf16_f32 v96, v96, v97
	v_cvt_pk_bf16_f32 v97, v98, v99
	v_cvt_pk_bf16_f32 v98, v88, v89
	v_add_u32_e32 v88, s4, v145
	v_ashrrev_i32_e32 v89, 31, v88
	v_lshlrev_b64 v[88:89], 11, v[88:89]
	v_lshl_add_u64 v[88:89], s[80:81], 0, v[88:89]
	v_cvt_pk_bf16_f32 v99, v90, v91
	global_store_dwordx4 v[112:113], v[96:99], off offset:256 nt
	s_nop 1
	v_lshl_add_u64 v[96:97], v[88:89], 0, v[140:141]
	v_cvt_pk_bf16_f32 v88, v100, v101
	v_cvt_pk_bf16_f32 v89, v102, v103
	v_cvt_pk_bf16_f32 v90, v92, v93
	v_cvt_pk_bf16_f32 v91, v94, v95
	global_store_dwordx4 v[96:97], v[88:91], off nt
	v_cvt_pk_bf16_f32 v80, v80, v81
	v_cvt_pk_bf16_f32 v81, v82, v83
	v_cvt_pk_bf16_f32 v82, v72, v73
	v_add_u32_e32 v72, s4, v146
	v_ashrrev_i32_e32 v73, 31, v72
	v_lshlrev_b64 v[72:73], 11, v[72:73]
	v_lshl_add_u64 v[72:73], s[80:81], 0, v[72:73]
	v_cvt_pk_bf16_f32 v83, v74, v75
	global_store_dwordx4 v[96:97], v[80:83], off offset:256 nt
	s_nop 1
	v_lshl_add_u64 v[80:81], v[72:73], 0, v[140:141]
	v_cvt_pk_bf16_f32 v72, v84, v85
	v_cvt_pk_bf16_f32 v73, v86, v87
	v_cvt_pk_bf16_f32 v74, v76, v77
	v_cvt_pk_bf16_f32 v75, v78, v79
	global_store_dwordx4 v[80:81], v[72:75], off nt
	v_cvt_pk_bf16_f32 v68, v68, v69
	v_cvt_pk_bf16_f32 v69, v70, v71
	v_cvt_pk_bf16_f32 v70, v64, v65
	v_add_u32_e32 v64, s4, v147
	v_ashrrev_i32_e32 v65, 31, v64
	v_lshlrev_b64 v[64:65], 11, v[64:65]
	v_lshl_add_u64 v[64:65], s[80:81], 0, v[64:65]
	v_lshl_add_u64 v[64:65], v[64:65], 0, v[140:141]
	v_cvt_pk_bf16_f32 v71, v66, v67
	global_store_dwordx4 v[80:81], v[68:71], off offset:256 nt
	v_cvt_pk_bf16_f32 v60, v60, v61
	v_cvt_pk_bf16_f32 v61, v62, v63
	v_cvt_pk_bf16_f32 v62, v56, v57
	v_cvt_pk_bf16_f32 v63, v58, v59
	global_store_dwordx4 v[64:65], v[60:63], off nt
	v_cvt_pk_bf16_f32 v48, v48, v49
	v_cvt_pk_bf16_f32 v49, v50, v51
	v_cvt_pk_bf16_f32 v50, v40, v41
	v_add_u32_e32 v40, s4, v148
	v_ashrrev_i32_e32 v41, 31, v40
	v_lshlrev_b64 v[40:41], 11, v[40:41]
	v_lshl_add_u64 v[40:41], s[80:81], 0, v[40:41]
	v_cvt_pk_bf16_f32 v51, v42, v43
	global_store_dwordx4 v[64:65], v[48:51], off offset:256 nt
	s_nop 1
	v_lshl_add_u64 v[48:49], v[40:41], 0, v[140:141]
	v_cvt_pk_bf16_f32 v40, v52, v53
	v_cvt_pk_bf16_f32 v41, v54, v55
	v_cvt_pk_bf16_f32 v42, v44, v45
	v_cvt_pk_bf16_f32 v43, v46, v47
	global_store_dwordx4 v[48:49], v[40:43], off nt
	v_cvt_pk_bf16_f32 v32, v32, v33
	v_cvt_pk_bf16_f32 v33, v34, v35
	v_cvt_pk_bf16_f32 v34, v24, v25
	v_add_u32_e32 v24, s4, v149
	v_ashrrev_i32_e32 v25, 31, v24
	v_lshlrev_b64 v[24:25], 11, v[24:25]
	v_lshl_add_u64 v[24:25], s[80:81], 0, v[24:25]
	v_cvt_pk_bf16_f32 v35, v26, v27
	global_store_dwordx4 v[48:49], v[32:35], off offset:256 nt
	s_nop 1
	v_lshl_add_u64 v[32:33], v[24:25], 0, v[140:141]
	v_cvt_pk_bf16_f32 v24, v36, v37
	v_cvt_pk_bf16_f32 v25, v38, v39
	v_cvt_pk_bf16_f32 v26, v28, v29
	v_cvt_pk_bf16_f32 v27, v30, v31
	global_store_dwordx4 v[32:33], v[24:27], off nt
	v_cvt_pk_bf16_f32 v16, v16, v17
	v_cvt_pk_bf16_f32 v17, v18, v19
	v_cvt_pk_bf16_f32 v18, v8, v9
	v_add_u32_e32 v8, s4, v150
	v_ashrrev_i32_e32 v9, 31, v8
	v_lshlrev_b64 v[8:9], 11, v[8:9]
	v_lshl_add_u64 v[8:9], s[80:81], 0, v[8:9]
	v_cvt_pk_bf16_f32 v19, v10, v11
	global_store_dwordx4 v[32:33], v[16:19], off offset:256 nt
	s_mov_b64 s[4:5], -1
	s_nop 0
	v_lshl_add_u64 v[16:17], v[8:9], 0, v[140:141]
	v_cvt_pk_bf16_f32 v8, v20, v21
	v_cvt_pk_bf16_f32 v9, v22, v23
	v_cvt_pk_bf16_f32 v10, v12, v13
	v_cvt_pk_bf16_f32 v11, v14, v15
	global_store_dwordx4 v[16:17], v[8:11], off nt
	v_cvt_pk_bf16_f32 v4, v4, v5
	v_cvt_pk_bf16_f32 v5, v6, v7
	v_cvt_pk_bf16_f32 v6, v0, v1
	v_cvt_pk_bf16_f32 v7, v2, v3
	global_store_dwordx4 v[16:17], v[4:7], off offset:256 nt
	s_cbranch_vccnz .LBB0_1672
	s_andn2_b64 vcc, exec, s[0:1]
	s_cbranch_vccnz .LBB0_1671
	s_barrier
	s_branch .LBB0_1671

.LBB0_1703:
	v_mul_f32_e32 v125, 0xbfb8aa3b, v125
	v_exp_f32_e32 v156, v125
	v_mul_f32_e32 v125, 0xbfb8aa3b, v126
	v_mul_f32_e32 v124, 0xbfb8aa3b, v124
	v_exp_f32_e32 v126, v125
	v_mul_f32_e32 v125, 0xbfb8aa3b, v127
	v_mul_f32_e32 v120, 0xbfb8aa3b, v120
	v_exp_f32_e32 v124, v124
	v_exp_f32_e32 v158, v125
	v_exp_f32_e32 v125, v120
	v_mul_f32_e32 v120, 0xbfb8aa3b, v121
	v_exp_f32_e32 v157, v120
	v_mul_f32_e32 v122, 0xbfb8aa3b, v122
	v_pk_add_f32 v[120:121], v[124:125], 1.0 op_sel_hi:[1,0]
	v_exp_f32_e32 v127, v122
	v_mul_f32_e32 v122, 0xbfb8aa3b, v123
	v_exp_f32_e32 v159, v122
	v_lshl_add_u32 v146, s20, 8, v148
	v_rcp_f32_e32 v121, v121
	v_ashrrev_i32_e32 v147, 31, v146
	v_pk_add_f32 v[122:123], v[156:157], 1.0 op_sel_hi:[1,0]
	v_lshlrev_b64 v[154:155], 10, v[146:147]
	v_rcp_f32_e32 v120, v120
	s_nop 0
	v_pk_fma_f32 v[120:121], v[120:121], s[10:11], 0.5 op_sel_hi:[1,0,0]
	v_rcp_f32_e32 v123, v123
	v_lshl_or_b32 v144, s39, 8, v150
	v_rcp_f32_e32 v122, v122
	s_nop 0
	v_pk_fma_f32 v[122:123], v[122:123], s[10:11], 0.5 op_sel_hi:[1,0,0]
	v_cvt_u32_f32_e32 v124, v121
	v_cvt_u32_f32_e32 v125, v120
	v_pk_add_f32 v[120:121], v[126:127], 1.0 op_sel_hi:[1,0]
	v_cvt_u32_f32_e32 v122, v122
	v_cvt_u32_f32_e32 v123, v123
	v_lshlrev_b32_e32 v122, 8, v122
	v_or_b32_e32 v125, v122, v125
	v_lshlrev_b32_e32 v123, 8, v123
	v_or_b32_e32 v124, v123, v124
	v_rcp_f32_e32 v121, v121
	v_mul_f32_e32 v117, 0xbfb8aa3b, v117
	v_rcp_f32_e32 v120, v120
	v_pk_add_f32 v[122:123], v[158:159], 1.0 op_sel_hi:[1,0]
	v_pk_fma_f32 v[120:121], v[120:121], s[10:11], 0.5 op_sel_hi:[1,0,0]
	s_nop 0
	v_cvt_u32_f32_sdwa v145, v120 dst_sel:WORD_1 dst_unused:UNUSED_PAD src0_sel:DWORD
	v_cvt_u32_f32_sdwa v147, v121 dst_sel:WORD_1 dst_unused:UNUSED_PAD src0_sel:DWORD
	v_mul_f32_e32 v116, 0xbfb8aa3b, v116
	v_rcp_f32_e32 v121, v123
	v_mul_f32_e32 v112, 0xbfb8aa3b, v112
	v_rcp_f32_e32 v120, v122
	s_nop 0
	v_pk_fma_f32 v[120:121], v[120:121], s[10:11], 0.5 op_sel_hi:[1,0,0]
	v_or_b32_e32 v122, v124, v147
	v_cvt_u32_f32_sdwa v121, v121 dst_sel:BYTE_3 dst_unused:UNUSED_PAD src0_sel:DWORD
	v_cvt_u32_f32_sdwa v120, v120 dst_sel:BYTE_3 dst_unused:UNUSED_PAD src0_sel:DWORD
	v_or_b32_e32 v123, v125, v145
	v_ashrrev_i32_e32 v145, 31, v144
	v_or_b32_e32 v121, v122, v121
	v_or_b32_e32 v120, v123, v120
	v_lshl_add_u64 v[122:123], s[90:91], 0, v[154:155]
	v_lshl_add_u64 v[122:123], v[122:123], 0, v[144:145]
	global_store_dwordx2 v[122:123], v[120:121], off nt
	v_exp_f32_e32 v120, v117
	v_mul_f32_e32 v117, 0xbfb8aa3b, v118
	v_exp_f32_e32 v118, v117
	v_mul_f32_e32 v117, 0xbfb8aa3b, v119
	v_exp_f32_e32 v116, v116
	v_exp_f32_e32 v124, v117
	v_exp_f32_e32 v117, v112
	v_mul_f32_e32 v112, 0xbfb8aa3b, v113
	v_exp_f32_e32 v121, v112
	v_mul_f32_e32 v114, 0xbfb8aa3b, v114
	v_pk_add_f32 v[112:113], v[116:117], 1.0 op_sel_hi:[1,0]
	v_exp_f32_e32 v119, v114
	v_mul_f32_e32 v114, 0xbfb8aa3b, v115
	v_exp_f32_e32 v125, v114
	v_mul_f32_e32 v109, 0xbfb8aa3b, v109
	v_rcp_f32_e32 v113, v113
	v_mul_f32_e32 v108, 0xbfb8aa3b, v108
	v_pk_add_f32 v[114:115], v[120:121], 1.0 op_sel_hi:[1,0]
	v_rcp_f32_e32 v112, v112
	s_nop 0
	v_pk_fma_f32 v[112:113], v[112:113], s[10:11], 0.5 op_sel_hi:[1,0,0]
	v_mul_f32_e32 v104, 0xbfb8aa3b, v104
	v_rcp_f32_e32 v115, v115
	v_exp_f32_e32 v108, v108
	v_rcp_f32_e32 v114, v114
	s_nop 0
	v_pk_fma_f32 v[114:115], v[114:115], s[10:11], 0.5 op_sel_hi:[1,0,0]
	v_cvt_u32_f32_e32 v116, v113
	v_cvt_u32_f32_e32 v117, v112
	v_pk_add_f32 v[112:113], v[118:119], 1.0 op_sel_hi:[1,0]
	v_cvt_u32_f32_e32 v114, v114
	v_cvt_u32_f32_e32 v115, v115
	v_lshlrev_b32_e32 v114, 8, v114
	v_or_b32_e32 v117, v114, v117
	v_lshlrev_b32_e32 v115, 8, v115
	v_or_b32_e32 v116, v115, v116
	v_rcp_f32_e32 v113, v113
	v_mul_f32_e32 v106, 0xbfb8aa3b, v106
	v_rcp_f32_e32 v112, v112
	v_pk_add_f32 v[114:115], v[124:125], 1.0 op_sel_hi:[1,0]
	v_pk_fma_f32 v[112:113], v[112:113], s[10:11], 0.5 op_sel_hi:[1,0,0]
	s_nop 0
	v_cvt_u32_f32_sdwa v120, v112 dst_sel:WORD_1 dst_unused:UNUSED_PAD src0_sel:DWORD
	v_cvt_u32_f32_sdwa v121, v113 dst_sel:WORD_1 dst_unused:UNUSED_PAD src0_sel:DWORD
	v_mul_f32_e32 v101, 0xbfb8aa3b, v101
	v_rcp_f32_e32 v113, v115
	v_mul_f32_e32 v100, 0xbfb8aa3b, v100
	v_rcp_f32_e32 v112, v114
	s_nop 0
	v_pk_fma_f32 v[112:113], v[112:113], s[10:11], 0.5 op_sel_hi:[1,0,0]
	v_or_b32_e32 v114, v116, v121
	v_cvt_u32_f32_sdwa v113, v113 dst_sel:BYTE_3 dst_unused:UNUSED_PAD src0_sel:DWORD
	v_cvt_u32_f32_sdwa v112, v112 dst_sel:BYTE_3 dst_unused:UNUSED_PAD src0_sel:DWORD
	v_or_b32_e32 v115, v117, v120
	v_mul_f32_e32 v96, 0xbfb8aa3b, v96
	v_or_b32_e32 v113, v114, v113
	v_exp_f32_e32 v114, v109
	v_mul_f32_e32 v109, 0xbfb8aa3b, v110
	v_exp_f32_e32 v110, v109
	v_mul_f32_e32 v109, 0xbfb8aa3b, v111
	v_exp_f32_e32 v116, v109
	v_exp_f32_e32 v109, v104
	v_mul_f32_e32 v104, 0xbfb8aa3b, v105
	v_or_b32_e32 v112, v115, v112
	v_exp_f32_e32 v115, v104
	v_pk_add_f32 v[104:105], v[108:109], 1.0 op_sel_hi:[1,0]
	v_exp_f32_e32 v111, v106
	v_mul_f32_e32 v106, 0xbfb8aa3b, v107
	v_exp_f32_e32 v117, v106
	global_store_dwordx2 v[122:123], v[112:113], off offset:128 nt
	v_rcp_f32_e32 v105, v105
	v_or_b32_e32 v112, 16, v146
	v_pk_add_f32 v[106:107], v[114:115], 1.0 op_sel_hi:[1,0]
	v_rcp_f32_e32 v104, v104
	s_nop 0
	v_pk_fma_f32 v[104:105], v[104:105], s[10:11], 0.5 op_sel_hi:[1,0,0]
	v_ashrrev_i32_e32 v113, 31, v112
	v_rcp_f32_e32 v107, v107
	v_lshlrev_b64 v[112:113], 10, v[112:113]
	v_rcp_f32_e32 v106, v106
	s_nop 0
	v_pk_fma_f32 v[106:107], v[106:107], s[10:11], 0.5 op_sel_hi:[1,0,0]
	v_cvt_u32_f32_e32 v108, v105
	v_cvt_u32_f32_e32 v109, v104
	v_pk_add_f32 v[104:105], v[110:111], 1.0 op_sel_hi:[1,0]
	v_cvt_u32_f32_e32 v106, v106
	v_cvt_u32_f32_e32 v107, v107
	v_lshlrev_b32_e32 v106, 8, v106
	v_or_b32_e32 v109, v106, v109
	v_lshlrev_b32_e32 v107, 8, v107
	v_or_b32_e32 v108, v107, v108
	v_rcp_f32_e32 v105, v105
	v_exp_f32_e32 v100, v100
	v_rcp_f32_e32 v104, v104
	v_pk_add_f32 v[106:107], v[116:117], 1.0 op_sel_hi:[1,0]
	v_pk_fma_f32 v[104:105], v[104:105], s[10:11], 0.5 op_sel_hi:[1,0,0]
	s_nop 0
	v_cvt_u32_f32_sdwa v114, v104 dst_sel:WORD_1 dst_unused:UNUSED_PAD src0_sel:DWORD
	v_cvt_u32_f32_sdwa v115, v105 dst_sel:WORD_1 dst_unused:UNUSED_PAD src0_sel:DWORD
	v_mul_f32_e32 v98, 0xbfb8aa3b, v98
	v_rcp_f32_e32 v105, v107
	v_mul_f32_e32 v93, 0xbfb8aa3b, v93
	v_rcp_f32_e32 v104, v106
	s_nop 0
	v_pk_fma_f32 v[104:105], v[104:105], s[10:11], 0.5 op_sel_hi:[1,0,0]
	v_or_b32_e32 v106, v108, v115
	v_cvt_u32_f32_sdwa v105, v105 dst_sel:BYTE_3 dst_unused:UNUSED_PAD src0_sel:DWORD
	v_cvt_u32_f32_sdwa v104, v104 dst_sel:BYTE_3 dst_unused:UNUSED_PAD src0_sel:DWORD
	v_or_b32_e32 v107, v109, v114
	v_mul_f32_e32 v92, 0xbfb8aa3b, v92
	v_or_b32_e32 v105, v106, v105
	v_or_b32_e32 v104, v107, v104
	v_lshl_add_u64 v[106:107], s[90:91], 0, v[112:113]
	v_lshl_add_u64 v[106:107], v[106:107], 0, v[144:145]
	global_store_dwordx2 v[106:107], v[104:105], off nt
	v_exp_f32_e32 v104, v101
	v_mul_f32_e32 v101, 0xbfb8aa3b, v102
	v_exp_f32_e32 v102, v101
	v_mul_f32_e32 v101, 0xbfb8aa3b, v103
	v_exp_f32_e32 v108, v101
	v_exp_f32_e32 v101, v96
	v_mul_f32_e32 v96, 0xbfb8aa3b, v97
	v_exp_f32_e32 v105, v96
	v_exp_f32_e32 v103, v98
	v_pk_add_f32 v[96:97], v[100:101], 1.0 op_sel_hi:[1,0]
	v_mul_f32_e32 v98, 0xbfb8aa3b, v99
	v_exp_f32_e32 v109, v98
	v_mul_f32_e32 v88, 0xbfb8aa3b, v88
	v_exp_f32_e32 v92, v92
	v_rcp_f32_e32 v97, v97
	v_mul_f32_e32 v90, 0xbfb8aa3b, v90
	v_pk_add_f32 v[98:99], v[104:105], 1.0 op_sel_hi:[1,0]
	v_rcp_f32_e32 v96, v96
	s_nop 0
	v_pk_fma_f32 v[96:97], v[96:97], s[10:11], 0.5 op_sel_hi:[1,0,0]
	v_mul_f32_e32 v85, 0xbfb8aa3b, v85
	v_rcp_f32_e32 v99, v99
	v_mul_f32_e32 v84, 0xbfb8aa3b, v84
	v_rcp_f32_e32 v98, v98
	s_nop 0
	v_pk_fma_f32 v[98:99], v[98:99], s[10:11], 0.5 op_sel_hi:[1,0,0]
	v_cvt_u32_f32_e32 v100, v97
	v_cvt_u32_f32_e32 v101, v96
	v_pk_add_f32 v[96:97], v[102:103], 1.0 op_sel_hi:[1,0]
	v_cvt_u32_f32_e32 v98, v98
	v_cvt_u32_f32_e32 v99, v99
	v_lshlrev_b32_e32 v98, 8, v98
	v_or_b32_e32 v101, v98, v101
	v_lshlrev_b32_e32 v99, 8, v99
	v_or_b32_e32 v100, v99, v100
	v_rcp_f32_e32 v97, v97
	v_mul_f32_e32 v80, 0xbfb8aa3b, v80
	v_rcp_f32_e32 v96, v96
	v_pk_add_f32 v[98:99], v[108:109], 1.0 op_sel_hi:[1,0]
	v_pk_fma_f32 v[96:97], v[96:97], s[10:11], 0.5 op_sel_hi:[1,0,0]
	s_nop 0
	v_cvt_u32_f32_sdwa v104, v96 dst_sel:WORD_1 dst_unused:UNUSED_PAD src0_sel:DWORD
	v_cvt_u32_f32_sdwa v105, v97 dst_sel:WORD_1 dst_unused:UNUSED_PAD src0_sel:DWORD
	v_exp_f32_e32 v84, v84
	v_rcp_f32_e32 v97, v99
	v_mul_f32_e32 v82, 0xbfb8aa3b, v82
	v_rcp_f32_e32 v96, v98
	s_nop 0
	v_pk_fma_f32 v[96:97], v[96:97], s[10:11], 0.5 op_sel_hi:[1,0,0]
	v_or_b32_e32 v98, v100, v105
	v_cvt_u32_f32_sdwa v97, v97 dst_sel:BYTE_3 dst_unused:UNUSED_PAD src0_sel:DWORD
	v_cvt_u32_f32_sdwa v96, v96 dst_sel:BYTE_3 dst_unused:UNUSED_PAD src0_sel:DWORD
	v_or_b32_e32 v99, v101, v104
	v_mul_f32_e32 v77, 0xbfb8aa3b, v77
	v_or_b32_e32 v97, v98, v97
	v_exp_f32_e32 v98, v93
	v_mul_f32_e32 v93, 0xbfb8aa3b, v94
	v_exp_f32_e32 v94, v93
	v_mul_f32_e32 v93, 0xbfb8aa3b, v95
	v_exp_f32_e32 v100, v93
	v_exp_f32_e32 v93, v88
	v_mul_f32_e32 v88, 0xbfb8aa3b, v89
	v_or_b32_e32 v96, v99, v96
	v_exp_f32_e32 v99, v88
	v_pk_add_f32 v[88:89], v[92:93], 1.0 op_sel_hi:[1,0]
	v_exp_f32_e32 v95, v90
	v_mul_f32_e32 v90, 0xbfb8aa3b, v91
	v_exp_f32_e32 v101, v90
	global_store_dwordx2 v[106:107], v[96:97], off offset:128 nt
	v_rcp_f32_e32 v89, v89
	v_or_b32_e32 v96, 32, v146
	v_pk_add_f32 v[90:91], v[98:99], 1.0 op_sel_hi:[1,0]
	v_rcp_f32_e32 v88, v88
	s_nop 0
	v_pk_fma_f32 v[88:89], v[88:89], s[10:11], 0.5 op_sel_hi:[1,0,0]
	v_ashrrev_i32_e32 v97, 31, v96
	v_rcp_f32_e32 v91, v91
	v_lshlrev_b64 v[96:97], 10, v[96:97]
	v_rcp_f32_e32 v90, v90
	s_nop 0
	v_pk_fma_f32 v[90:91], v[90:91], s[10:11], 0.5 op_sel_hi:[1,0,0]
	v_cvt_u32_f32_e32 v92, v89
	v_cvt_u32_f32_e32 v93, v88
	v_pk_add_f32 v[88:89], v[94:95], 1.0 op_sel_hi:[1,0]
	v_cvt_u32_f32_e32 v90, v90
	v_cvt_u32_f32_e32 v91, v91
	v_lshlrev_b32_e32 v90, 8, v90
	v_or_b32_e32 v93, v90, v93
	v_lshlrev_b32_e32 v91, 8, v91
	v_or_b32_e32 v92, v91, v92
	v_rcp_f32_e32 v89, v89
	v_mul_f32_e32 v76, 0xbfb8aa3b, v76
	v_rcp_f32_e32 v88, v88
	v_pk_add_f32 v[90:91], v[100:101], 1.0 op_sel_hi:[1,0]
	v_pk_fma_f32 v[88:89], v[88:89], s[10:11], 0.5 op_sel_hi:[1,0,0]
	s_nop 0
	v_cvt_u32_f32_sdwa v98, v88 dst_sel:WORD_1 dst_unused:UNUSED_PAD src0_sel:DWORD
	v_cvt_u32_f32_sdwa v99, v89 dst_sel:WORD_1 dst_unused:UNUSED_PAD src0_sel:DWORD
	v_mul_f32_e32 v72, 0xbfb8aa3b, v72
	v_rcp_f32_e32 v89, v91
	v_exp_f32_e32 v76, v76
	v_rcp_f32_e32 v88, v90
	s_nop 0
	v_pk_fma_f32 v[88:89], v[88:89], s[10:11], 0.5 op_sel_hi:[1,0,0]
	v_or_b32_e32 v90, v92, v99
	v_cvt_u32_f32_sdwa v89, v89 dst_sel:BYTE_3 dst_unused:UNUSED_PAD src0_sel:DWORD
	v_cvt_u32_f32_sdwa v88, v88 dst_sel:BYTE_3 dst_unused:UNUSED_PAD src0_sel:DWORD
	v_or_b32_e32 v91, v93, v98
	v_mul_f32_e32 v74, 0xbfb8aa3b, v74
	v_or_b32_e32 v89, v90, v89
	v_or_b32_e32 v88, v91, v88
	v_lshl_add_u64 v[90:91], s[90:91], 0, v[96:97]
	v_lshl_add_u64 v[90:91], v[90:91], 0, v[144:145]
	global_store_dwordx2 v[90:91], v[88:89], off nt
	v_exp_f32_e32 v88, v85
	v_mul_f32_e32 v85, 0xbfb8aa3b, v86
	v_exp_f32_e32 v86, v85
	v_mul_f32_e32 v85, 0xbfb8aa3b, v87
	v_exp_f32_e32 v92, v85
	v_exp_f32_e32 v85, v80
	v_mul_f32_e32 v80, 0xbfb8aa3b, v81
	v_exp_f32_e32 v89, v80
	v_exp_f32_e32 v87, v82
	v_pk_add_f32 v[80:81], v[84:85], 1.0 op_sel_hi:[1,0]
	v_mul_f32_e32 v82, 0xbfb8aa3b, v83
	v_exp_f32_e32 v93, v82
	v_mul_f32_e32 v69, 0xbfb8aa3b, v69
	v_mul_f32_e32 v68, 0xbfb8aa3b, v68
	v_rcp_f32_e32 v81, v81
	v_mul_f32_e32 v64, 0xbfb8aa3b, v64
	v_pk_add_f32 v[82:83], v[88:89], 1.0 op_sel_hi:[1,0]
	v_rcp_f32_e32 v80, v80
	s_nop 0
	v_pk_fma_f32 v[80:81], v[80:81], s[10:11], 0.5 op_sel_hi:[1,0,0]
	v_exp_f32_e32 v68, v68
	v_rcp_f32_e32 v83, v83
	v_mul_f32_e32 v66, 0xbfb8aa3b, v66
	v_rcp_f32_e32 v82, v82
	s_nop 0
	v_pk_fma_f32 v[82:83], v[82:83], s[10:11], 0.5 op_sel_hi:[1,0,0]
	v_cvt_u32_f32_e32 v84, v81
	v_cvt_u32_f32_e32 v85, v80
	v_pk_add_f32 v[80:81], v[86:87], 1.0 op_sel_hi:[1,0]
	v_cvt_u32_f32_e32 v82, v82
	v_cvt_u32_f32_e32 v83, v83
	v_lshlrev_b32_e32 v82, 8, v82
	v_or_b32_e32 v85, v82, v85
	v_lshlrev_b32_e32 v83, 8, v83
	v_or_b32_e32 v84, v83, v84
	v_rcp_f32_e32 v81, v81
	v_mul_f32_e32 v61, 0xbfb8aa3b, v61
	v_rcp_f32_e32 v80, v80
	v_pk_add_f32 v[82:83], v[92:93], 1.0 op_sel_hi:[1,0]
	v_pk_fma_f32 v[80:81], v[80:81], s[10:11], 0.5 op_sel_hi:[1,0,0]
	s_nop 0
	v_cvt_u32_f32_sdwa v88, v80 dst_sel:WORD_1 dst_unused:UNUSED_PAD src0_sel:DWORD
	v_cvt_u32_f32_sdwa v89, v81 dst_sel:WORD_1 dst_unused:UNUSED_PAD src0_sel:DWORD
	v_mul_f32_e32 v60, 0xbfb8aa3b, v60
	v_rcp_f32_e32 v81, v83
	v_mul_f32_e32 v56, 0xbfb8aa3b, v56
	v_rcp_f32_e32 v80, v82
	s_nop 0
	v_pk_fma_f32 v[80:81], v[80:81], s[10:11], 0.5 op_sel_hi:[1,0,0]
	v_or_b32_e32 v82, v84, v89
	v_cvt_u32_f32_sdwa v81, v81 dst_sel:BYTE_3 dst_unused:UNUSED_PAD src0_sel:DWORD
	v_cvt_u32_f32_sdwa v80, v80 dst_sel:BYTE_3 dst_unused:UNUSED_PAD src0_sel:DWORD
	v_or_b32_e32 v83, v85, v88
	v_exp_f32_e32 v60, v60
	v_or_b32_e32 v81, v82, v81
	v_exp_f32_e32 v82, v77
	v_mul_f32_e32 v77, 0xbfb8aa3b, v78
	v_exp_f32_e32 v78, v77
	v_mul_f32_e32 v77, 0xbfb8aa3b, v79
	v_exp_f32_e32 v84, v77
	v_exp_f32_e32 v77, v72
	v_mul_f32_e32 v72, 0xbfb8aa3b, v73
	v_or_b32_e32 v80, v83, v80
	v_exp_f32_e32 v83, v72
	v_pk_add_f32 v[72:73], v[76:77], 1.0 op_sel_hi:[1,0]
	v_exp_f32_e32 v79, v74
	v_mul_f32_e32 v74, 0xbfb8aa3b, v75
	v_exp_f32_e32 v85, v74
	global_store_dwordx2 v[90:91], v[80:81], off offset:128 nt
	v_rcp_f32_e32 v73, v73
	v_or_b32_e32 v80, 48, v146
	v_pk_add_f32 v[74:75], v[82:83], 1.0 op_sel_hi:[1,0]
	v_rcp_f32_e32 v72, v72
	s_nop 0
	v_pk_fma_f32 v[72:73], v[72:73], s[10:11], 0.5 op_sel_hi:[1,0,0]
	v_ashrrev_i32_e32 v81, 31, v80
	v_rcp_f32_e32 v75, v75
	v_lshlrev_b64 v[80:81], 10, v[80:81]
	v_rcp_f32_e32 v74, v74
	s_nop 0
	v_pk_fma_f32 v[74:75], v[74:75], s[10:11], 0.5 op_sel_hi:[1,0,0]
	v_cvt_u32_f32_e32 v76, v73
	v_cvt_u32_f32_e32 v77, v72
	v_pk_add_f32 v[72:73], v[78:79], 1.0 op_sel_hi:[1,0]
	v_cvt_u32_f32_e32 v74, v74
	v_cvt_u32_f32_e32 v75, v75
	v_lshlrev_b32_e32 v74, 8, v74
	v_or_b32_e32 v77, v74, v77
	v_lshlrev_b32_e32 v75, 8, v75
	v_or_b32_e32 v76, v75, v76
	v_rcp_f32_e32 v73, v73
	v_mul_f32_e32 v58, 0xbfb8aa3b, v58
	v_rcp_f32_e32 v72, v72
	v_pk_add_f32 v[74:75], v[84:85], 1.0 op_sel_hi:[1,0]
	v_pk_fma_f32 v[72:73], v[72:73], s[10:11], 0.5 op_sel_hi:[1,0,0]
	s_nop 0
	v_cvt_u32_f32_sdwa v82, v72 dst_sel:WORD_1 dst_unused:UNUSED_PAD src0_sel:DWORD
	v_cvt_u32_f32_sdwa v83, v73 dst_sel:WORD_1 dst_unused:UNUSED_PAD src0_sel:DWORD
	v_mul_f32_e32 v53, 0xbfb8aa3b, v53
	v_rcp_f32_e32 v73, v75
	v_mul_f32_e32 v52, 0xbfb8aa3b, v52
	v_rcp_f32_e32 v72, v74
	s_nop 0
	v_pk_fma_f32 v[72:73], v[72:73], s[10:11], 0.5 op_sel_hi:[1,0,0]
	v_or_b32_e32 v74, v76, v83
	v_cvt_u32_f32_sdwa v73, v73 dst_sel:BYTE_3 dst_unused:UNUSED_PAD src0_sel:DWORD
	v_cvt_u32_f32_sdwa v72, v72 dst_sel:BYTE_3 dst_unused:UNUSED_PAD src0_sel:DWORD
	v_or_b32_e32 v75, v77, v82
	v_mul_f32_e32 v48, 0xbfb8aa3b, v48
	v_or_b32_e32 v73, v74, v73
	v_or_b32_e32 v72, v75, v72
	v_lshl_add_u64 v[74:75], s[90:91], 0, v[80:81]
	v_lshl_add_u64 v[74:75], v[74:75], 0, v[144:145]
	global_store_dwordx2 v[74:75], v[72:73], off nt
	v_exp_f32_e32 v72, v69
	v_mul_f32_e32 v69, 0xbfb8aa3b, v70
	v_exp_f32_e32 v70, v69
	v_mul_f32_e32 v69, 0xbfb8aa3b, v71
	v_exp_f32_e32 v76, v69
	v_exp_f32_e32 v69, v64
	v_mul_f32_e32 v64, 0xbfb8aa3b, v65
	v_exp_f32_e32 v73, v64
	v_exp_f32_e32 v71, v66
	v_pk_add_f32 v[64:65], v[68:69], 1.0 op_sel_hi:[1,0]
	v_mul_f32_e32 v66, 0xbfb8aa3b, v67
	v_exp_f32_e32 v77, v66
	v_exp_f32_e32 v52, v52
	v_mul_f32_e32 v50, 0xbfb8aa3b, v50
	v_rcp_f32_e32 v65, v65
	v_mul_f32_e32 v45, 0xbfb8aa3b, v45
	v_pk_add_f32 v[66:67], v[72:73], 1.0 op_sel_hi:[1,0]
	v_rcp_f32_e32 v64, v64
	s_nop 0
	v_pk_fma_f32 v[64:65], v[64:65], s[10:11], 0.5 op_sel_hi:[1,0,0]
	v_mul_f32_e32 v44, 0xbfb8aa3b, v44
	v_rcp_f32_e32 v67, v67
	v_mul_f32_e32 v40, 0xbfb8aa3b, v40
	v_rcp_f32_e32 v66, v66
	s_nop 0
	v_pk_fma_f32 v[66:67], v[66:67], s[10:11], 0.5 op_sel_hi:[1,0,0]
	v_cvt_u32_f32_e32 v68, v65
	v_cvt_u32_f32_e32 v69, v64
	v_pk_add_f32 v[64:65], v[70:71], 1.0 op_sel_hi:[1,0]
	v_cvt_u32_f32_e32 v66, v66
	v_cvt_u32_f32_e32 v67, v67
	v_lshlrev_b32_e32 v66, 8, v66
	v_or_b32_e32 v69, v66, v69
	v_lshlrev_b32_e32 v67, 8, v67
	v_or_b32_e32 v68, v67, v68
	v_rcp_f32_e32 v65, v65
	v_exp_f32_e32 v44, v44
	v_rcp_f32_e32 v64, v64
	v_pk_add_f32 v[66:67], v[76:77], 1.0 op_sel_hi:[1,0]
	v_pk_fma_f32 v[64:65], v[64:65], s[10:11], 0.5 op_sel_hi:[1,0,0]
	s_nop 0
	v_cvt_u32_f32_sdwa v72, v64 dst_sel:WORD_1 dst_unused:UNUSED_PAD src0_sel:DWORD
	v_cvt_u32_f32_sdwa v73, v65 dst_sel:WORD_1 dst_unused:UNUSED_PAD src0_sel:DWORD
	v_mul_f32_e32 v42, 0xbfb8aa3b, v42
	v_rcp_f32_e32 v65, v67
	v_mul_f32_e32 v37, 0xbfb8aa3b, v37
	v_rcp_f32_e32 v64, v66
	s_nop 0
	v_pk_fma_f32 v[64:65], v[64:65], s[10:11], 0.5 op_sel_hi:[1,0,0]
	v_or_b32_e32 v66, v68, v73
	v_cvt_u32_f32_sdwa v65, v65 dst_sel:BYTE_3 dst_unused:UNUSED_PAD src0_sel:DWORD
	v_cvt_u32_f32_sdwa v64, v64 dst_sel:BYTE_3 dst_unused:UNUSED_PAD src0_sel:DWORD
	v_or_b32_e32 v67, v69, v72
	v_mul_f32_e32 v36, 0xbfb8aa3b, v36
	v_or_b32_e32 v65, v66, v65
	v_exp_f32_e32 v66, v61
	v_mul_f32_e32 v61, 0xbfb8aa3b, v62
	v_exp_f32_e32 v62, v61
	v_mul_f32_e32 v61, 0xbfb8aa3b, v63
	v_exp_f32_e32 v68, v61
	v_exp_f32_e32 v61, v56
	v_mul_f32_e32 v56, 0xbfb8aa3b, v57
	v_or_b32_e32 v64, v67, v64
	v_exp_f32_e32 v67, v56
	v_pk_add_f32 v[56:57], v[60:61], 1.0 op_sel_hi:[1,0]
	v_exp_f32_e32 v63, v58
	v_mul_f32_e32 v58, 0xbfb8aa3b, v59
	v_exp_f32_e32 v69, v58
	global_store_dwordx2 v[74:75], v[64:65], off offset:128 nt
	v_rcp_f32_e32 v57, v57
	v_add_u32_e32 v64, 0x80, v146
	v_pk_add_f32 v[58:59], v[66:67], 1.0 op_sel_hi:[1,0]
	v_rcp_f32_e32 v56, v56
	s_nop 0
	v_pk_fma_f32 v[56:57], v[56:57], s[10:11], 0.5 op_sel_hi:[1,0,0]
	v_ashrrev_i32_e32 v65, 31, v64
	v_rcp_f32_e32 v59, v59
	v_lshlrev_b64 v[64:65], 10, v[64:65]
	v_rcp_f32_e32 v58, v58
	s_nop 0
	v_pk_fma_f32 v[58:59], v[58:59], s[10:11], 0.5 op_sel_hi:[1,0,0]
	v_cvt_u32_f32_e32 v60, v57
	v_cvt_u32_f32_e32 v61, v56
	v_pk_add_f32 v[56:57], v[62:63], 1.0 op_sel_hi:[1,0]
	v_cvt_u32_f32_e32 v58, v58
	v_cvt_u32_f32_e32 v59, v59
	v_lshlrev_b32_e32 v58, 8, v58
	v_or_b32_e32 v61, v58, v61
	v_lshlrev_b32_e32 v59, 8, v59
	v_or_b32_e32 v60, v59, v60
	v_rcp_f32_e32 v57, v57
	v_mul_f32_e32 v32, 0xbfb8aa3b, v32
	v_rcp_f32_e32 v56, v56
	v_pk_add_f32 v[58:59], v[68:69], 1.0 op_sel_hi:[1,0]
	v_pk_fma_f32 v[56:57], v[56:57], s[10:11], 0.5 op_sel_hi:[1,0,0]
	s_nop 0
	v_cvt_u32_f32_sdwa v66, v56 dst_sel:WORD_1 dst_unused:UNUSED_PAD src0_sel:DWORD
	v_cvt_u32_f32_sdwa v67, v57 dst_sel:WORD_1 dst_unused:UNUSED_PAD src0_sel:DWORD
	v_exp_f32_e32 v36, v36
	v_rcp_f32_e32 v57, v59
	v_mul_f32_e32 v34, 0xbfb8aa3b, v34
	v_rcp_f32_e32 v56, v58
	s_nop 0
	v_pk_fma_f32 v[56:57], v[56:57], s[10:11], 0.5 op_sel_hi:[1,0,0]
	v_or_b32_e32 v58, v60, v67
	v_cvt_u32_f32_sdwa v57, v57 dst_sel:BYTE_3 dst_unused:UNUSED_PAD src0_sel:DWORD
	v_cvt_u32_f32_sdwa v56, v56 dst_sel:BYTE_3 dst_unused:UNUSED_PAD src0_sel:DWORD
	v_or_b32_e32 v59, v61, v66
	v_mul_f32_e32 v29, 0xbfb8aa3b, v29
	v_or_b32_e32 v57, v58, v57
	v_or_b32_e32 v56, v59, v56
	v_lshl_add_u64 v[58:59], s[90:91], 0, v[64:65]
	v_lshl_add_u64 v[58:59], v[58:59], 0, v[144:145]
	global_store_dwordx2 v[58:59], v[56:57], off nt
	v_exp_f32_e32 v56, v53
	v_mul_f32_e32 v53, 0xbfb8aa3b, v54
	v_exp_f32_e32 v54, v53
	v_mul_f32_e32 v53, 0xbfb8aa3b, v55
	v_exp_f32_e32 v60, v53
	v_exp_f32_e32 v53, v48
	v_mul_f32_e32 v48, 0xbfb8aa3b, v49
	v_exp_f32_e32 v57, v48
	v_exp_f32_e32 v55, v50
	v_pk_add_f32 v[48:49], v[52:53], 1.0 op_sel_hi:[1,0]
	v_mul_f32_e32 v50, 0xbfb8aa3b, v51
	v_exp_f32_e32 v61, v50
	v_mul_f32_e32 v28, 0xbfb8aa3b, v28
	v_mul_f32_e32 v24, 0xbfb8aa3b, v24
	v_rcp_f32_e32 v49, v49
	v_exp_f32_e32 v28, v28
	v_pk_add_f32 v[50:51], v[56:57], 1.0 op_sel_hi:[1,0]
	v_rcp_f32_e32 v48, v48
	s_nop 0
	v_pk_fma_f32 v[48:49], v[48:49], s[10:11], 0.5 op_sel_hi:[1,0,0]
	v_mul_f32_e32 v26, 0xbfb8aa3b, v26
	v_rcp_f32_e32 v51, v51
	v_mul_f32_e32 v21, 0xbfb8aa3b, v21
	v_rcp_f32_e32 v50, v50
	s_nop 0
	v_pk_fma_f32 v[50:51], v[50:51], s[10:11], 0.5 op_sel_hi:[1,0,0]
	v_cvt_u32_f32_e32 v52, v49
	v_cvt_u32_f32_e32 v53, v48
	v_pk_add_f32 v[48:49], v[54:55], 1.0 op_sel_hi:[1,0]
	v_cvt_u32_f32_e32 v50, v50
	v_cvt_u32_f32_e32 v51, v51
	v_lshlrev_b32_e32 v50, 8, v50
	v_or_b32_e32 v53, v50, v53
	v_lshlrev_b32_e32 v51, 8, v51
	v_or_b32_e32 v52, v51, v52
	v_rcp_f32_e32 v49, v49
	v_mul_f32_e32 v20, 0xbfb8aa3b, v20
	v_rcp_f32_e32 v48, v48
	v_pk_add_f32 v[50:51], v[60:61], 1.0 op_sel_hi:[1,0]
	v_pk_fma_f32 v[48:49], v[48:49], s[10:11], 0.5 op_sel_hi:[1,0,0]
	s_nop 0
	v_cvt_u32_f32_sdwa v56, v48 dst_sel:WORD_1 dst_unused:UNUSED_PAD src0_sel:DWORD
	v_cvt_u32_f32_sdwa v57, v49 dst_sel:WORD_1 dst_unused:UNUSED_PAD src0_sel:DWORD
	v_mul_f32_e32 v16, 0xbfb8aa3b, v16
	v_rcp_f32_e32 v49, v51
	v_exp_f32_e32 v20, v20
	v_rcp_f32_e32 v48, v50
	s_nop 0
	v_pk_fma_f32 v[48:49], v[48:49], s[10:11], 0.5 op_sel_hi:[1,0,0]
	v_or_b32_e32 v50, v52, v57
	v_cvt_u32_f32_sdwa v49, v49 dst_sel:BYTE_3 dst_unused:UNUSED_PAD src0_sel:DWORD
	v_cvt_u32_f32_sdwa v48, v48 dst_sel:BYTE_3 dst_unused:UNUSED_PAD src0_sel:DWORD
	v_or_b32_e32 v51, v53, v56
	v_mul_f32_e32 v18, 0xbfb8aa3b, v18
	v_or_b32_e32 v49, v50, v49
	v_exp_f32_e32 v50, v45
	v_mul_f32_e32 v45, 0xbfb8aa3b, v46
	v_exp_f32_e32 v46, v45
	v_mul_f32_e32 v45, 0xbfb8aa3b, v47
	v_exp_f32_e32 v52, v45
	v_exp_f32_e32 v45, v40
	v_mul_f32_e32 v40, 0xbfb8aa3b, v41
	v_or_b32_e32 v48, v51, v48
	v_exp_f32_e32 v51, v40
	v_pk_add_f32 v[40:41], v[44:45], 1.0 op_sel_hi:[1,0]
	v_exp_f32_e32 v47, v42
	v_mul_f32_e32 v42, 0xbfb8aa3b, v43
	v_exp_f32_e32 v53, v42
	global_store_dwordx2 v[58:59], v[48:49], off offset:128 nt
	v_rcp_f32_e32 v41, v41
	v_add_u32_e32 v48, 0x90, v146
	v_pk_add_f32 v[42:43], v[50:51], 1.0 op_sel_hi:[1,0]
	v_rcp_f32_e32 v40, v40
	s_nop 0
	v_pk_fma_f32 v[40:41], v[40:41], s[10:11], 0.5 op_sel_hi:[1,0,0]
	v_ashrrev_i32_e32 v49, 31, v48
	v_rcp_f32_e32 v43, v43
	v_lshlrev_b64 v[48:49], 10, v[48:49]
	v_rcp_f32_e32 v42, v42
	s_nop 0
	v_pk_fma_f32 v[42:43], v[42:43], s[10:11], 0.5 op_sel_hi:[1,0,0]
	v_cvt_u32_f32_e32 v44, v41
	v_cvt_u32_f32_e32 v45, v40
	v_pk_add_f32 v[40:41], v[46:47], 1.0 op_sel_hi:[1,0]
	v_cvt_u32_f32_e32 v42, v42
	v_cvt_u32_f32_e32 v43, v43
	v_lshlrev_b32_e32 v42, 8, v42
	v_or_b32_e32 v45, v42, v45
	v_lshlrev_b32_e32 v43, 8, v43
	v_or_b32_e32 v44, v43, v44
	v_rcp_f32_e32 v41, v41
	v_mul_f32_e32 v13, 0xbfb8aa3b, v13
	v_rcp_f32_e32 v40, v40
	v_pk_add_f32 v[42:43], v[52:53], 1.0 op_sel_hi:[1,0]
	v_pk_fma_f32 v[40:41], v[40:41], s[10:11], 0.5 op_sel_hi:[1,0,0]
	s_nop 0
	v_cvt_u32_f32_sdwa v50, v40 dst_sel:WORD_1 dst_unused:UNUSED_PAD src0_sel:DWORD
	v_cvt_u32_f32_sdwa v51, v41 dst_sel:WORD_1 dst_unused:UNUSED_PAD src0_sel:DWORD
	v_mul_f32_e32 v12, 0xbfb8aa3b, v12
	v_rcp_f32_e32 v41, v43
	v_mul_f32_e32 v8, 0xbfb8aa3b, v8
	v_rcp_f32_e32 v40, v42
	s_nop 0
	v_pk_fma_f32 v[40:41], v[40:41], s[10:11], 0.5 op_sel_hi:[1,0,0]
	v_or_b32_e32 v42, v44, v51
	v_cvt_u32_f32_sdwa v41, v41 dst_sel:BYTE_3 dst_unused:UNUSED_PAD src0_sel:DWORD
	v_cvt_u32_f32_sdwa v40, v40 dst_sel:BYTE_3 dst_unused:UNUSED_PAD src0_sel:DWORD
	v_or_b32_e32 v43, v45, v50
	v_exp_f32_e32 v12, v12
	v_or_b32_e32 v41, v42, v41
	v_or_b32_e32 v40, v43, v40
	v_lshl_add_u64 v[42:43], s[90:91], 0, v[48:49]
	v_lshl_add_u64 v[42:43], v[42:43], 0, v[144:145]
	global_store_dwordx2 v[42:43], v[40:41], off nt
	v_exp_f32_e32 v40, v37
	v_mul_f32_e32 v37, 0xbfb8aa3b, v38
	v_exp_f32_e32 v38, v37
	v_mul_f32_e32 v37, 0xbfb8aa3b, v39
	v_exp_f32_e32 v44, v37
	v_exp_f32_e32 v37, v32
	v_mul_f32_e32 v32, 0xbfb8aa3b, v33
	v_exp_f32_e32 v41, v32
	v_exp_f32_e32 v39, v34
	v_pk_add_f32 v[32:33], v[36:37], 1.0 op_sel_hi:[1,0]
	v_mul_f32_e32 v34, 0xbfb8aa3b, v35
	v_exp_f32_e32 v45, v34
	v_mul_f32_e32 v10, 0xbfb8aa3b, v10
	v_mul_f32_e32 v5, 0xbfb8aa3b, v5
	v_rcp_f32_e32 v33, v33
	v_mul_f32_e32 v4, 0xbfb8aa3b, v4
	v_pk_add_f32 v[34:35], v[40:41], 1.0 op_sel_hi:[1,0]
	v_rcp_f32_e32 v32, v32
	s_nop 0
	v_pk_fma_f32 v[32:33], v[32:33], s[10:11], 0.5 op_sel_hi:[1,0,0]
	v_mul_f32_e32 v0, 0xbfb8aa3b, v0
	v_rcp_f32_e32 v35, v35
	v_exp_f32_e32 v4, v4
	v_rcp_f32_e32 v34, v34
	s_nop 0
	v_pk_fma_f32 v[34:35], v[34:35], s[10:11], 0.5 op_sel_hi:[1,0,0]
	v_cvt_u32_f32_e32 v36, v33
	v_cvt_u32_f32_e32 v37, v32
	v_pk_add_f32 v[32:33], v[38:39], 1.0 op_sel_hi:[1,0]
	v_cvt_u32_f32_e32 v34, v34
	v_cvt_u32_f32_e32 v35, v35
	v_lshlrev_b32_e32 v34, 8, v34
	v_or_b32_e32 v37, v34, v37
	v_lshlrev_b32_e32 v35, 8, v35
	v_or_b32_e32 v36, v35, v36
	v_rcp_f32_e32 v33, v33
	v_mul_f32_e32 v2, 0xbfb8aa3b, v2
	v_rcp_f32_e32 v32, v32
	v_pk_add_f32 v[34:35], v[44:45], 1.0 op_sel_hi:[1,0]
	v_pk_fma_f32 v[32:33], v[32:33], s[10:11], 0.5 op_sel_hi:[1,0,0]
	s_nop 0
	v_cvt_u32_f32_sdwa v40, v32 dst_sel:WORD_1 dst_unused:UNUSED_PAD src0_sel:DWORD
	v_cvt_u32_f32_sdwa v41, v33 dst_sel:WORD_1 dst_unused:UNUSED_PAD src0_sel:DWORD
	v_rcp_f32_e32 v33, v35
	v_rcp_f32_e32 v32, v34
	s_nop 0
	v_pk_fma_f32 v[32:33], v[32:33], s[10:11], 0.5 op_sel_hi:[1,0,0]
	v_or_b32_e32 v34, v36, v41
	v_cvt_u32_f32_sdwa v33, v33 dst_sel:BYTE_3 dst_unused:UNUSED_PAD src0_sel:DWORD
	v_cvt_u32_f32_sdwa v32, v32 dst_sel:BYTE_3 dst_unused:UNUSED_PAD src0_sel:DWORD
	v_or_b32_e32 v35, v37, v40
	v_or_b32_e32 v33, v34, v33
	v_exp_f32_e32 v34, v29
	v_mul_f32_e32 v29, 0xbfb8aa3b, v30
	v_exp_f32_e32 v30, v29
	v_mul_f32_e32 v29, 0xbfb8aa3b, v31
	v_exp_f32_e32 v36, v29
	v_exp_f32_e32 v29, v24
	v_mul_f32_e32 v24, 0xbfb8aa3b, v25
	v_or_b32_e32 v32, v35, v32
	v_exp_f32_e32 v35, v24
	v_pk_add_f32 v[24:25], v[28:29], 1.0 op_sel_hi:[1,0]
	v_exp_f32_e32 v31, v26
	v_mul_f32_e32 v26, 0xbfb8aa3b, v27
	v_exp_f32_e32 v37, v26
	global_store_dwordx2 v[42:43], v[32:33], off offset:128 nt
	v_rcp_f32_e32 v25, v25
	v_add_u32_e32 v32, 0xa0, v146
	v_pk_add_f32 v[26:27], v[34:35], 1.0 op_sel_hi:[1,0]
	v_rcp_f32_e32 v24, v24
	s_nop 0
	v_pk_fma_f32 v[24:25], v[24:25], s[10:11], 0.5 op_sel_hi:[1,0,0]
	v_ashrrev_i32_e32 v33, 31, v32
	v_rcp_f32_e32 v27, v27
	v_lshlrev_b64 v[32:33], 10, v[32:33]
	v_rcp_f32_e32 v26, v26
	s_nop 0
	v_pk_fma_f32 v[26:27], v[26:27], s[10:11], 0.5 op_sel_hi:[1,0,0]
	v_cvt_u32_f32_e32 v28, v25
	v_cvt_u32_f32_e32 v29, v24
	v_pk_add_f32 v[24:25], v[30:31], 1.0 op_sel_hi:[1,0]
	v_cvt_u32_f32_e32 v26, v26
	v_cvt_u32_f32_e32 v27, v27
	v_lshlrev_b32_e32 v26, 8, v26
	v_or_b32_e32 v29, v26, v29
	v_lshlrev_b32_e32 v27, 8, v27
	v_or_b32_e32 v28, v27, v28
	v_rcp_f32_e32 v25, v25
	v_rcp_f32_e32 v24, v24
	v_pk_add_f32 v[26:27], v[36:37], 1.0 op_sel_hi:[1,0]
	v_pk_fma_f32 v[24:25], v[24:25], s[10:11], 0.5 op_sel_hi:[1,0,0]
	s_nop 0
	v_cvt_u32_f32_sdwa v34, v24 dst_sel:WORD_1 dst_unused:UNUSED_PAD src0_sel:DWORD
	v_cvt_u32_f32_sdwa v35, v25 dst_sel:WORD_1 dst_unused:UNUSED_PAD src0_sel:DWORD
	v_rcp_f32_e32 v25, v27
	v_rcp_f32_e32 v24, v26
	s_nop 0
	v_pk_fma_f32 v[24:25], v[24:25], s[10:11], 0.5 op_sel_hi:[1,0,0]
	v_or_b32_e32 v26, v28, v35
	v_cvt_u32_f32_sdwa v25, v25 dst_sel:BYTE_3 dst_unused:UNUSED_PAD src0_sel:DWORD
	v_cvt_u32_f32_sdwa v24, v24 dst_sel:BYTE_3 dst_unused:UNUSED_PAD src0_sel:DWORD
	v_or_b32_e32 v27, v29, v34
	v_or_b32_e32 v25, v26, v25
	v_or_b32_e32 v24, v27, v24
	v_lshl_add_u64 v[26:27], s[90:91], 0, v[32:33]
	v_lshl_add_u64 v[26:27], v[26:27], 0, v[144:145]
	global_store_dwordx2 v[26:27], v[24:25], off nt
	v_exp_f32_e32 v24, v21
	v_mul_f32_e32 v21, 0xbfb8aa3b, v22
	v_exp_f32_e32 v22, v21
	v_mul_f32_e32 v21, 0xbfb8aa3b, v23
	v_exp_f32_e32 v28, v21
	v_exp_f32_e32 v21, v16
	v_mul_f32_e32 v16, 0xbfb8aa3b, v17
	v_exp_f32_e32 v25, v16
	v_exp_f32_e32 v23, v18
	v_pk_add_f32 v[16:17], v[20:21], 1.0 op_sel_hi:[1,0]
	v_mul_f32_e32 v18, 0xbfb8aa3b, v19
	v_exp_f32_e32 v29, v18
	v_rcp_f32_e32 v17, v17
	v_pk_add_f32 v[18:19], v[24:25], 1.0 op_sel_hi:[1,0]
	v_rcp_f32_e32 v16, v16
	s_nop 0
	v_pk_fma_f32 v[16:17], v[16:17], s[10:11], 0.5 op_sel_hi:[1,0,0]
	v_rcp_f32_e32 v19, v19
	v_rcp_f32_e32 v18, v18
	s_nop 0
	v_pk_fma_f32 v[18:19], v[18:19], s[10:11], 0.5 op_sel_hi:[1,0,0]
	v_cvt_u32_f32_e32 v20, v17
	v_cvt_u32_f32_e32 v21, v16
	v_pk_add_f32 v[16:17], v[22:23], 1.0 op_sel_hi:[1,0]
	v_cvt_u32_f32_e32 v18, v18
	v_cvt_u32_f32_e32 v19, v19
	v_lshlrev_b32_e32 v18, 8, v18
	v_or_b32_e32 v21, v18, v21
	v_lshlrev_b32_e32 v19, 8, v19
	v_or_b32_e32 v20, v19, v20
	v_rcp_f32_e32 v17, v17
	v_rcp_f32_e32 v16, v16
	v_pk_add_f32 v[18:19], v[28:29], 1.0 op_sel_hi:[1,0]
	v_pk_fma_f32 v[16:17], v[16:17], s[10:11], 0.5 op_sel_hi:[1,0,0]
	s_nop 0
	v_cvt_u32_f32_sdwa v24, v16 dst_sel:WORD_1 dst_unused:UNUSED_PAD src0_sel:DWORD
	v_cvt_u32_f32_sdwa v25, v17 dst_sel:WORD_1 dst_unused:UNUSED_PAD src0_sel:DWORD
	v_rcp_f32_e32 v17, v19
	v_rcp_f32_e32 v16, v18
	s_nop 0
	v_pk_fma_f32 v[16:17], v[16:17], s[10:11], 0.5 op_sel_hi:[1,0,0]
	v_or_b32_e32 v18, v20, v25
	v_cvt_u32_f32_sdwa v17, v17 dst_sel:BYTE_3 dst_unused:UNUSED_PAD src0_sel:DWORD
	v_cvt_u32_f32_sdwa v16, v16 dst_sel:BYTE_3 dst_unused:UNUSED_PAD src0_sel:DWORD
	v_or_b32_e32 v19, v21, v24
	v_or_b32_e32 v17, v18, v17
	v_exp_f32_e32 v18, v13
	v_mul_f32_e32 v13, 0xbfb8aa3b, v14
	v_exp_f32_e32 v14, v13
	v_mul_f32_e32 v13, 0xbfb8aa3b, v15
	v_exp_f32_e32 v20, v13
	v_exp_f32_e32 v13, v8
	v_mul_f32_e32 v8, 0xbfb8aa3b, v9
	v_or_b32_e32 v16, v19, v16
	v_exp_f32_e32 v19, v8
	v_pk_add_f32 v[8:9], v[12:13], 1.0 op_sel_hi:[1,0]
	v_exp_f32_e32 v15, v10
	v_mul_f32_e32 v10, 0xbfb8aa3b, v11
	v_exp_f32_e32 v21, v10
	global_store_dwordx2 v[26:27], v[16:17], off offset:128 nt
	v_rcp_f32_e32 v9, v9
	v_add_u32_e32 v16, 0xb0, v146
	v_pk_add_f32 v[10:11], v[18:19], 1.0 op_sel_hi:[1,0]
	v_rcp_f32_e32 v8, v8
	s_nop 0
	v_pk_fma_f32 v[8:9], v[8:9], s[10:11], 0.5 op_sel_hi:[1,0,0]
	v_ashrrev_i32_e32 v17, 31, v16
	v_rcp_f32_e32 v11, v11
	v_lshlrev_b64 v[16:17], 10, v[16:17]
	v_rcp_f32_e32 v10, v10
	s_nop 0
	v_pk_fma_f32 v[10:11], v[10:11], s[10:11], 0.5 op_sel_hi:[1,0,0]
	v_cvt_u32_f32_e32 v12, v9
	v_cvt_u32_f32_e32 v13, v8
	v_pk_add_f32 v[8:9], v[14:15], 1.0 op_sel_hi:[1,0]
	v_cvt_u32_f32_e32 v10, v10
	v_cvt_u32_f32_e32 v11, v11
	v_lshlrev_b32_e32 v10, 8, v10
	v_or_b32_e32 v13, v10, v13
	v_lshlrev_b32_e32 v11, 8, v11
	v_or_b32_e32 v12, v11, v12
	v_rcp_f32_e32 v9, v9
	v_rcp_f32_e32 v8, v8
	v_pk_add_f32 v[10:11], v[20:21], 1.0 op_sel_hi:[1,0]
	v_pk_fma_f32 v[8:9], v[8:9], s[10:11], 0.5 op_sel_hi:[1,0,0]
	s_nop 0
	v_cvt_u32_f32_sdwa v18, v8 dst_sel:WORD_1 dst_unused:UNUSED_PAD src0_sel:DWORD
	v_cvt_u32_f32_sdwa v19, v9 dst_sel:WORD_1 dst_unused:UNUSED_PAD src0_sel:DWORD
	v_rcp_f32_e32 v9, v11
	v_rcp_f32_e32 v8, v10
	s_nop 0
	v_pk_fma_f32 v[8:9], v[8:9], s[10:11], 0.5 op_sel_hi:[1,0,0]
	v_or_b32_e32 v10, v12, v19
	v_cvt_u32_f32_sdwa v9, v9 dst_sel:BYTE_3 dst_unused:UNUSED_PAD src0_sel:DWORD
	v_cvt_u32_f32_sdwa v8, v8 dst_sel:BYTE_3 dst_unused:UNUSED_PAD src0_sel:DWORD
	v_or_b32_e32 v11, v13, v18
	v_or_b32_e32 v9, v10, v9
	v_or_b32_e32 v8, v11, v8
	v_lshl_add_u64 v[10:11], s[90:91], 0, v[16:17]
	v_lshl_add_u64 v[10:11], v[10:11], 0, v[144:145]
	global_store_dwordx2 v[10:11], v[8:9], off nt
	v_exp_f32_e32 v8, v5
	v_mul_f32_e32 v5, 0xbfb8aa3b, v6
	v_exp_f32_e32 v6, v5
	v_mul_f32_e32 v5, 0xbfb8aa3b, v7
	v_exp_f32_e32 v12, v5
	v_exp_f32_e32 v5, v0
	v_mul_f32_e32 v0, 0xbfb8aa3b, v1
	v_exp_f32_e32 v9, v0
	v_exp_f32_e32 v7, v2
	v_pk_add_f32 v[0:1], v[4:5], 1.0 op_sel_hi:[1,0]
	v_mul_f32_e32 v2, 0xbfb8aa3b, v3
	v_exp_f32_e32 v13, v2
	v_rcp_f32_e32 v1, v1
	v_pk_add_f32 v[2:3], v[8:9], 1.0 op_sel_hi:[1,0]
	v_rcp_f32_e32 v0, v0
	s_nop 0
	v_pk_fma_f32 v[0:1], v[0:1], s[10:11], 0.5 op_sel_hi:[1,0,0]
	v_rcp_f32_e32 v3, v3
	v_rcp_f32_e32 v2, v2
	s_nop 0
	v_pk_fma_f32 v[2:3], v[2:3], s[10:11], 0.5 op_sel_hi:[1,0,0]
	v_cvt_u32_f32_e32 v4, v1
	v_cvt_u32_f32_e32 v5, v0
	v_pk_add_f32 v[0:1], v[6:7], 1.0 op_sel_hi:[1,0]
	v_cvt_u32_f32_e32 v2, v2
	v_cvt_u32_f32_e32 v3, v3
	v_lshlrev_b32_e32 v2, 8, v2
	v_or_b32_e32 v5, v2, v5
	v_lshlrev_b32_e32 v3, 8, v3
	v_or_b32_e32 v4, v3, v4
	v_rcp_f32_e32 v1, v1
	v_rcp_f32_e32 v0, v0
	v_pk_add_f32 v[2:3], v[12:13], 1.0 op_sel_hi:[1,0]
	v_pk_fma_f32 v[0:1], v[0:1], s[10:11], 0.5 op_sel_hi:[1,0,0]
	s_nop 0
	v_cvt_u32_f32_sdwa v8, v0 dst_sel:WORD_1 dst_unused:UNUSED_PAD src0_sel:DWORD
	v_cvt_u32_f32_sdwa v9, v1 dst_sel:WORD_1 dst_unused:UNUSED_PAD src0_sel:DWORD
	v_rcp_f32_e32 v1, v3
	v_rcp_f32_e32 v0, v2
	s_nop 0
	v_pk_fma_f32 v[0:1], v[0:1], s[10:11], 0.5 op_sel_hi:[1,0,0]
	v_or_b32_e32 v2, v4, v9
	v_cvt_u32_f32_sdwa v1, v1 dst_sel:BYTE_3 dst_unused:UNUSED_PAD src0_sel:DWORD
	v_cvt_u32_f32_sdwa v0, v0 dst_sel:BYTE_3 dst_unused:UNUSED_PAD src0_sel:DWORD
	v_or_b32_e32 v3, v5, v8
	s_andn2_b64 vcc, exec, s[4:5]
	v_or_b32_e32 v1, v2, v1
	v_or_b32_e32 v0, v3, v0
	s_mov_b64 s[4:5], -1
	global_store_dwordx2 v[10:11], v[0:1], off offset:128 nt
	s_cbranch_vccnz .LBB0_1692
	s_andn2_b64 vcc, exec, s[0:1]
	s_cbranch_vccnz .LBB0_1691
	s_barrier
	s_branch .LBB0_1691
